# epilogue load prefetch (GMA/GMB/GOUT/FFN2 rolling window, FFN1 rstd hoist) + FIN qt fragment loads hoisted out of serialized vmcnt(0) chain
# speedup vs baseline: 1.0185x; 1.0093x over previous
; #define LAS __attribute__((address_space(3)))
; #define F4_GLOAD(g, gptr) do { _Pragma("unroll") for (int i_ = 0; i_ < 4; ++i_) g[i_] = *(const u32x4*)((gptr) + (size_t)((lane >> 3) + 8 * i_) * RW + 8 * (lane & 7)); } while (0)
; __device__ __forceinline__ void ph_fin4(Ctx& C) {
;     ...
;         for (int hv = 0; hv < CHL / 256; ++hv) {
;         const size_t base_f = (size_t)(cf * CHL + hv * 256 + wave * 32) * RW + h * 64, base_b = base_f + (size_t)S * RW;
;         u32x4 g0[4], g1[4], g2[4], g3[4];
;         F4_GLOAD(g0, yl + base_f); F4_GLOAD(g1, yl + base_b); F4_GLOAD(g2, r + base_f); F4_GLOAD(g3, kraw + base_f);
;         const int t0 = cf * CHL + hv * 256 + wave * 32, t = t0 + r31; const size_t rowf = (size_t)t * RW + h * 64, rowb = ((size_t)S + t) * RW + h * 64;
;         f32x16 acc[2];
; #pragma unroll
;         for (int vt = 0; vt < 2; ++vt)
; #pragma unroll
;             for (int e = 0; e < 16; ++e) acc[vt][e] = 0.f;
; #pragma unroll
;         for (int z = 0; z < 2; ++z) { const bf16* qp = qt + (z ? rowb : rowf) + 8 * hh;
; #pragma unroll
;             for (int ks = 0; ks < 4; ++ks) { const bf16x8 bq = *(const bf16x8*)(qp + 16 * ks);
; #pragma unroll
;                 for (int vt = 0; vt < 2; ++vt) { const bf16x8 af = *(const LAS bf16x8*)(s0img + (z * 64 + 32 * vt + r31) * F4_S0STR + 16 * ks + 8 * hh); acc[vt] = __builtin_amdgcn_mfma_f32_32x32x16_bf16(af, bq, acc[vt], 0, 0, 0); } } }
.LBB0_895:
	s_add_i32 s0, s58, s0
	v_or_b32_e32 v228, s0, v184
	v_ashrrev_i32_e32 v229, 31, v228
	v_lshlrev_b64 v[228:229], 11, v[228:229]
	v_lshl_add_u64 v[228:229], v[116:117], 0, v[228:229]
	s_mov_b32 s98, s53
	s_mov_b32 s99, 0
	global_load_dwordx4 v[232:235], v[228:229], off offset:64
	global_load_dwordx4 v[236:239], v[228:229], off offset:96
	v_lshl_add_u64 v[228:229], v[228:229], 0, s[98:99]
	global_load_dwordx4 v[240:243], v[228:229], off
	global_load_dwordx4 v[244:247], v[228:229], off offset:32
	global_load_dwordx4 v[248:251], v[228:229], off offset:64
	global_load_dwordx4 v[252:255], v[228:229], off offset:96
	s_ashr_i32 s1, s0, 31
	s_lshl_b64 s[42:43], s[0:1], 11
	v_cndmask_b32_e64 v0, 0, 1, s[4:5]
	s_or_b32 s42, s42, s59
	v_cmp_ne_u32_e64 s[2:3], 1, v0
	v_lshl_add_u64 v[0:1], v[130:131], 0, s[42:43]
	v_lshl_add_u64 v[2:3], v[0:1], 0, v[114:115]
	global_load_dwordx4 v[92:95], v[2:3], off
	v_lshl_add_u64 v[2:3], v[0:1], 0, v[118:119]
	global_load_dwordx4 v[88:91], v[2:3], off
	v_lshl_add_u64 v[2:3], v[0:1], 0, v[120:121]
	global_load_dwordx4 v[84:87], v[2:3], off
	v_lshl_add_u64 v[2:3], v[0:1], 0, v[122:123]
	v_lshl_add_u64 v[0:1], v[0:1], 0, s[40:41]
	global_load_dwordx4 v[36:39], v[2:3], off
	v_lshl_add_u64 v[2:3], v[0:1], 0, v[114:115]
	global_load_dwordx4 v[32:35], v[2:3], off
	v_lshl_add_u64 v[2:3], v[0:1], 0, v[118:119]
	global_load_dwordx4 v[72:75], v[2:3], off
	v_lshl_add_u64 v[2:3], v[0:1], 0, v[120:121]
	v_lshl_add_u64 v[0:1], v[0:1], 0, v[122:123]
	global_load_dwordx4 v[76:79], v[2:3], off
	global_load_dwordx4 v[80:83], v[0:1], off
	v_lshl_add_u64 v[0:1], v[132:133], 0, s[42:43]
	v_lshl_add_u64 v[2:3], v[0:1], 0, v[114:115]
	global_load_dwordx4 v[44:47], v[2:3], off
	v_lshl_add_u64 v[2:3], v[0:1], 0, v[118:119]
	global_load_dwordx4 v[48:51], v[2:3], off
	v_lshl_add_u64 v[2:3], v[0:1], 0, v[120:121]
	v_lshl_add_u64 v[0:1], v[0:1], 0, v[122:123]
	global_load_dwordx4 v[56:59], v[2:3], off
	global_load_dwordx4 v[64:67], v[0:1], off
	v_lshl_add_u64 v[0:1], v[134:135], 0, s[42:43]
	v_lshl_add_u64 v[2:3], v[0:1], 0, v[114:115]
	global_load_dwordx4 v[40:43], v[2:3], off
	v_lshl_add_u64 v[2:3], v[0:1], 0, v[118:119]
	global_load_dwordx4 v[52:55], v[2:3], off
	v_lshl_add_u64 v[2:3], v[0:1], 0, v[120:121]
	v_lshl_add_u64 v[0:1], v[0:1], 0, v[122:123]
	global_load_dwordx4 v[60:63], v[2:3], off
	global_load_dwordx4 v[68:71], v[0:1], off
	v_or_b32_e32 v0, s0, v184
	v_ashrrev_i32_e32 v1, 31, v0
	v_lshlrev_b64 v[0:1], 11, v[0:1]
	v_lshl_add_u64 v[104:105], v[116:117], 0, v[0:1]
	global_load_dwordx4 v[0:3], v[104:105], off
	ds_read_b128 v[4:7], v187
	ds_read_b128 v[96:99], v187 offset:32
	global_load_dwordx4 v[100:103], v[104:105], off offset:32
	v_add3_u32 v189, v186, v185, s54
	v_add_u32_e32 v190, 0x4800, v188
	v_add_u32_e32 v191, 0x4c40, v188
	v_add_u32_e32 v192, 0x5080, v188
	v_add_u32_e32 v193, 0x4800, v112
	s_waitcnt vmcnt(1) lgkmcnt(1)
	v_mfma_f32_32x32x16_bf16 v[16:31], v[4:7], v[0:3], 0
	ds_read_b128 v[4:7], v187 offset:4608
	s_waitcnt vmcnt(0) lgkmcnt(1)
	v_mfma_f32_32x32x16_bf16 v[16:31], v[96:99], v[100:103], v[16:31]
	ds_read_b128 v[96:99], v187 offset:4640
	s_waitcnt lgkmcnt(1)
	v_mfma_f32_32x32x16_bf16 v[0:15], v[4:7], v[0:3], 0
	s_waitcnt lgkmcnt(0)
	v_mfma_f32_32x32x16_bf16 v[0:15], v[96:99], v[100:103], v[0:15]
	s_nop 0
	ds_read_b128 v[100:103], v187 offset:64
	s_waitcnt vmcnt(0) lgkmcnt(0)
	v_mfma_f32_32x32x16_bf16 v[16:31], v[100:103], v[232:235], v[16:31]
	ds_read_b128 v[100:103], v187 offset:4672
	s_waitcnt lgkmcnt(0)
	v_mfma_f32_32x32x16_bf16 v[0:15], v[100:103], v[232:235], v[0:15]
	s_nop 0
	ds_read_b128 v[100:103], v187 offset:96
	v_add_co_u32_e32 v104, vcc, s53, v104
	s_nop 1
	v_addc_co_u32_e32 v105, vcc, 0, v105, vcc
	s_waitcnt vmcnt(0) lgkmcnt(0)
	v_mfma_f32_32x32x16_bf16 v[16:31], v[100:103], v[236:239], v[16:31]
	ds_read_b128 v[100:103], v187 offset:4704
	s_waitcnt lgkmcnt(0)
	v_mfma_f32_32x32x16_bf16 v[0:15], v[100:103], v[236:239], v[0:15]
	s_nop 0
	ds_read_b128 v[100:103], v187 offset:9216
	s_waitcnt vmcnt(0) lgkmcnt(0)
	v_mfma_f32_32x32x16_bf16 v[16:31], v[100:103], v[240:243], v[16:31]
	ds_read_b128 v[100:103], v187 offset:13824
	s_waitcnt lgkmcnt(0)
	v_mfma_f32_32x32x16_bf16 v[0:15], v[100:103], v[240:243], v[0:15]
	s_nop 0
	ds_read_b128 v[100:103], v187 offset:9248
	s_waitcnt vmcnt(0) lgkmcnt(0)
	v_mfma_f32_32x32x16_bf16 v[16:31], v[100:103], v[244:247], v[16:31]
	ds_read_b128 v[100:103], v187 offset:13856
	s_waitcnt lgkmcnt(0)
	v_mfma_f32_32x32x16_bf16 v[0:15], v[100:103], v[244:247], v[0:15]
	s_nop 0
	ds_read_b128 v[100:103], v187 offset:9280
	s_waitcnt vmcnt(0) lgkmcnt(0)
	v_mfma_f32_32x32x16_bf16 v[16:31], v[100:103], v[248:251], v[16:31]
	ds_read_b128 v[100:103], v187 offset:13888
	s_waitcnt lgkmcnt(0)
	v_mfma_f32_32x32x16_bf16 v[0:15], v[100:103], v[248:251], v[0:15]
	s_nop 0
	ds_read_b128 v[100:103], v187 offset:9312
	s_waitcnt vmcnt(0) lgkmcnt(0)
	v_mfma_f32_32x32x16_bf16 v[16:31], v[100:103], v[252:255], v[16:31]
	ds_read_b128 v[100:103], v187 offset:13920
	ds_write2_b64 v189, v[92:93], v[94:95] offset1:1
	ds_write2_b64 v190, v[88:89], v[90:91] offset1:1
	ds_write2_b64 v191, v[84:85], v[86:87] offset1:1
	ds_write2_b64 v192, v[36:37], v[38:39] offset1:1
	s_waitcnt lgkmcnt(0)
	ds_read2_b64 v[104:107], v193 offset1:2
	ds_read2_b64 v[108:111], v193 offset0:4 offset1:6
	ds_read2_b64 v[146:149], v193 offset0:8 offset1:10
	ds_read2_b64 v[36:39], v193 offset0:12 offset1:14
	s_waitcnt lgkmcnt(0)
	ds_write2_b64 v189, v[32:33], v[34:35] offset1:1
	ds_write2_b64 v190, v[72:73], v[74:75] offset1:1
	ds_write2_b64 v191, v[76:77], v[78:79] offset1:1
	ds_write2_b64 v192, v[80:81], v[82:83] offset1:1
	v_lshl_add_u64 v[72:73], v[136:137], 0, s[42:43]
	s_waitcnt lgkmcnt(12)
; __device__ __forceinline__ void unpack4(u32x2 w, float (&f)[4]) { f[0] = __uint_as_float(w.x << 16); f[1] = __uint_as_float(w.x & 0xffff0000u); f[2] = __uint_as_float(w.y << 16); f[3] = __uint_as_float(w.y & 0xffff0000u); }
; #define F4_GLOAD(g, gptr) do { _Pragma("unroll") for (int i_ = 0; i_ < 4; ++i_) g[i_] = *(const u32x4*)((gptr) + (size_t)((lane >> 3) + 8 * i_) * RW + 8 * (lane & 7)); } while (0)
; __device__ __forceinline__ void ph_fin4(Ctx& C) {
;     ...
;         u32x2 q0[2][4], q1[2][4];
;         float ssum = 0.f, bsum = 0.f;
;         F4_XPOSE(q0, g0); F4_XPOSE(q1, g1);
;         F4_GLOAD(g0, a + base_f); F4_GLOAD(g1, a + base_b);
; #pragma unroll
;         for (int vt = 0; vt < 2; ++vt)
; #pragma unroll
;             for (int gr = 0; gr < 4; ++gr) { float f0[4], f1[4]; unpack4(q0[vt][gr], f0); unpack4(q1[vt][gr], f1);
; #pragma unroll
;                 for (int e = 0; e < 4; ++e) { const float y = acc[vt][4 * gr + e] + f0[e] + f1[e]; acc[vt][4 * gr + e] = y; ssum += y; } }
	v_mfma_f32_32x32x16_bf16 v[0:15], v[100:103], v[252:255], v[0:15]
	s_waitcnt lgkmcnt(0)
	v_lshl_add_u64 v[96:97], v[72:73], 0, s[40:41]
	ds_read2_b64 v[150:153], v193 offset1:2
	ds_read2_b64 v[154:157], v193 offset0:4 offset1:6
	ds_read2_b64 v[174:177], v193 offset0:8 offset1:10
	ds_read2_b64 v[32:35], v193 offset0:12 offset1:14
	s_waitcnt lgkmcnt(0)
	v_lshl_add_u64 v[74:75], v[72:73], 0, v[114:115]
	v_lshl_add_u64 v[88:89], v[96:97], 0, v[120:121]
	global_load_dwordx4 v[76:79], v[74:75], off
	v_lshl_add_u64 v[80:81], v[96:97], 0, v[118:119]
	global_load_dwordx4 v[88:91], v[88:89], off
	v_lshl_add_u64 v[74:75], v[72:73], 0, v[118:119]
	global_load_dwordx4 v[84:87], v[74:75], off
	v_lshl_add_u64 v[74:75], v[72:73], 0, v[120:121]
	global_load_dwordx4 v[92:95], v[74:75], off
	v_lshl_add_u64 v[74:75], v[72:73], 0, v[122:123]
	v_lshl_add_u64 v[72:73], v[96:97], 0, v[114:115]
	v_lshl_add_u64 v[96:97], v[96:97], 0, v[122:123]
	global_load_dwordx4 v[100:103], v[74:75], off
	s_waitcnt lgkmcnt(11)
	v_lshlrev_b32_e32 v159, 16, v105
	global_load_dwordx4 v[96:99], v[96:97], off
	v_lshlrev_b32_e32 v158, 16, v104
	global_load_dwordx4 v[72:75], v[72:73], off
	v_mov_b32_e32 v162, v16
	global_load_dwordx4 v[80:83], v[80:81], off
	v_mov_b32_e32 v163, v18
	s_waitcnt lgkmcnt(3)
	v_lshlrev_b32_e32 v161, 16, v151
	v_lshlrev_b32_e32 v160, 16, v150
	v_pk_add_f32 v[158:159], v[162:163], v[158:159]
	v_and_b32_e32 v105, 0xffff0000, v105
	v_and_b32_e32 v104, 0xffff0000, v104
	v_mov_b32_e32 v18, v17
	v_pk_add_f32 v[170:171], v[158:159], v[160:161]
	v_and_b32_e32 v151, 0xffff0000, v151
	v_and_b32_e32 v150, 0xffff0000, v150
	v_pk_add_f32 v[16:17], v[18:19], v[104:105]
	v_add_f32_e32 v158, 0, v170
	v_pk_add_f32 v[172:173], v[16:17], v[150:151]
	v_lshlrev_b32_e32 v17, 16, v107
	v_add_f32_e32 v16, v172, v158
	v_add_f32_e32 v16, v171, v16
	v_add_f32_e32 v150, v173, v16
	v_lshlrev_b32_e32 v16, 16, v106
	v_mov_b32_e32 v104, v20
	v_mov_b32_e32 v105, v22
	v_lshlrev_b32_e32 v19, 16, v153
	v_lshlrev_b32_e32 v18, 16, v152
	v_pk_add_f32 v[16:17], v[104:105], v[16:17]
	v_mov_b32_e32 v22, v21
	v_pk_add_f32 v[166:167], v[16:17], v[18:19]
	v_and_b32_e32 v17, 0xffff0000, v107
	v_and_b32_e32 v16, 0xffff0000, v106
	v_and_b32_e32 v19, 0xffff0000, v153
	v_and_b32_e32 v18, 0xffff0000, v152
	v_pk_add_f32 v[16:17], v[22:23], v[16:17]
	v_add_f32_e32 v20, v166, v150
	v_pk_add_f32 v[168:169], v[16:17], v[18:19]
	v_lshlrev_b32_e32 v17, 16, v109
	v_add_f32_e32 v16, v168, v20
	v_add_f32_e32 v16, v167, v16
	v_add_f32_e32 v22, v169, v16
	v_lshlrev_b32_e32 v16, 16, v108
	v_mov_b32_e32 v20, v24
	v_mov_b32_e32 v21, v26
	s_waitcnt lgkmcnt(2)
	v_lshlrev_b32_e32 v19, 16, v155
	v_lshlrev_b32_e32 v18, 16, v154
	v_pk_add_f32 v[16:17], v[20:21], v[16:17]
	v_mov_b32_e32 v26, v25
	v_pk_add_f32 v[162:163], v[16:17], v[18:19]
	v_and_b32_e32 v17, 0xffff0000, v109
	v_and_b32_e32 v16, 0xffff0000, v108
	v_and_b32_e32 v19, 0xffff0000, v155
	v_and_b32_e32 v18, 0xffff0000, v154
	v_pk_add_f32 v[16:17], v[26:27], v[16:17]
	v_add_f32_e32 v20, v162, v22
	v_pk_add_f32 v[164:165], v[16:17], v[18:19]
	v_lshlrev_b32_e32 v17, 16, v111
	v_add_f32_e32 v16, v164, v20
	v_add_f32_e32 v16, v163, v16
	v_add_f32_e32 v22, v165, v16
	v_lshlrev_b32_e32 v16, 16, v110
	v_mov_b32_e32 v20, v28
	v_mov_b32_e32 v21, v30
	v_lshlrev_b32_e32 v19, 16, v157
	v_lshlrev_b32_e32 v18, 16, v156
	v_pk_add_f32 v[16:17], v[20:21], v[16:17]
	v_mov_b32_e32 v30, v29
	v_pk_add_f32 v[158:159], v[16:17], v[18:19]
	v_and_b32_e32 v17, 0xffff0000, v111
	v_and_b32_e32 v16, 0xffff0000, v110
	v_and_b32_e32 v19, 0xffff0000, v157
	v_and_b32_e32 v18, 0xffff0000, v156
	v_pk_add_f32 v[16:17], v[30:31], v[16:17]
	v_add_f32_e32 v20, v158, v22
	v_pk_add_f32 v[160:161], v[16:17], v[18:19]
	v_lshlrev_b32_e32 v17, 16, v147
	v_add_f32_e32 v16, v160, v20
	v_add_f32_e32 v16, v159, v16
	v_add_f32_e32 v22, v161, v16
	v_lshlrev_b32_e32 v16, 16, v146
	v_mov_b32_e32 v20, v0
	v_mov_b32_e32 v21, v2
	s_waitcnt lgkmcnt(1)
	v_lshlrev_b32_e32 v19, 16, v175
	v_lshlrev_b32_e32 v18, 16, v174
	v_pk_add_f32 v[16:17], v[20:21], v[16:17]
	v_mov_b32_e32 v2, v1
	v_pk_add_f32 v[154:155], v[16:17], v[18:19]
	v_and_b32_e32 v17, 0xffff0000, v147
	v_and_b32_e32 v16, 0xffff0000, v146
	v_and_b32_e32 v19, 0xffff0000, v175
	v_and_b32_e32 v18, 0xffff0000, v174
	v_pk_add_f32 v[0:1], v[2:3], v[16:17]
	v_add_f32_e32 v20, v154, v22
	v_pk_add_f32 v[156:157], v[0:1], v[18:19]
	v_lshlrev_b32_e32 v1, 16, v148
	v_add_f32_e32 v0, v156, v20
	v_add_f32_e32 v0, v155, v0
	v_and_b32_e32 v2, 0xffff0000, v148
	v_lshlrev_b32_e32 v3, 16, v176
	v_add_f32_e32 v1, v4, v1
	v_add_f32_e32 v0, v157, v0
	v_and_b32_e32 v16, 0xffff0000, v176
	v_add_f32_e32 v150, v1, v3
	v_add_f32_e32 v1, v5, v2
	v_add_f32_e32 v0, v150, v0
	v_add_f32_e32 v148, v1, v16
	v_add_f32_e32 v4, v148, v0
	v_and_b32_e32 v1, 0xffff0000, v149
	v_lshlrev_b32_e32 v0, 16, v149
	v_and_b32_e32 v3, 0xffff0000, v177
	v_lshlrev_b32_e32 v2, 16, v177
	v_pk_add_f32 v[0:1], v[6:7], v[0:1]
	ds_write2_b64 v189, v[44:45], v[46:47] offset1:1
	ds_write2_b64 v190, v[48:49], v[50:51] offset1:1
	ds_write2_b64 v191, v[56:57], v[58:59] offset1:1
	ds_write2_b64 v192, v[64:65], v[66:67] offset1:1
	v_pk_add_f32 v[152:153], v[0:1], v[2:3]
	v_and_b32_e32 v1, 0xffff0000, v36
	v_add_f32_e32 v0, v152, v4
	v_add_f32_e32 v4, v153, v0
	v_lshlrev_b32_e32 v0, 16, v36
	s_waitcnt lgkmcnt(4)
	v_and_b32_e32 v3, 0xffff0000, v32
	v_lshlrev_b32_e32 v2, 16, v32
	v_pk_add_f32 v[0:1], v[8:9], v[0:1]
	s_waitcnt lgkmcnt(0)
	ds_read2_b64 v[104:107], v193 offset1:2
	ds_read2_b64 v[64:67], v193 offset0:4 offset1:6
	ds_read2_b64 v[56:59], v193 offset0:8 offset1:10
	ds_read2_b64 v[48:51], v193 offset0:12 offset1:14
	v_pk_add_f32 v[146:147], v[0:1], v[2:3]
	s_waitcnt lgkmcnt(0)
; __device__ __forceinline__ void unpack4(u32x2 w, float (&f)[4]) { f[0] = __uint_as_float(w.x << 16); f[1] = __uint_as_float(w.x & 0xffff0000u); f[2] = __uint_as_float(w.y << 16); f[3] = __uint_as_float(w.y & 0xffff0000u); }
; #define F4_GLOAD(g, gptr) do { _Pragma("unroll") for (int i_ = 0; i_ < 4; ++i_) g[i_] = *(const u32x4*)((gptr) + (size_t)((lane >> 3) + 8 * i_) * RW + 8 * (lane & 7)); } while (0)
; __device__ __forceinline__ void ph_fin4(Ctx& C) {
;     ...
;         { u32x2 q2[2][4], q3[2][4];
;           F4_XPOSE(q0, g2); F4_XPOSE(q1, g3);
;           F4_GLOAD(g2, v + base_f); F4_GLOAD(g3, gate + base_f);
;           F4_XPOSE(q2, g0); F4_XPOSE(q3, g1);
; #pragma unroll
;           for (int vt = 0; vt < 2; ++vt)
; #pragma unroll
;               for (int gr = 0; gr < 4; ++gr) { const int co = 32 * vt + 8 * gr + 4 * hh; float fr_[4], fk[4], fa0[4], fa1[4]; unpack4(q0[vt][gr], fr_); unpack4(q1[vt][gr], fk); unpack4(q2[vt][gr], fa0); unpack4(q3[vt][gr], fa1);
;                   const f32x4 ka4 = *(const f32x4*)(k_a + h * 64 + co), rk4 = *(const f32x4*)(r_k + h * 64 + co);
; #pragma unroll
;                   for (int e = 0; e < 4; ++e) bsum += fr_[e] * fk[e] * ((1.0f + (fa0[e] - 1.0f) * ka4[e]) + (1.0f + (fa1[e] - 1.0f) * ka4[e])) * rk4[e]; } }
	ds_write2_b64 v189, v[40:41], v[42:43] offset1:1
	ds_write2_b64 v190, v[52:53], v[54:55] offset1:1
	ds_write2_b64 v191, v[60:61], v[62:63] offset1:1
	ds_write2_b64 v192, v[68:69], v[70:71] offset1:1
	v_add_f32_e32 v0, v146, v4
	s_waitcnt lgkmcnt(0)
	v_lshl_add_u64 v[8:9], v[138:139], 0, s[42:43]
	v_add_f32_e32 v32, v147, v0
	ds_read2_b64 v[108:111], v193 offset1:2
	ds_read2_b64 v[68:71], v193 offset0:4 offset1:6
	ds_read2_b64 v[60:63], v193 offset0:8 offset1:10
	ds_read2_b64 v[52:55], v193 offset0:12 offset1:14
	s_waitcnt lgkmcnt(0)
	v_lshl_add_u64 v[0:1], v[8:9], 0, v[114:115]
	v_lshl_add_u64 v[4:5], v[8:9], 0, v[118:119]
	v_lshl_add_u64 v[16:17], v[8:9], 0, v[120:121]
	v_lshl_add_u64 v[8:9], v[8:9], 0, v[122:123]
	global_load_dwordx4 v[16:19], v[16:17], off
	s_waitcnt lgkmcnt(11)
	v_lshlrev_b32_e32 v36, 16, v105
	global_load_dwordx4 v[20:23], v[8:9], off
	v_lshl_add_u64 v[8:9], v[140:141], 0, s[42:43]
	v_lshl_add_u64 v[24:25], v[8:9], 0, v[114:115]
	v_lshl_add_u64 v[28:29], v[8:9], 0, v[118:119]
	v_lshl_add_u64 v[40:41], v[8:9], 0, v[120:121]
	v_lshl_add_u64 v[8:9], v[8:9], 0, v[122:123]
	global_load_dwordx4 v[0:3], v[0:1], off
	s_waitcnt lgkmcnt(3)
	v_lshlrev_b32_e32 v149, 16, v109
	global_load_dwordx4 v[4:7], v[4:5], off
	v_and_b32_e32 v109, 0xffff0000, v109
	global_load_dwordx4 v[24:27], v[24:25], off
	s_nop 0
	global_load_dwordx4 v[44:47], v[8:9], off
	v_lshlrev_b32_e32 v8, 16, v104
	global_load_dwordx4 v[28:31], v[28:29], off
	v_and_b32_e32 v9, 0xffff0000, v104
	global_load_dwordx4 v[40:43], v[40:41], off
	s_waitcnt vmcnt(15)
	ds_write2_b64 v189, v[76:77], v[78:79] offset1:1
	s_waitcnt vmcnt(13)
	ds_write2_b64 v190, v[84:85], v[86:87] offset1:1
	s_waitcnt vmcnt(12)
	ds_write2_b64 v191, v[92:93], v[94:95] offset1:1
	s_waitcnt vmcnt(11)
	ds_write2_b64 v192, v[100:101], v[102:103] offset1:1
	s_waitcnt lgkmcnt(0)
	ds_read2_b64 v[92:95], v193 offset1:2
	ds_read2_b64 v[100:103], v193 offset0:4 offset1:6
	ds_read2_b64 v[84:87], v193 offset0:8 offset1:10
	ds_read2_b64 v[76:79], v193 offset0:12 offset1:14
	s_waitcnt lgkmcnt(0)
	s_waitcnt vmcnt(9)
	ds_write2_b64 v189, v[72:73], v[74:75] offset1:1
	s_waitcnt vmcnt(8)
	ds_write2_b64 v190, v[80:81], v[82:83] offset1:1
	ds_write2_b64 v191, v[88:89], v[90:91] offset1:1
	ds_write2_b64 v192, v[96:97], v[98:99] offset1:1
	s_waitcnt lgkmcnt(0)
	ds_read2_b64 v[88:91], v193 offset1:2
	ds_read2_b64 v[96:99], v193 offset0:4 offset1:6
	ds_read2_b64 v[80:83], v193 offset0:8 offset1:10
	ds_read2_b64 v[72:75], v193 offset0:12 offset1:14
	s_waitcnt lgkmcnt(0)
	global_load_dwordx4 v[174:177], v[124:125], off
	global_load_dwordx4 v[194:197], v[126:127], off
	v_and_b32_e32 v104, 0xffff0000, v105
	v_lshlrev_b32_e32 v105, 16, v108
	s_waitcnt lgkmcnt(11)
	v_lshlrev_b32_e32 v151, 16, v92
	s_waitcnt lgkmcnt(3)
	v_lshlrev_b32_e32 v199, 16, v88
	v_mul_f32_e32 v8, v8, v105
	v_add_f32_e32 v105, -1.0, v151
	v_add_f32_e32 v151, -1.0, v199
	v_and_b32_e32 v108, 0xffff0000, v108
	v_and_b32_e32 v92, 0xffff0000, v92
	v_and_b32_e32 v88, 0xffff0000, v88
	v_add_f32_e32 v88, -1.0, v88
	v_lshlrev_b32_e32 v198, 16, v93
	v_lshlrev_b32_e32 v200, 16, v89
	v_and_b32_e32 v93, 0xffff0000, v93
	v_and_b32_e32 v89, 0xffff0000, v89
	s_waitcnt vmcnt(1)
	v_fma_f32 v105, v105, v174, 1.0
	v_fma_f32 v151, v151, v174, 1.0
	v_add_f32_e32 v105, v105, v151
	v_mul_f32_e32 v8, v8, v105
	s_waitcnt vmcnt(0)
	v_fma_f32 v105, v194, v8, 0
	v_mul_f32_e32 v8, v9, v108
	v_add_f32_e32 v9, -1.0, v92
	v_fma_f32 v9, v9, v175, 1.0
	v_fma_f32 v88, v88, v175, 1.0
	v_add_f32_e32 v9, v9, v88
	v_mul_f32_e32 v8, v8, v9
	v_fmac_f32_e32 v105, v195, v8
	v_mul_f32_e32 v8, v36, v149
	v_add_f32_e32 v9, -1.0, v198
	v_add_f32_e32 v36, -1.0, v200
	v_fma_f32 v9, v9, v176, 1.0
	v_fma_f32 v36, v36, v176, 1.0
	v_add_f32_e32 v9, v9, v36
	v_mul_f32_e32 v8, v8, v9
	v_add_f32_e32 v9, -1.0, v93
	v_add_f32_e32 v36, -1.0, v89
	v_fma_f32 v9, v9, v177, 1.0
	v_fma_f32 v36, v36, v177, 1.0
	v_fmac_f32_e32 v105, v196, v8
	v_mul_f32_e32 v8, v104, v109
	v_add_f32_e32 v9, v9, v36
	v_mul_f32_e32 v8, v8, v9
	v_fmac_f32_e32 v105, v197, v8
	v_lshlrev_b32_e32 v8, 16, v106
	v_and_b32_e32 v9, 0xffff0000, v106
	v_lshlrev_b32_e32 v36, 16, v107
	v_and_b32_e32 v104, 0xffff0000, v107
	v_lshlrev_b32_e32 v106, 16, v110
	v_and_b32_e32 v107, 0xffff0000, v110
	v_lshlrev_b32_e32 v108, 16, v111
	v_and_b32_e32 v109, 0xffff0000, v111
	v_lshlrev_b32_e32 v110, 16, v94
	v_and_b32_e32 v111, 0xffff0000, v94
	v_lshlrev_b32_e32 v149, 16, v95
	v_and_b32_e32 v151, 0xffff0000, v95
	v_lshlrev_b32_e32 v174, 16, v90
	v_and_b32_e32 v175, 0xffff0000, v90
	v_lshlrev_b32_e32 v176, 16, v91
	v_and_b32_e32 v177, 0xffff0000, v91
	global_load_dwordx4 v[88:91], v[124:125], off offset:32
	global_load_dwordx4 v[92:95], v[126:127], off offset:32
	v_mul_f32_e32 v8, v8, v106
	v_add_f32_e32 v106, -1.0, v110
	v_add_f32_e32 v110, -1.0, v174
	s_waitcnt vmcnt(1)
	v_fma_f32 v106, v106, v88, 1.0
	v_fma_f32 v88, v110, v88, 1.0
	v_add_f32_e32 v88, v106, v88
	v_mul_f32_e32 v8, v8, v88
	s_waitcnt vmcnt(0)
	v_fmac_f32_e32 v105, v92, v8
	v_mul_f32_e32 v8, v9, v107
	v_add_f32_e32 v9, -1.0, v111
	v_add_f32_e32 v88, -1.0, v175
	v_fma_f32 v9, v9, v89, 1.0
	v_fma_f32 v88, v88, v89, 1.0
	v_add_f32_e32 v9, v9, v88
	v_mul_f32_e32 v8, v8, v9
	v_fmac_f32_e32 v105, v93, v8
	v_mul_f32_e32 v8, v36, v108
	v_add_f32_e32 v9, -1.0, v149
	v_add_f32_e32 v36, -1.0, v176
	v_fma_f32 v9, v9, v90, 1.0
	v_fma_f32 v36, v36, v90, 1.0
	v_add_f32_e32 v9, v9, v36
	v_mul_f32_e32 v8, v8, v9
	v_add_f32_e32 v9, -1.0, v151
	v_add_f32_e32 v36, -1.0, v177
	v_fma_f32 v9, v9, v91, 1.0
	v_fma_f32 v36, v36, v91, 1.0
	v_fmac_f32_e32 v105, v94, v8
	v_mul_f32_e32 v8, v104, v109
	v_add_f32_e32 v9, v9, v36
	v_mul_f32_e32 v8, v8, v9
	v_fmac_f32_e32 v105, v95, v8
	global_load_dwordx4 v[88:91], v[124:125], off offset:64
	global_load_dwordx4 v[92:95], v[126:127], off offset:64
	v_lshlrev_b32_e32 v8, 16, v64
	v_and_b32_e32 v9, 0xffff0000, v64
	v_lshlrev_b32_e32 v36, 16, v65
	v_and_b32_e32 v64, 0xffff0000, v65
	v_lshlrev_b32_e32 v65, 16, v68
	v_lshlrev_b32_e32 v106, 16, v100
	s_waitcnt lgkmcnt(2)
; __device__ __forceinline__ void unpack4(u32x2 w, float (&f)[4]) { f[0] = __uint_as_float(w.x << 16); f[1] = __uint_as_float(w.x & 0xffff0000u); f[2] = __uint_as_float(w.y << 16); f[3] = __uint_as_float(w.y & 0xffff0000u); }
; __device__ __forceinline__ void ph_fin4(Ctx& C) {
;     ...
;           for (int vt = 0; vt < 2; ++vt)
; #pragma unroll
;               for (int gr = 0; gr < 4; ++gr) { const int co = 32 * vt + 8 * gr + 4 * hh; float fr_[4], fk[4], fa0[4], fa1[4]; unpack4(q0[vt][gr], fr_); unpack4(q1[vt][gr], fk); unpack4(q2[vt][gr], fa0); unpack4(q3[vt][gr], fa1);
;                   const f32x4 ka4 = *(const f32x4*)(k_a + h * 64 + co), rk4 = *(const f32x4*)(r_k + h * 64 + co);
; #pragma unroll
;                   for (int e = 0; e < 4; ++e) bsum += fr_[e] * fk[e] * ((1.0f + (fa0[e] - 1.0f) * ka4[e]) + (1.0f + (fa1[e] - 1.0f) * ka4[e])) * rk4[e]; } }
	v_lshlrev_b32_e32 v108, 16, v96
	v_mul_f32_e32 v8, v8, v65
	v_add_f32_e32 v65, -1.0, v106
	v_add_f32_e32 v106, -1.0, v108
	v_and_b32_e32 v68, 0xffff0000, v68
	v_and_b32_e32 v100, 0xffff0000, v100
	v_and_b32_e32 v96, 0xffff0000, v96
	v_lshlrev_b32_e32 v104, 16, v69
	v_lshlrev_b32_e32 v107, 16, v101
	v_lshlrev_b32_e32 v109, 16, v97
	v_and_b32_e32 v101, 0xffff0000, v101
	v_and_b32_e32 v97, 0xffff0000, v97
	v_and_b32_e32 v69, 0xffff0000, v69
	v_mov_b32_e32 v151, v152
	v_mov_b32_e32 v149, v153
	s_waitcnt vmcnt(1)
	v_fma_f32 v65, v65, v88, 1.0
	v_fma_f32 v88, v106, v88, 1.0
	v_add_f32_e32 v65, v65, v88
	v_mul_f32_e32 v8, v8, v65
	s_waitcnt vmcnt(0)
	v_fmac_f32_e32 v105, v92, v8
	v_mul_f32_e32 v8, v9, v68
	v_add_f32_e32 v9, -1.0, v100
	v_add_f32_e32 v65, -1.0, v96
	v_fma_f32 v9, v9, v89, 1.0
	v_fma_f32 v65, v65, v89, 1.0
	v_add_f32_e32 v9, v9, v65
	v_mul_f32_e32 v8, v8, v9
	v_fmac_f32_e32 v105, v93, v8
	v_mul_f32_e32 v8, v36, v104
	v_add_f32_e32 v9, -1.0, v107
	v_add_f32_e32 v36, -1.0, v109
	v_fma_f32 v9, v9, v90, 1.0
	v_fma_f32 v36, v36, v90, 1.0
	v_add_f32_e32 v9, v9, v36
	v_mul_f32_e32 v8, v8, v9
	v_add_f32_e32 v9, -1.0, v101
	v_add_f32_e32 v36, -1.0, v97
	v_fma_f32 v9, v9, v91, 1.0
	v_fma_f32 v36, v36, v91, 1.0
	v_fmac_f32_e32 v105, v94, v8
	v_mul_f32_e32 v8, v64, v69
	v_add_f32_e32 v9, v9, v36
	v_mul_f32_e32 v8, v8, v9
	v_fmac_f32_e32 v105, v95, v8
	v_lshlrev_b32_e32 v8, 16, v66
	v_and_b32_e32 v9, 0xffff0000, v66
	v_lshlrev_b32_e32 v36, 16, v67
	v_and_b32_e32 v88, 0xffff0000, v67
	v_lshlrev_b32_e32 v89, 16, v70
	v_and_b32_e32 v90, 0xffff0000, v70
	v_lshlrev_b32_e32 v91, 16, v71
	v_and_b32_e32 v92, 0xffff0000, v71
	global_load_dwordx4 v[64:67], v[124:125], off offset:96
	global_load_dwordx4 v[68:71], v[126:127], off offset:96
	v_lshlrev_b32_e32 v93, 16, v102
	v_lshlrev_b32_e32 v97, 16, v98
	v_mul_f32_e32 v8, v8, v89
	v_add_f32_e32 v89, -1.0, v93
	v_add_f32_e32 v93, -1.0, v97
	v_and_b32_e32 v94, 0xffff0000, v102
	v_and_b32_e32 v98, 0xffff0000, v98
	v_lshlrev_b32_e32 v95, 16, v103
	v_lshlrev_b32_e32 v100, 16, v99
	v_and_b32_e32 v96, 0xffff0000, v103
	v_and_b32_e32 v99, 0xffff0000, v99
	s_waitcnt vmcnt(1)
	v_fma_f32 v89, v89, v64, 1.0
	v_fma_f32 v64, v93, v64, 1.0
	v_add_f32_e32 v64, v89, v64
	v_mul_f32_e32 v8, v8, v64
	s_waitcnt vmcnt(0)
	v_fmac_f32_e32 v105, v68, v8
	v_mul_f32_e32 v8, v9, v90
	v_add_f32_e32 v9, -1.0, v94
	v_add_f32_e32 v64, -1.0, v98
	v_fma_f32 v9, v9, v65, 1.0
	v_fma_f32 v64, v64, v65, 1.0
	v_add_f32_e32 v9, v9, v64
	v_mul_f32_e32 v8, v8, v9
	v_fmac_f32_e32 v105, v69, v8
	v_mul_f32_e32 v8, v36, v91
	v_add_f32_e32 v9, -1.0, v95
	v_add_f32_e32 v36, -1.0, v100
	v_fma_f32 v9, v9, v66, 1.0
	v_fma_f32 v36, v36, v66, 1.0
	v_add_f32_e32 v9, v9, v36
	v_mul_f32_e32 v8, v8, v9
	v_add_f32_e32 v9, -1.0, v96
	v_add_f32_e32 v36, -1.0, v99
	v_fma_f32 v9, v9, v67, 1.0
	v_fma_f32 v36, v36, v67, 1.0
	v_fmac_f32_e32 v105, v70, v8
	v_mul_f32_e32 v8, v88, v92
	v_add_f32_e32 v9, v9, v36
	v_mul_f32_e32 v8, v8, v9
	v_fmac_f32_e32 v105, v71, v8
	global_load_dwordx4 v[64:67], v[124:125], off offset:128
	global_load_dwordx4 v[68:71], v[126:127], off offset:128
	v_lshlrev_b32_e32 v8, 16, v56
	v_and_b32_e32 v9, 0xffff0000, v56
	v_lshlrev_b32_e32 v36, 16, v57
	v_and_b32_e32 v56, 0xffff0000, v57
	v_lshlrev_b32_e32 v57, 16, v60
	v_lshlrev_b32_e32 v89, 16, v84
	s_waitcnt lgkmcnt(1)
	v_lshlrev_b32_e32 v91, 16, v80
	v_mul_f32_e32 v8, v8, v57
	v_add_f32_e32 v57, -1.0, v89
	v_add_f32_e32 v89, -1.0, v91
	v_and_b32_e32 v60, 0xffff0000, v60
	v_and_b32_e32 v84, 0xffff0000, v84
	v_and_b32_e32 v80, 0xffff0000, v80
	v_lshlrev_b32_e32 v88, 16, v61
	v_lshlrev_b32_e32 v90, 16, v85
	v_lshlrev_b32_e32 v92, 16, v81
	v_and_b32_e32 v85, 0xffff0000, v85
	v_and_b32_e32 v81, 0xffff0000, v81
	v_and_b32_e32 v61, 0xffff0000, v61
	s_waitcnt vmcnt(1)
	v_fma_f32 v57, v57, v64, 1.0
	v_fma_f32 v64, v89, v64, 1.0
	v_add_f32_e32 v57, v57, v64
	v_mul_f32_e32 v8, v8, v57
	s_waitcnt vmcnt(0)
	v_fmac_f32_e32 v105, v68, v8
	v_mul_f32_e32 v8, v9, v60
	v_add_f32_e32 v9, -1.0, v84
	v_add_f32_e32 v57, -1.0, v80
	v_fma_f32 v9, v9, v65, 1.0
	v_fma_f32 v57, v57, v65, 1.0
	v_add_f32_e32 v9, v9, v57
	v_mul_f32_e32 v8, v8, v9
	v_fmac_f32_e32 v105, v69, v8
	v_mul_f32_e32 v8, v36, v88
	v_add_f32_e32 v9, -1.0, v90
	v_add_f32_e32 v36, -1.0, v92
	v_fma_f32 v9, v9, v66, 1.0
	v_fma_f32 v36, v36, v66, 1.0
	v_add_f32_e32 v9, v9, v36
	v_mul_f32_e32 v8, v8, v9
	v_add_f32_e32 v9, -1.0, v85
	v_add_f32_e32 v36, -1.0, v81
	v_fma_f32 v9, v9, v67, 1.0
	v_fma_f32 v36, v36, v67, 1.0
	v_fmac_f32_e32 v105, v70, v8
	v_mul_f32_e32 v8, v56, v61
	v_add_f32_e32 v9, v9, v36
	v_mul_f32_e32 v8, v8, v9
	v_fmac_f32_e32 v105, v71, v8
	global_load_dwordx4 v[64:67], v[124:125], off offset:160
	global_load_dwordx4 v[68:71], v[126:127], off offset:160
	v_lshlrev_b32_e32 v8, 16, v58
	v_lshlrev_b32_e32 v36, 16, v62
	v_lshlrev_b32_e32 v57, 16, v86
	v_lshlrev_b32_e32 v60, 16, v82
	v_mul_f32_e32 v8, v8, v36
	v_add_f32_e32 v36, -1.0, v57
	v_add_f32_e32 v57, -1.0, v60
	v_and_b32_e32 v9, 0xffff0000, v58
	v_and_b32_e32 v56, 0xffff0000, v62
	v_and_b32_e32 v58, 0xffff0000, v86
	v_and_b32_e32 v61, 0xffff0000, v82
	v_lshlrev_b32_e32 v60, 16, v83
	s_waitcnt vmcnt(1)
	v_fma_f32 v36, v36, v64, 1.0
	v_fma_f32 v57, v57, v64, 1.0
	v_add_f32_e32 v36, v36, v57
	v_mul_f32_e32 v8, v8, v36
	s_waitcnt vmcnt(0)
; __device__ __forceinline__ void unpack4(u32x2 w, float (&f)[4]) { f[0] = __uint_as_float(w.x << 16); f[1] = __uint_as_float(w.x & 0xffff0000u); f[2] = __uint_as_float(w.y << 16); f[3] = __uint_as_float(w.y & 0xffff0000u); }
; __device__ __forceinline__ void ph_fin4(Ctx& C) {
;     ...
;               for (int gr = 0; gr < 4; ++gr) { const int co = 32 * vt + 8 * gr + 4 * hh; float fr_[4], fk[4], fa0[4], fa1[4]; unpack4(q0[vt][gr], fr_); unpack4(q1[vt][gr], fk); unpack4(q2[vt][gr], fa0); unpack4(q3[vt][gr], fa1);
;                   const f32x4 ka4 = *(const f32x4*)(k_a + h * 64 + co), rk4 = *(const f32x4*)(r_k + h * 64 + co);
; #pragma unroll
;                   for (int e = 0; e < 4; ++e) bsum += fr_[e] * fk[e] * ((1.0f + (fa0[e] - 1.0f) * ka4[e]) + (1.0f + (fa1[e] - 1.0f) * ka4[e])) * rk4[e]; } }
;         ssum += __shfl_xor(ssum, 32); bsum += __shfl_xor(bsum, 32);
	v_fmac_f32_e32 v105, v68, v8
	v_mul_f32_e32 v8, v9, v56
	v_add_f32_e32 v9, -1.0, v58
	v_add_f32_e32 v36, -1.0, v61
	v_fma_f32 v9, v9, v65, 1.0
	v_fma_f32 v36, v36, v65, 1.0
	v_add_f32_e32 v9, v9, v36
	v_mul_f32_e32 v8, v8, v9
	v_fmac_f32_e32 v105, v69, v8
	v_and_b32_e32 v9, 0xffff0000, v59
	v_lshlrev_b32_e32 v8, 16, v59
	v_and_b32_e32 v57, 0xffff0000, v63
	v_lshlrev_b32_e32 v56, 16, v63
	v_and_b32_e32 v59, 0xffff0000, v87
	v_lshlrev_b32_e32 v58, 16, v87
	v_and_b32_e32 v61, 0xffff0000, v83
	v_pk_mul_f32 v[8:9], v[8:9], v[56:57]
	v_pk_add_f32 v[56:57], v[58:59], -1.0 op_sel_hi:[1,0]
	v_pk_add_f32 v[58:59], v[60:61], -1.0 op_sel_hi:[1,0]
	v_pk_fma_f32 v[56:57], v[56:57], v[66:67], 1.0 op_sel_hi:[1,1,0]
	v_pk_fma_f32 v[58:59], v[58:59], v[66:67], 1.0 op_sel_hi:[1,1,0]
	v_and_b32_e32 v65, 0xffff0000, v52
	v_pk_add_f32 v[56:57], v[56:57], v[58:59]
	v_lshlrev_b32_e32 v64, 16, v52
	v_pk_mul_f32 v[8:9], v[8:9], v[56:57]
	global_load_dwordx4 v[56:59], v[124:125], off offset:192
	global_load_dwordx4 v[60:63], v[126:127], off offset:192
	v_pk_mul_f32 v[8:9], v[70:71], v[8:9]
	v_and_b32_e32 v67, 0xffff0000, v76
	v_add_f32_e32 v8, v8, v105
	v_add_f32_e32 v36, v9, v8
	v_and_b32_e32 v9, 0xffff0000, v48
	v_lshlrev_b32_e32 v8, 16, v48
	v_lshlrev_b32_e32 v66, 16, v76
	s_waitcnt lgkmcnt(0)
	v_and_b32_e32 v69, 0xffff0000, v72
	v_lshlrev_b32_e32 v68, 16, v72
	v_pk_mul_f32 v[8:9], v[8:9], v[64:65]
	v_pk_add_f32 v[64:65], v[66:67], -1.0 op_sel_hi:[1,0]
	v_pk_add_f32 v[66:67], v[68:69], -1.0 op_sel_hi:[1,0]
	v_lshlrev_b32_e32 v48, 16, v53
	v_lshlrev_b32_e32 v52, 16, v77
	s_waitcnt vmcnt(1)
	v_pk_fma_f32 v[64:65], v[64:65], v[56:57], 1.0 op_sel_hi:[1,1,0]
	v_pk_fma_f32 v[56:57], v[66:67], v[56:57], 1.0 op_sel_hi:[1,1,0]
	s_nop 0
	v_pk_add_f32 v[56:57], v[64:65], v[56:57]
	v_and_b32_e32 v65, 0xffff0000, v74
	v_pk_mul_f32 v[8:9], v[8:9], v[56:57]
	v_and_b32_e32 v57, 0xffff0000, v73
	s_waitcnt vmcnt(0)
	v_pk_mul_f32 v[8:9], v[60:61], v[8:9]
	v_lshlrev_b32_e32 v56, 16, v73
	v_add_f32_e32 v8, v8, v36
	v_add_f32_e32 v36, v9, v8
	v_and_b32_e32 v9, 0xffff0000, v49
	v_lshlrev_b32_e32 v8, 16, v49
	v_and_b32_e32 v49, 0xffff0000, v53
	v_and_b32_e32 v53, 0xffff0000, v77
	v_pk_mul_f32 v[8:9], v[8:9], v[48:49]
	v_pk_add_f32 v[48:49], v[52:53], -1.0 op_sel_hi:[1,0]
	v_pk_add_f32 v[52:53], v[56:57], -1.0 op_sel_hi:[1,0]
	v_pk_fma_f32 v[48:49], v[48:49], v[58:59], 1.0 op_sel_hi:[1,1,0]
	v_pk_fma_f32 v[52:53], v[52:53], v[58:59], 1.0 op_sel_hi:[1,1,0]
	v_lshlrev_b32_e32 v64, 16, v74
	v_pk_add_f32 v[48:49], v[48:49], v[52:53]
	v_and_b32_e32 v53, 0xffff0000, v78
	v_pk_mul_f32 v[8:9], v[8:9], v[48:49]
	v_and_b32_e32 v49, 0xffff0000, v54
	v_pk_mul_f32 v[8:9], v[62:63], v[8:9]
	global_load_dwordx4 v[56:59], v[124:125], off offset:224
	global_load_dwordx4 v[60:63], v[126:127], off offset:224
	v_add_f32_e32 v8, v8, v36
	v_add_f32_e32 v36, v9, v8
	v_and_b32_e32 v9, 0xffff0000, v50
	v_lshlrev_b32_e32 v8, 16, v50
	v_lshlrev_b32_e32 v48, 16, v54
	v_lshlrev_b32_e32 v52, 16, v78
	v_pk_mul_f32 v[8:9], v[8:9], v[48:49]
	v_pk_add_f32 v[48:49], v[52:53], -1.0 op_sel_hi:[1,0]
	v_pk_add_f32 v[52:53], v[64:65], -1.0 op_sel_hi:[1,0]
	v_lshlrev_b32_e32 v50, 16, v79
	ds_write2_b64 v189, v[0:1], v[2:3] offset1:1
	ds_write2_b64 v190, v[4:5], v[6:7] offset1:1
	ds_write2_b64 v191, v[16:17], v[18:19] offset1:1
	ds_write2_b64 v192, v[20:21], v[22:23] offset1:1
	s_waitcnt lgkmcnt(0)
	s_waitcnt vmcnt(1)
	v_pk_fma_f32 v[48:49], v[48:49], v[56:57], 1.0 op_sel_hi:[1,1,0]
	v_pk_fma_f32 v[52:53], v[52:53], v[56:57], 1.0 op_sel_hi:[1,1,0]
	s_nop 0
	v_pk_add_f32 v[48:49], v[48:49], v[52:53]
	v_and_b32_e32 v53, 0xffff0000, v75
	v_pk_mul_f32 v[8:9], v[8:9], v[48:49]
	v_and_b32_e32 v49, 0xffff0000, v55
	s_waitcnt vmcnt(0)
	v_pk_mul_f32 v[8:9], v[60:61], v[8:9]
	v_lshlrev_b32_e32 v48, 16, v55
	v_add_f32_e32 v8, v8, v36
	v_add_f32_e32 v36, v9, v8
	v_and_b32_e32 v9, 0xffff0000, v51
	v_lshlrev_b32_e32 v8, 16, v51
	v_and_b32_e32 v51, 0xffff0000, v79
	v_lshlrev_b32_e32 v52, 16, v75
	v_pk_mul_f32 v[8:9], v[8:9], v[48:49]
	v_pk_add_f32 v[48:49], v[50:51], -1.0 op_sel_hi:[1,0]
	v_pk_add_f32 v[50:51], v[52:53], -1.0 op_sel_hi:[1,0]
	v_pk_fma_f32 v[48:49], v[48:49], v[58:59], 1.0 op_sel_hi:[1,1,0]
	v_pk_fma_f32 v[50:51], v[50:51], v[58:59], 1.0 op_sel_hi:[1,1,0]
	s_nop 0
	v_pk_add_f32 v[48:49], v[48:49], v[50:51]
	v_and_b32_e32 v51, 0xffff0000, v35
	v_pk_mul_f32 v[8:9], v[8:9], v[48:49]
	v_lshlrev_b32_e32 v50, 16, v35
	v_pk_mul_f32 v[8:9], v[62:63], v[8:9]
	v_and_b32_e32 v35, 0xffff0000, v34
	v_add_f32_e32 v8, v8, v36
	v_add_f32_e32 v36, v9, v8
	v_and_b32_e32 v9, 64, v182
	v_xor_b32_e32 v8, 32, v182
	v_add_u32_e32 v9, 64, v9
	v_cmp_lt_i32_e32 vcc, v8, v9
	v_and_b32_e32 v9, 0xffff0000, v39
	v_lshlrev_b32_e32 v34, 16, v34
	v_cndmask_b32_e32 v8, v182, v8, vcc
	v_lshlrev_b32_e32 v63, 2, v8
	v_lshlrev_b32_e32 v8, 16, v39
	v_pk_add_f32 v[8:9], v[14:15], v[8:9]
	v_and_b32_e32 v15, 0xffff0000, v38
	v_lshlrev_b32_e32 v14, 16, v38
	v_pk_add_f32 v[12:13], v[12:13], v[14:15]
	v_and_b32_e32 v15, 0xffff0000, v37
	v_lshlrev_b32_e32 v14, 16, v37
	v_pk_add_f32 v[12:13], v[12:13], v[34:35]
	v_and_b32_e32 v35, 0xffff0000, v33
	v_lshlrev_b32_e32 v34, 16, v33
	v_pk_add_f32 v[10:11], v[10:11], v[14:15]
	v_pk_add_f32 v[8:9], v[8:9], v[50:51]
	v_pk_add_f32 v[10:11], v[10:11], v[34:35]
	ds_bpermute_b32 v48, v63, v36
	v_add_f32_e32 v14, v10, v32
	v_add_f32_e32 v14, v11, v14
	v_add_f32_e32 v14, v12, v14
	v_add_f32_e32 v14, v13, v14
	v_add_f32_e32 v14, v8, v14
	v_add_f32_e32 v14, v9, v14
	ds_bpermute_b32 v15, v63, v14
	s_waitcnt lgkmcnt(1)
	v_add_f32_e32 v62, v36, v48
	s_waitcnt lgkmcnt(0)
; __device__ __forceinline__ void unpack4(u32x2 w, float (&f)[4]) { f[0] = __uint_as_float(w.x << 16); f[1] = __uint_as_float(w.x & 0xffff0000u); f[2] = __uint_as_float(w.y << 16); f[3] = __uint_as_float(w.y & 0xffff0000u); }
; __device__ __forceinline__ void ph_fin4(Ctx& C) {
;     ...
;         ssum += __shfl_xor(ssum, 32); bsum += __shfl_xor(bsum, 32);
;         const float mu = ssum * (1.0f / 64.f); float vs = 0.f;
; #pragma unroll
;         for (int vt = 0; vt < 2; ++vt)
; #pragma unroll
;             for (int e = 0; e < 16; ++e) { const float dv = acc[vt][e] - mu; acc[vt][e] = dv; vs += dv * dv; }
;         vs += __shfl_xor(vs, 32);
;         const float rstd = 1.0f / sqrtf(vs * (1.0f / 64.f) + 64e-5f);
;         F4_XPOSE(q0, g2); F4_XPOSE(q1, g3);
; #pragma unroll
;         for (int vt = 0; vt < 2; ++vt)
; #pragma unroll
;             for (int gr = 0; gr < 4; ++gr) { const int co = 32 * vt + 8 * gr + 4 * hh; float fv[4], fg[4]; unpack4(q0[vt][gr], fv); unpack4(q1[vt][gr], fg);
;                 const f32x4 w4 = *(const f32x4*)(lnw + h * 64 + co), b4 = *(const f32x4*)(lnb + h * 64 + co); float o[4];
	v_add_f32_e32 v14, v14, v15
	v_mul_f32_e32 v74, 0x3c800000, v14
	v_pk_add_f32 v[64:65], v[10:11], v[74:75] op_sel_hi:[1,0] neg_lo:[0,1] neg_hi:[0,1]
	v_pk_add_f32 v[60:61], v[8:9], v[74:75] op_sel_hi:[1,0] neg_lo:[0,1] neg_hi:[0,1]
	ds_read2_b64 v[36:39], v193 offset1:2
	ds_read2_b64 v[16:19], v193 offset0:4 offset1:6
	ds_read2_b64 v[8:11], v193 offset0:8 offset1:10
	ds_read2_b64 v[4:7], v193 offset0:12 offset1:14
	s_waitcnt lgkmcnt(0)
	ds_write2_b64 v189, v[24:25], v[26:27] offset1:1
	ds_write2_b64 v190, v[28:29], v[30:31] offset1:1
	ds_write2_b64 v191, v[40:41], v[42:43] offset1:1
	ds_write2_b64 v192, v[44:45], v[46:47] offset1:1
	s_waitcnt lgkmcnt(0)
	v_fmamk_f32 v66, v14, 0xbc800000, v146
	v_fmac_f32_e32 v147, 0xbc800000, v14
	v_pk_add_f32 v[58:59], v[12:13], v[74:75] op_sel_hi:[1,0] neg_lo:[0,1] neg_hi:[0,1]
	ds_read2_b64 v[40:43], v193 offset1:2
	ds_read2_b64 v[46:49], v193 offset0:4 offset1:6
	ds_read2_b64 v[12:15], v193 offset0:8 offset1:10
	ds_read2_b64 v[0:3], v193 offset0:12 offset1:14
	s_waitcnt lgkmcnt(0)
	global_load_dwordx4 v[22:25], v[128:129], off
	global_load_dwordx4 v[26:29], v[144:145], off
	s_waitcnt lgkmcnt(11)
	v_lshlrev_b32_e32 v91, 16, v37
	v_lshlrev_b32_e32 v90, 16, v36
	v_and_b32_e32 v87, 0xffff0000, v37
	v_and_b32_e32 v86, 0xffff0000, v36
	s_waitcnt lgkmcnt(3)
	v_lshlrev_b32_e32 v95, 16, v41
	v_lshlrev_b32_e32 v94, 16, v40
	v_and_b32_e32 v93, 0xffff0000, v41
	v_and_b32_e32 v92, 0xffff0000, v40
	global_load_dwordx4 v[30:33], v[128:129], off offset:32
	global_load_dwordx4 v[34:37], v[144:145], off offset:32
	v_lshlrev_b32_e32 v103, 16, v39
	v_lshlrev_b32_e32 v102, 16, v38
	v_and_b32_e32 v101, 0xffff0000, v39
	v_and_b32_e32 v100, 0xffff0000, v38
	v_lshlrev_b32_e32 v107, 16, v43
	v_lshlrev_b32_e32 v106, 16, v42
	v_and_b32_e32 v105, 0xffff0000, v43
	v_and_b32_e32 v104, 0xffff0000, v42
	global_load_dwordx4 v[38:41], v[128:129], off offset:64
	global_load_dwordx4 v[42:45], v[144:145], off offset:64
	global_load_dwordx4 v[50:53], v[128:129], off offset:96
	global_load_dwordx4 v[54:57], v[144:145], off offset:96
	v_pk_add_f32 v[78:79], v[170:171], v[74:75] op_sel_hi:[1,0] neg_lo:[0,1] neg_hi:[0,1]
	v_pk_add_f32 v[76:77], v[172:173], v[74:75] op_sel_hi:[1,0] neg_lo:[0,1] neg_hi:[0,1]
	s_waitcnt lgkmcnt(2)
	v_lshlrev_b32_e32 v203, 16, v49
	v_lshlrev_b32_e32 v202, 16, v48
	v_and_b32_e32 v205, 0xffff0000, v49
	v_and_b32_e32 v204, 0xffff0000, v48
	v_pk_mul_f32 v[80:81], v[78:79], v[78:79]
	v_pk_mul_f32 v[82:83], v[76:77], v[76:77]
	v_pk_add_f32 v[88:89], v[166:167], v[74:75] op_sel_hi:[1,0] neg_lo:[0,1] neg_hi:[0,1]
	v_add_f32_e32 v67, v80, v82
	v_add_f32_e32 v67, v81, v67
	v_pk_add_f32 v[84:85], v[168:169], v[74:75] op_sel_hi:[1,0] neg_lo:[0,1] neg_hi:[0,1]
	v_add_f32_e32 v67, v83, v67
	v_pk_mul_f32 v[166:167], v[84:85], v[84:85]
	v_pk_add_f32 v[156:157], v[156:157], v[74:75] op_sel_hi:[1,0] neg_lo:[0,1] neg_hi:[0,1]
	s_waitcnt lgkmcnt(1)
	v_lshlrev_b32_e32 v217, 16, v13
	v_pk_mul_f32 v[210:211], v[156:157], v[156:157]
	v_lshlrev_b32_e32 v216, 16, v12
	v_and_b32_e32 v219, 0xffff0000, v13
	v_and_b32_e32 v218, 0xffff0000, v12
	v_pk_add_f32 v[12:13], v[150:151], v[74:75] op_sel_hi:[1,0] neg_lo:[0,1] neg_hi:[0,1]
	v_lshlrev_b32_e32 v213, 16, v9
	v_lshlrev_b32_e32 v212, 16, v8
	v_and_b32_e32 v215, 0xffff0000, v9
	v_and_b32_e32 v214, 0xffff0000, v8
	v_pk_add_f32 v[8:9], v[148:149], v[74:75] op_sel_hi:[1,0] neg_lo:[0,1] neg_hi:[0,1]
	v_pk_mul_f32 v[68:69], v[64:65], v[64:65]
	v_pk_mul_f32 v[70:71], v[58:59], v[58:59]
	v_pk_mul_f32 v[72:73], v[60:61], v[60:61]
	v_lshlrev_b32_e32 v199, 16, v19
	v_lshlrev_b32_e32 v198, 16, v18
	v_and_b32_e32 v201, 0xffff0000, v19
	v_and_b32_e32 v200, 0xffff0000, v18
	v_lshlrev_b32_e32 v169, 16, v47
	v_lshlrev_b32_e32 v168, 16, v46
	v_and_b32_e32 v47, 0xffff0000, v47
	v_and_b32_e32 v46, 0xffff0000, v46
	s_waitcnt vmcnt(7)
	v_mov_b32_e32 v96, v22
	s_waitcnt vmcnt(6)
	v_mov_b32_e32 v98, v26
	v_mov_b32_e32 v99, v28
	v_mov_b32_e32 v28, v27
	v_pk_mul_f32 v[26:27], v[88:89], v[88:89]
	v_mov_b32_e32 v97, v24
	v_add_f32_e32 v26, v26, v67
	v_add_f32_e32 v26, v166, v26
	v_add_f32_e32 v26, v27, v26
	s_waitcnt vmcnt(5)
	v_mov_b32_e32 v108, v30
	s_waitcnt vmcnt(4)
	v_mov_b32_e32 v110, v34
	v_mov_b32_e32 v111, v36
	v_mov_b32_e32 v36, v35
	v_pk_add_f32 v[34:35], v[162:163], v[74:75] op_sel_hi:[1,0] neg_lo:[0,1] neg_hi:[0,1]
	v_mov_b32_e32 v109, v32
	v_mov_b32_e32 v32, v31
	v_pk_mul_f32 v[174:175], v[34:35], v[34:35]
	v_pk_add_f32 v[30:31], v[164:165], v[74:75] op_sel_hi:[1,0] neg_lo:[0,1] neg_hi:[0,1]
	s_waitcnt vmcnt(3)
	v_mov_b32_e32 v170, v38
	v_mov_b32_e32 v171, v40
	s_waitcnt vmcnt(2)
	v_mov_b32_e32 v172, v42
	v_mov_b32_e32 v173, v44
	v_mov_b32_e32 v40, v39
	v_mov_b32_e32 v44, v43
	v_pk_add_f32 v[42:43], v[158:159], v[74:75] op_sel_hi:[1,0] neg_lo:[0,1] neg_hi:[0,1]
	v_pk_add_f32 v[38:39], v[160:161], v[74:75] op_sel_hi:[1,0] neg_lo:[0,1] neg_hi:[0,1]
	s_waitcnt vmcnt(1)
	v_mov_b32_e32 v206, v50
	v_mov_b32_e32 v207, v52
	v_mov_b32_e32 v52, v51
	global_load_dwordx4 v[48:51], v[128:129], off offset:128
	global_load_dwordx4 v[158:161], v[144:145], off offset:128
	v_add_f32_e32 v26, v167, v26
	v_pk_mul_f32 v[176:177], v[30:31], v[30:31]
	v_add_f32_e32 v26, v174, v26
	v_add_f32_e32 v26, v176, v26
	v_add_f32_e32 v26, v175, v26
	v_pk_mul_f32 v[194:195], v[42:43], v[42:43]
	v_add_f32_e32 v26, v177, v26
	v_pk_mul_f32 v[196:197], v[38:39], v[38:39]
	v_add_f32_e32 v26, v194, v26
	v_add_f32_e32 v26, v196, v26
	s_waitcnt vmcnt(2)
; #define LAS __attribute__((address_space(3)))
; __device__ __forceinline__ unsigned pk2(float lo, float hi) { return (unsigned)f2bf(lo) | ((unsigned)f2bf(hi) << 16); }
; __device__ __forceinline__ void unpack4(u32x2 w, float (&f)[4]) { f[0] = __uint_as_float(w.x << 16); f[1] = __uint_as_float(w.x & 0xffff0000u); f[2] = __uint_as_float(w.y << 16); f[3] = __uint_as_float(w.y & 0xffff0000u); }
; __device__ __forceinline__ void ph_fin4(Ctx& C) {
;     ...
;         ssum += __shfl_xor(ssum, 32); bsum += __shfl_xor(bsum, 32);
;         const float mu = ssum * (1.0f / 64.f); float vs = 0.f;
; #pragma unroll
;         for (int vt = 0; vt < 2; ++vt)
; #pragma unroll
;             for (int e = 0; e < 16; ++e) { const float dv = acc[vt][e] - mu; acc[vt][e] = dv; vs += dv * dv; }
;         vs += __shfl_xor(vs, 32);
;         const float rstd = 1.0f / sqrtf(vs * (1.0f / 64.f) + 64e-5f);
;         F4_XPOSE(q0, g2); F4_XPOSE(q1, g3);
; #pragma unroll
;         for (int vt = 0; vt < 2; ++vt)
; #pragma unroll
;             for (int gr = 0; gr < 4; ++gr) { const int co = 32 * vt + 8 * gr + 4 * hh; float fv[4], fg[4]; unpack4(q0[vt][gr], fv); unpack4(q1[vt][gr], fg);
;                 const f32x4 w4 = *(const f32x4*)(lnw + h * 64 + co), b4 = *(const f32x4*)(lnb + h * 64 + co); float o[4];
; #pragma unroll
;                 for (int e = 0; e < 4; ++e) o[e] = (acc[vt][4 * gr + e] * rstd * w4[e] + b4[e] + bsum * fv[e]) * fg[e];
;                 u32x2 w; w.x = pk2(o[0], o[1]); w.y = pk2(o[2], o[3]); *(LAS u32x2*)(tr + r31 * F4_TSTR + co) = w; }
	v_mov_b32_e32 v208, v54
	v_mov_b32_e32 v209, v56
	v_mov_b32_e32 v56, v55
	v_pk_add_f32 v[54:55], v[154:155], v[74:75] op_sel_hi:[1,0] neg_lo:[0,1] neg_hi:[0,1]
	v_add_f32_e32 v26, v195, v26
	v_pk_mul_f32 v[154:155], v[54:55], v[54:55]
	v_add_f32_e32 v26, v197, v26
	v_add_f32_e32 v26, v154, v26
	v_add_f32_e32 v26, v210, v26
	v_add_f32_e32 v26, v155, v26
	v_add_f32_e32 v26, v211, v26
	v_pk_mul_f32 v[74:75], v[8:9], v[8:9]
	v_mov_b32_e32 v24, v23
	v_lshlrev_b32_e32 v165, 16, v17
	v_lshlrev_b32_e32 v164, 16, v16
	v_and_b32_e32 v163, 0xffff0000, v17
	v_and_b32_e32 v162, 0xffff0000, v16
	global_load_dwordx4 v[16:19], v[128:129], off offset:160
	global_load_dwordx4 v[20:23], v[144:145], off offset:160
	s_waitcnt vmcnt(3)
	v_mov_b32_e32 v220, v48
	v_mov_b32_e32 v221, v50
	v_mov_b32_e32 v50, v49
	v_pk_mul_f32 v[48:49], v[12:13], v[12:13]
	s_waitcnt vmcnt(2)
	v_mov_b32_e32 v222, v158
	v_add_f32_e32 v26, v48, v26
	v_add_f32_e32 v26, v74, v26
	v_add_f32_e32 v26, v49, v26
	v_add_f32_e32 v26, v75, v26
	v_fmac_f32_e32 v26, v66, v66
	v_fmac_f32_e32 v26, v147, v147
	v_add_f32_e32 v26, v68, v26
	v_add_f32_e32 v26, v69, v26
	v_add_f32_e32 v26, v70, v26
	v_add_f32_e32 v26, v71, v26
	v_add_f32_e32 v26, v72, v26
	v_add_f32_e32 v26, v73, v26
	ds_bpermute_b32 v27, v63, v26
	v_mov_b32_e32 v223, v160
	v_mov_b32_e32 v160, v159
	s_waitcnt lgkmcnt(0)
	v_add_f32_e32 v26, v26, v27
	v_fmamk_f32 v26, v26, 0x3c800000, v180
	v_cmp_gt_f32_e32 vcc, s55, v26
	v_mul_f32_e32 v27, 0x4f800000, v26
	s_nop 0
	v_cndmask_b32_e32 v26, v26, v27, vcc
	v_sqrt_f32_e32 v27, v26
	s_nop 0
	v_add_u32_e32 v48, -1, v27
	v_fma_f32 v49, -v48, v27, v26
	v_cmp_ge_f32_e64 s[4:5], 0, v49
	v_add_u32_e32 v49, 1, v27
	s_nop 0
	v_cndmask_b32_e64 v48, v27, v48, s[4:5]
	v_fma_f32 v27, -v49, v27, v26
	v_cmp_lt_f32_e64 s[4:5], 0, v27
	s_nop 1
	v_cndmask_b32_e64 v27, v48, v49, s[4:5]
	v_mul_f32_e32 v48, 0x37800000, v27
	v_cndmask_b32_e32 v27, v27, v48, vcc
	v_cmp_class_f32_e32 vcc, v26, v181
	s_mov_b64 s[4:5], 0
	s_nop 0
	v_cndmask_b32_e32 v26, v27, v26, vcc
	v_div_scale_f32 v27, s[0:1], v26, v26, 1.0
	v_rcp_f32_e32 v48, v27
	s_movk_i32 s0, 0x100
	v_fma_f32 v49, -v27, v48, 1.0
	v_fmac_f32_e32 v48, v49, v48
	v_div_scale_f32 v49, vcc, 1.0, v26, 1.0
	v_mul_f32_e32 v63, v49, v48
	v_fma_f32 v67, -v27, v63, v49
	v_fmac_f32_e32 v63, v67, v48
	v_fma_f32 v27, -v27, v63, v49
	v_div_fmas_f32 v27, v27, v48, v63
	v_div_fixup_f32 v26, v27, v26, 1.0
	v_pk_mul_f32 v[48:49], v[78:79], v[26:27] op_sel_hi:[1,0]
	v_pk_mul_f32 v[68:69], v[76:77], v[26:27] op_sel_hi:[1,0]
	v_pk_fma_f32 v[48:49], v[96:97], v[48:49], v[98:99]
	v_pk_fma_f32 v[24:25], v[24:25], v[68:69], v[28:29]
	v_pk_fma_f32 v[48:49], v[62:63], v[90:91], v[48:49] op_sel_hi:[0,1,1]
	v_pk_mul_f32 v[48:49], v[48:49], v[94:95]
	v_pk_fma_f32 v[24:25], v[62:63], v[86:87], v[24:25] op_sel_hi:[0,1,1]
	v_pk_mul_f32 v[24:25], v[24:25], v[92:93]
	v_and_b32_sdwa v28, v48, v183 dst_sel:DWORD dst_unused:UNUSED_PAD src0_sel:WORD_1 src1_sel:DWORD
	v_add3_u32 v28, v48, v28, s56
	v_and_b32_sdwa v48, v24, v183 dst_sel:DWORD dst_unused:UNUSED_PAD src0_sel:WORD_1 src1_sel:DWORD
	v_and_b32_sdwa v27, v49, v183 dst_sel:DWORD dst_unused:UNUSED_PAD src0_sel:WORD_1 src1_sel:DWORD
	v_add3_u32 v24, v24, v48, s56
	v_add3_u32 v27, v49, v27, s56
	v_and_b32_sdwa v29, v25, v183 dst_sel:DWORD dst_unused:UNUSED_PAD src0_sel:WORD_1 src1_sel:DWORD
	v_and_b32_e32 v24, 0xffff0000, v24
	v_add3_u32 v25, v25, v29, s56
	v_or_b32_sdwa v24, v24, v28 dst_sel:DWORD dst_unused:UNUSED_PAD src0_sel:DWORD src1_sel:WORD_1
	v_pk_mul_f32 v[28:29], v[88:89], v[26:27] op_sel_hi:[1,0]
	v_pk_mul_f32 v[48:49], v[84:85], v[26:27] op_sel_hi:[1,0]
	v_pk_fma_f32 v[28:29], v[28:29], v[108:109], v[110:111]
	v_pk_fma_f32 v[32:33], v[48:49], v[32:33], v[36:37]
	v_pk_fma_f32 v[28:29], v[62:63], v[102:103], v[28:29] op_sel_hi:[0,1,1]
	v_and_b32_e32 v25, 0xffff0000, v25
	v_pk_mul_f32 v[28:29], v[28:29], v[106:107]
	v_pk_fma_f32 v[32:33], v[62:63], v[100:101], v[32:33] op_sel_hi:[0,1,1]
	v_or_b32_sdwa v25, v25, v27 dst_sel:DWORD dst_unused:UNUSED_PAD src0_sel:DWORD src1_sel:WORD_1
	v_pk_mul_f32 v[32:33], v[32:33], v[104:105]
	v_and_b32_sdwa v27, v29, v183 dst_sel:DWORD dst_unused:UNUSED_PAD src0_sel:WORD_1 src1_sel:DWORD
	v_and_b32_sdwa v36, v28, v183 dst_sel:DWORD dst_unused:UNUSED_PAD src0_sel:WORD_1 src1_sel:DWORD
	v_add3_u32 v28, v28, v36, s56
	v_add3_u32 v27, v29, v27, s56
	v_and_b32_sdwa v29, v33, v183 dst_sel:DWORD dst_unused:UNUSED_PAD src0_sel:WORD_1 src1_sel:DWORD
	v_and_b32_sdwa v36, v32, v183 dst_sel:DWORD dst_unused:UNUSED_PAD src0_sel:WORD_1 src1_sel:DWORD
	v_add3_u32 v29, v33, v29, s56
	v_add3_u32 v32, v32, v36, s56
	v_and_b32_e32 v29, 0xffff0000, v29
	v_and_b32_e32 v32, 0xffff0000, v32
	v_or_b32_sdwa v29, v29, v27 dst_sel:DWORD dst_unused:UNUSED_PAD src0_sel:DWORD src1_sel:WORD_1
	v_or_b32_sdwa v28, v32, v28 dst_sel:DWORD dst_unused:UNUSED_PAD src0_sel:DWORD src1_sel:WORD_1
	ds_write2_b64 v193, v[24:25], v[28:29] offset1:2
	v_pk_mul_f32 v[24:25], v[34:35], v[26:27] op_sel_hi:[1,0]
	v_pk_mul_f32 v[28:29], v[30:31], v[26:27] op_sel_hi:[1,0]
	v_pk_fma_f32 v[24:25], v[24:25], v[170:171], v[172:173]
	v_pk_fma_f32 v[28:29], v[28:29], v[40:41], v[44:45]
	v_pk_fma_f32 v[24:25], v[62:63], v[164:165], v[24:25] op_sel_hi:[0,1,1]
	v_pk_mul_f32 v[24:25], v[24:25], v[168:169]
	v_pk_fma_f32 v[28:29], v[62:63], v[162:163], v[28:29] op_sel_hi:[0,1,1]
	v_pk_mul_f32 v[28:29], v[28:29], v[46:47]
	v_and_b32_sdwa v27, v25, v183 dst_sel:DWORD dst_unused:UNUSED_PAD src0_sel:WORD_1 src1_sel:DWORD
	v_and_b32_sdwa v30, v24, v183 dst_sel:DWORD dst_unused:UNUSED_PAD src0_sel:WORD_1 src1_sel:DWORD
	v_add3_u32 v24, v24, v30, s56
	v_add3_u32 v25, v25, v27, s56
; #define LAS __attribute__((address_space(3)))
; __device__ __forceinline__ unsigned pk2(float lo, float hi) { return (unsigned)f2bf(lo) | ((unsigned)f2bf(hi) << 16); }
; __device__ __forceinline__ void unpack4(u32x2 w, float (&f)[4]) { f[0] = __uint_as_float(w.x << 16); f[1] = __uint_as_float(w.x & 0xffff0000u); f[2] = __uint_as_float(w.y << 16); f[3] = __uint_as_float(w.y & 0xffff0000u); }
; __device__ __forceinline__ void ph_fin4(Ctx& C) {
;     ...
;         F4_XPOSE(q0, g2); F4_XPOSE(q1, g3);
; #pragma unroll
;         for (int vt = 0; vt < 2; ++vt)
; #pragma unroll
;             for (int gr = 0; gr < 4; ++gr) { const int co = 32 * vt + 8 * gr + 4 * hh; float fv[4], fg[4]; unpack4(q0[vt][gr], fv); unpack4(q1[vt][gr], fg);
;                 const f32x4 w4 = *(const f32x4*)(lnw + h * 64 + co), b4 = *(const f32x4*)(lnb + h * 64 + co); float o[4];
; #pragma unroll
;                 for (int e = 0; e < 4; ++e) o[e] = (acc[vt][4 * gr + e] * rstd * w4[e] + b4[e] + bsum * fv[e]) * fg[e];
;                 u32x2 w; w.x = pk2(o[0], o[1]); w.y = pk2(o[2], o[3]); *(LAS u32x2*)(tr + r31 * F4_TSTR + co) = w; }
	v_and_b32_sdwa v27, v29, v183 dst_sel:DWORD dst_unused:UNUSED_PAD src0_sel:WORD_1 src1_sel:DWORD
	v_and_b32_sdwa v30, v28, v183 dst_sel:DWORD dst_unused:UNUSED_PAD src0_sel:WORD_1 src1_sel:DWORD
	v_add3_u32 v27, v29, v27, s56
	v_add3_u32 v28, v28, v30, s56
	v_and_b32_e32 v27, 0xffff0000, v27
	v_and_b32_e32 v28, 0xffff0000, v28
	v_or_b32_sdwa v24, v28, v24 dst_sel:DWORD dst_unused:UNUSED_PAD src0_sel:DWORD src1_sel:WORD_1
	v_pk_mul_f32 v[28:29], v[42:43], v[26:27] op_sel_hi:[1,0]
	v_pk_mul_f32 v[30:31], v[38:39], v[26:27] op_sel_hi:[1,0]
	v_pk_fma_f32 v[28:29], v[28:29], v[206:207], v[208:209]
	v_pk_fma_f32 v[30:31], v[30:31], v[52:53], v[56:57]
	v_pk_fma_f32 v[28:29], v[62:63], v[198:199], v[28:29] op_sel_hi:[0,1,1]
	v_pk_mul_f32 v[28:29], v[28:29], v[202:203]
	v_pk_fma_f32 v[30:31], v[62:63], v[200:201], v[30:31] op_sel_hi:[0,1,1]
	v_or_b32_sdwa v25, v27, v25 dst_sel:DWORD dst_unused:UNUSED_PAD src0_sel:DWORD src1_sel:WORD_1
	v_pk_mul_f32 v[30:31], v[30:31], v[204:205]
	v_and_b32_sdwa v27, v29, v183 dst_sel:DWORD dst_unused:UNUSED_PAD src0_sel:WORD_1 src1_sel:DWORD
	v_and_b32_sdwa v32, v28, v183 dst_sel:DWORD dst_unused:UNUSED_PAD src0_sel:WORD_1 src1_sel:DWORD
	v_add3_u32 v28, v28, v32, s56
	v_add3_u32 v27, v29, v27, s56
	v_and_b32_sdwa v29, v31, v183 dst_sel:DWORD dst_unused:UNUSED_PAD src0_sel:WORD_1 src1_sel:DWORD
	v_and_b32_sdwa v32, v30, v183 dst_sel:DWORD dst_unused:UNUSED_PAD src0_sel:WORD_1 src1_sel:DWORD
	v_add3_u32 v29, v31, v29, s56
	v_add3_u32 v30, v30, v32, s56
	v_and_b32_e32 v29, 0xffff0000, v29
	v_and_b32_e32 v30, 0xffff0000, v30
	v_or_b32_sdwa v29, v29, v27 dst_sel:DWORD dst_unused:UNUSED_PAD src0_sel:DWORD src1_sel:WORD_1
	v_or_b32_sdwa v28, v30, v28 dst_sel:DWORD dst_unused:UNUSED_PAD src0_sel:DWORD src1_sel:WORD_1
	ds_write2_b64 v193, v[24:25], v[28:29] offset0:4 offset1:6
	v_pk_mul_f32 v[24:25], v[54:55], v[26:27] op_sel_hi:[1,0]
	v_pk_mul_f32 v[28:29], v[156:157], v[26:27] op_sel_hi:[1,0]
	v_pk_fma_f32 v[24:25], v[24:25], v[220:221], v[222:223]
	v_pk_fma_f32 v[28:29], v[28:29], v[50:51], v[160:161]
	v_pk_fma_f32 v[24:25], v[62:63], v[212:213], v[24:25] op_sel_hi:[0,1,1]
	v_pk_mul_f32 v[24:25], v[24:25], v[216:217]
	v_pk_fma_f32 v[28:29], v[62:63], v[214:215], v[28:29] op_sel_hi:[0,1,1]
	v_pk_mul_f32 v[28:29], v[28:29], v[218:219]
	v_and_b32_sdwa v27, v25, v183 dst_sel:DWORD dst_unused:UNUSED_PAD src0_sel:WORD_1 src1_sel:DWORD
	v_and_b32_sdwa v30, v24, v183 dst_sel:DWORD dst_unused:UNUSED_PAD src0_sel:WORD_1 src1_sel:DWORD
	v_add3_u32 v25, v25, v27, s56
	v_and_b32_sdwa v27, v29, v183 dst_sel:DWORD dst_unused:UNUSED_PAD src0_sel:WORD_1 src1_sel:DWORD
	v_add3_u32 v24, v24, v30, s56
	v_and_b32_sdwa v30, v28, v183 dst_sel:DWORD dst_unused:UNUSED_PAD src0_sel:WORD_1 src1_sel:DWORD
	v_add3_u32 v27, v29, v27, s56
	v_add3_u32 v28, v28, v30, s56
	v_and_b32_e32 v27, 0xffff0000, v27
	v_and_b32_e32 v28, 0xffff0000, v28
	v_pk_mul_f32 v[12:13], v[12:13], v[26:27] op_sel_hi:[1,0]
	s_waitcnt vmcnt(1)
	v_mov_b32_e32 v32, v16
	v_mov_b32_e32 v33, v18
	s_waitcnt vmcnt(0)
	v_mov_b32_e32 v34, v20
	v_mov_b32_e32 v35, v22
	v_or_b32_sdwa v24, v28, v24 dst_sel:DWORD dst_unused:UNUSED_PAD src0_sel:DWORD src1_sel:WORD_1
	v_lshlrev_b32_e32 v29, 16, v11
	v_lshlrev_b32_e32 v28, 16, v10
	v_pk_fma_f32 v[12:13], v[12:13], v[32:33], v[34:35]
	v_pk_mul_f32 v[8:9], v[8:9], v[26:27] op_sel_hi:[1,0]
	v_mov_b32_e32 v18, v17
	v_mov_b32_e32 v22, v21
	v_and_b32_e32 v11, 0xffff0000, v11
	v_and_b32_e32 v10, 0xffff0000, v10
	v_lshlrev_b32_e32 v31, 16, v15
	v_lshlrev_b32_e32 v30, 16, v14
	v_pk_fma_f32 v[12:13], v[62:63], v[28:29], v[12:13] op_sel_hi:[0,1,1]
	v_pk_fma_f32 v[8:9], v[8:9], v[18:19], v[22:23]
	v_and_b32_e32 v15, 0xffff0000, v15
	v_and_b32_e32 v14, 0xffff0000, v14
	v_pk_mul_f32 v[12:13], v[12:13], v[30:31]
	v_pk_fma_f32 v[8:9], v[62:63], v[10:11], v[8:9] op_sel_hi:[0,1,1]
	v_pk_mul_f32 v[8:9], v[8:9], v[14:15]
	v_and_b32_sdwa v10, v13, v183 dst_sel:DWORD dst_unused:UNUSED_PAD src0_sel:WORD_1 src1_sel:DWORD
	v_and_b32_sdwa v11, v12, v183 dst_sel:DWORD dst_unused:UNUSED_PAD src0_sel:WORD_1 src1_sel:DWORD
	v_add3_u32 v11, v12, v11, s56
	v_add3_u32 v10, v13, v10, s56
	v_and_b32_sdwa v12, v9, v183 dst_sel:DWORD dst_unused:UNUSED_PAD src0_sel:WORD_1 src1_sel:DWORD
	v_and_b32_sdwa v13, v8, v183 dst_sel:DWORD dst_unused:UNUSED_PAD src0_sel:WORD_1 src1_sel:DWORD
	v_add3_u32 v9, v9, v12, s56
	v_add3_u32 v8, v8, v13, s56
	v_and_b32_e32 v9, 0xffff0000, v9
	v_and_b32_e32 v8, 0xffff0000, v8
	v_or_b32_sdwa v25, v27, v25 dst_sel:DWORD dst_unused:UNUSED_PAD src0_sel:DWORD src1_sel:WORD_1
	v_or_b32_sdwa v9, v9, v10 dst_sel:DWORD dst_unused:UNUSED_PAD src0_sel:DWORD src1_sel:WORD_1
	v_or_b32_sdwa v8, v8, v11 dst_sel:DWORD dst_unused:UNUSED_PAD src0_sel:DWORD src1_sel:WORD_1
	ds_write2_b64 v193, v[24:25], v[8:9] offset0:8 offset1:10
	global_load_dwordx4 v[8:11], v[128:129], off offset:192
	global_load_dwordx4 v[12:15], v[144:145], off offset:192
	v_mov_b32_e32 v67, v64
	v_pk_mul_f32 v[20:21], v[66:67], v[26:27] op_sel_hi:[1,0]
	v_lshlrev_b32_e32 v17, 16, v5
	v_lshlrev_b32_e32 v16, 16, v4
	v_lshlrev_b32_e32 v19, 16, v1
	v_lshlrev_b32_e32 v18, 16, v0
	v_mov_b32_e32 v64, v147
	v_and_b32_e32 v5, 0xffff0000, v5
	v_and_b32_e32 v4, 0xffff0000, v4
	v_and_b32_e32 v1, 0xffff0000, v1
	v_and_b32_e32 v0, 0xffff0000, v0
	s_and_b64 vcc, exec, s[2:3]
	s_waitcnt vmcnt(1)
; #define LAS __attribute__((address_space(3)))
; __device__ __forceinline__ unsigned pk2(float lo, float hi) { return (unsigned)f2bf(lo) | ((unsigned)f2bf(hi) << 16); }
; __device__ __forceinline__ void unpack4(u32x2 w, float (&f)[4]) { f[0] = __uint_as_float(w.x << 16); f[1] = __uint_as_float(w.x & 0xffff0000u); f[2] = __uint_as_float(w.y << 16); f[3] = __uint_as_float(w.y & 0xffff0000u); }
; __device__ __forceinline__ void ph_fin4(Ctx& C) {
;     ...
;         F4_XPOSE(q0, g2); F4_XPOSE(q1, g3);
; #pragma unroll
;         for (int vt = 0; vt < 2; ++vt)
; #pragma unroll
;             for (int gr = 0; gr < 4; ++gr) { const int co = 32 * vt + 8 * gr + 4 * hh; float fv[4], fg[4]; unpack4(q0[vt][gr], fv); unpack4(q1[vt][gr], fg);
;                 const f32x4 w4 = *(const f32x4*)(lnw + h * 64 + co), b4 = *(const f32x4*)(lnb + h * 64 + co); float o[4];
; #pragma unroll
;                 for (int e = 0; e < 4; ++e) o[e] = (acc[vt][4 * gr + e] * rstd * w4[e] + b4[e] + bsum * fv[e]) * fg[e];
;                 u32x2 w; w.x = pk2(o[0], o[1]); w.y = pk2(o[2], o[3]); *(LAS u32x2*)(tr + r31 * F4_TSTR + co) = w; }
;         asm volatile("s_waitcnt lgkmcnt(0)" ::: "memory");
; #pragma unroll
;         for (int i = 0; i < 4; ++i) { const int tk = (lane >> 3) + 8 * i; const LAS u32x2* s_ = (const LAS u32x2*)(tr + tk * F4_TSTR + 8 * (lane & 7)); const u32x2 lo_ = s_[0], hi_ = s_[1]; *(u32x4*)(orw + base_f + (size_t)tk * RW + 8 * (lane & 7)) = (u32x4){lo_.x, lo_.y, hi_.x, hi_.y}; }
;         asm volatile("s_waitcnt lgkmcnt(0)" ::: "memory");
	v_mov_b32_e32 v22, v8
	v_mov_b32_e32 v23, v10
	s_waitcnt vmcnt(0)
	v_mov_b32_e32 v24, v12
	v_mov_b32_e32 v25, v14
	v_pk_fma_f32 v[20:21], v[20:21], v[22:23], v[24:25]
	v_mov_b32_e32 v10, v9
	v_pk_fma_f32 v[16:17], v[62:63], v[16:17], v[20:21] op_sel_hi:[0,1,1]
	v_pk_mul_f32 v[16:17], v[16:17], v[18:19]
	v_pk_mul_f32 v[18:19], v[64:65], v[26:27] op_sel_hi:[1,0]
	v_mov_b32_e32 v14, v13
	v_pk_fma_f32 v[8:9], v[18:19], v[10:11], v[14:15]
	v_mov_b32_e32 v18, v58
	v_pk_fma_f32 v[4:5], v[62:63], v[4:5], v[8:9] op_sel_hi:[0,1,1]
	v_pk_mul_f32 v[0:1], v[4:5], v[0:1]
	v_mov_b32_e32 v19, v60
	v_and_b32_sdwa v8, v1, v183 dst_sel:DWORD dst_unused:UNUSED_PAD src0_sel:WORD_1 src1_sel:DWORD
	v_and_b32_sdwa v9, v0, v183 dst_sel:DWORD dst_unused:UNUSED_PAD src0_sel:WORD_1 src1_sel:DWORD
	v_add3_u32 v1, v1, v8, s56
	v_add3_u32 v0, v0, v9, s56
	global_load_dwordx4 v[8:11], v[128:129], off offset:224
	global_load_dwordx4 v[12:15], v[144:145], off offset:224
	v_and_b32_sdwa v4, v17, v183 dst_sel:DWORD dst_unused:UNUSED_PAD src0_sel:WORD_1 src1_sel:DWORD
	v_and_b32_sdwa v5, v16, v183 dst_sel:DWORD dst_unused:UNUSED_PAD src0_sel:WORD_1 src1_sel:DWORD
	v_pk_mul_f32 v[18:19], v[18:19], v[26:27] op_sel_hi:[1,0]
	v_add3_u32 v5, v16, v5, s56
	v_add3_u32 v4, v17, v4, s56
	v_and_b32_e32 v1, 0xffff0000, v1
	v_and_b32_e32 v0, 0xffff0000, v0
	v_lshlrev_b32_e32 v17, 16, v7
	v_lshlrev_b32_e32 v16, 16, v6
	v_or_b32_sdwa v1, v1, v4 dst_sel:DWORD dst_unused:UNUSED_PAD src0_sel:DWORD src1_sel:WORD_1
	v_or_b32_sdwa v0, v0, v5 dst_sel:DWORD dst_unused:UNUSED_PAD src0_sel:DWORD src1_sel:WORD_1
	v_and_b32_e32 v5, 0xffff0000, v7
	v_and_b32_e32 v4, 0xffff0000, v6
	v_lshlrev_b32_e32 v7, 16, v3
	v_lshlrev_b32_e32 v6, 16, v2
	v_mov_b32_e32 v60, v59
	v_and_b32_e32 v3, 0xffff0000, v3
	v_and_b32_e32 v2, 0xffff0000, v2
	s_waitcnt vmcnt(1)
	v_mov_b32_e32 v20, v8
	v_mov_b32_e32 v21, v10
	s_waitcnt vmcnt(0)
	v_mov_b32_e32 v22, v12
	v_mov_b32_e32 v23, v14
	v_pk_fma_f32 v[18:19], v[18:19], v[20:21], v[22:23]
	v_mov_b32_e32 v10, v9
	v_pk_fma_f32 v[16:17], v[62:63], v[16:17], v[18:19] op_sel_hi:[0,1,1]
	v_pk_mul_f32 v[6:7], v[16:17], v[6:7]
	v_pk_mul_f32 v[16:17], v[60:61], v[26:27] op_sel_hi:[1,0]
	v_mov_b32_e32 v14, v13
	v_pk_fma_f32 v[8:9], v[16:17], v[10:11], v[14:15]
	s_nop 0
	v_pk_fma_f32 v[4:5], v[62:63], v[4:5], v[8:9] op_sel_hi:[0,1,1]
	v_pk_mul_f32 v[2:3], v[4:5], v[2:3]
	v_and_b32_sdwa v4, v7, v183 dst_sel:DWORD dst_unused:UNUSED_PAD src0_sel:WORD_1 src1_sel:DWORD
	v_and_b32_sdwa v5, v6, v183 dst_sel:DWORD dst_unused:UNUSED_PAD src0_sel:WORD_1 src1_sel:DWORD
	v_add3_u32 v5, v6, v5, s56
	v_add3_u32 v4, v7, v4, s56
	v_and_b32_sdwa v6, v3, v183 dst_sel:DWORD dst_unused:UNUSED_PAD src0_sel:WORD_1 src1_sel:DWORD
	v_and_b32_sdwa v7, v2, v183 dst_sel:DWORD dst_unused:UNUSED_PAD src0_sel:WORD_1 src1_sel:DWORD
	v_add3_u32 v3, v3, v6, s56
	v_add3_u32 v2, v2, v7, s56
	v_and_b32_e32 v3, 0xffff0000, v3
	v_and_b32_e32 v2, 0xffff0000, v2
	v_or_b32_sdwa v3, v3, v4 dst_sel:DWORD dst_unused:UNUSED_PAD src0_sel:DWORD src1_sel:WORD_1
	v_or_b32_sdwa v2, v2, v5 dst_sel:DWORD dst_unused:UNUSED_PAD src0_sel:DWORD src1_sel:WORD_1
	ds_write2_b64 v193, v[0:1], v[2:3] offset0:12 offset1:14
	s_waitcnt lgkmcnt(0)
	ds_read2_b64 v[0:3], v189 offset1:1
	v_lshl_add_u64 v[4:5], v[142:143], 0, s[42:43]
	v_lshl_add_u64 v[6:7], v[4:5], 0, v[114:115]
	s_waitcnt lgkmcnt(0)
	global_store_dwordx4 v[6:7], v[0:3], off
	ds_read2_b64 v[0:3], v190 offset1:1
	v_lshl_add_u64 v[6:7], v[4:5], 0, v[118:119]
	s_waitcnt lgkmcnt(0)
	global_store_dwordx4 v[6:7], v[0:3], off
	ds_read2_b64 v[0:3], v191 offset1:1
	v_lshl_add_u64 v[6:7], v[4:5], 0, v[120:121]
	v_lshl_add_u64 v[4:5], v[4:5], 0, v[122:123]
	s_waitcnt lgkmcnt(0)
	global_store_dwordx4 v[6:7], v[0:3], off
	ds_read2_b64 v[0:3], v192 offset1:1
	s_waitcnt lgkmcnt(0)
	global_store_dwordx4 v[4:5], v[0:3], off
	s_waitcnt lgkmcnt(0)
	s_cbranch_vccz .LBB0_895
	s_add_i32 s57, s57, s48
	s_cmpk_gt_i32 s57, 0x1ff
	s_cbranch_scc0 .LBB0_894

.LBB0_1182:
	s_lshl_b32 s0, s60, 8
	v_mov_b32_e32 v142, v147
	v_mov_b32_e32 v143, v146
	s_add_i32 s0, s0, s51
	s_and_b64 vcc, exec, s[2:3]
	v_add_u32_e32 v144, s0, v142
	s_lshl_b32 s0, s59, 8
	s_or_b32 s0, s0, s52
	v_lshl_add_u32 v142, v143, 3, s0
	v_ashrrev_i32_e32 v145, 31, v144
	v_lshlrev_b64 v[152:153], 13, v[144:145]
	v_ashrrev_i32_e32 v143, 31, v142
	v_lshl_add_u64 v[152:153], s[16:17], 0, v[152:153]
	v_lshlrev_b64 v[142:143], 1, v[142:143]
	v_lshl_add_u64 v[156:157], v[152:153], 0, v[142:143]
	v_mov_b32_e32 v162, v156
	v_mov_b32_e32 v163, v157
	global_load_dwordx4 v[164:167], v[162:163], off
	global_load_dwordx4 v[168:171], v[162:163], off offset:256
	s_mov_b64 s[98:99], 0x20000
	v_lshl_add_u64 v[162:163], v[162:163], 0, s[98:99]
	global_load_dwordx4 v[172:175], v[162:163], off
	global_load_dwordx4 v[176:179], v[162:163], off offset:256
	s_mov_b64 s[98:99], 0x20000
	v_lshl_add_u64 v[162:163], v[162:163], 0, s[98:99]
	global_load_dwordx4 v[180:183], v[162:163], off
	global_load_dwordx4 v[184:187], v[162:163], off offset:256
	s_mov_b64 s[98:99], 0x20000
	v_lshl_add_u64 v[162:163], v[162:163], 0, s[98:99]
	global_load_dwordx4 v[188:191], v[162:163], off
	global_load_dwordx4 v[192:195], v[162:163], off offset:256
	s_mov_b64 s[98:99], 0xa0000
	v_lshl_add_u64 v[162:163], v[162:163], 0, s[98:99]
	global_load_dwordx4 v[196:199], v[162:163], off
	global_load_dwordx4 v[200:203], v[162:163], off offset:256
	s_mov_b64 s[98:99], 0x20000
	v_lshl_add_u64 v[162:163], v[162:163], 0, s[98:99]
	global_load_dwordx4 v[204:207], v[162:163], off
	global_load_dwordx4 v[208:211], v[162:163], off offset:256
	s_mov_b64 s[98:99], 0x20000
	v_lshl_add_u64 v[162:163], v[162:163], 0, s[98:99]
	global_load_dwordx4 v[212:215], v[162:163], off
	global_load_dwordx4 v[216:219], v[162:163], off offset:256
	s_mov_b64 s[98:99], 0x20000
	v_lshl_add_u64 v[162:163], v[162:163], 0, s[98:99]
	global_load_dwordx4 v[220:223], v[162:163], off
	global_load_dwordx4 v[224:227], v[162:163], off offset:256
	s_waitcnt vmcnt(15)
	s_nop 1
	v_mov_b32_e32 v152, v164
	v_mov_b32_e32 v153, v165
	v_mov_b32_e32 v154, v166
	v_mov_b32_e32 v155, v167
	s_mov_b64 s[2:3], -1
	s_nop 0
	v_lshlrev_b32_e32 v158, 16, v152
	v_and_b32_e32 v152, 0xffff0000, v152
	v_lshlrev_b32_e32 v159, 16, v153
	v_and_b32_e32 v153, 0xffff0000, v153
	v_lshlrev_b32_e32 v161, 16, v155
	v_and_b32_e32 v155, 0xffff0000, v155
	v_lshlrev_b32_e32 v160, 16, v154
	v_and_b32_e32 v154, 0xffff0000, v154
	v_fma_f32 v124, v124, v158, 0
	v_fma_f32 v125, v125, v152, 0
	v_fma_f32 v126, v126, v159, 0
	v_fma_f32 v127, v127, v153, 0
	v_fma_f32 v123, v123, v155, 0
	v_fma_f32 v152, v120, v160, 0
	v_fma_f32 v153, v121, v154, 0
	v_fma_f32 v154, v122, v161, 0
	v_cvt_pk_bf16_f32 v120, v124, v125
	v_cvt_pk_bf16_f32 v121, v126, v127
	v_cvt_pk_bf16_f32 v122, v152, v153
	v_cvt_pk_bf16_f32 v123, v154, v123
	s_waitcnt vmcnt(14)
	s_nop 1
	v_mov_b32_e32 v124, v168
	v_mov_b32_e32 v125, v169
	v_mov_b32_e32 v126, v170
	v_mov_b32_e32 v127, v171
	v_add_u32_e32 v152, 16, v144
	v_lshlrev_b64 v[154:155], 12, v[144:145]
	v_ashrrev_i32_e32 v153, 31, v152
	v_lshl_add_u64 v[154:155], s[14:15], 0, v[154:155]
	v_lshlrev_b64 v[156:157], 13, v[152:153]
	v_lshl_add_u64 v[154:155], v[154:155], 0, v[142:143]
	v_lshl_add_u64 v[156:157], s[16:17], 0, v[156:157]
	global_store_dwordx4 v[154:155], v[120:123], off
	v_lshl_add_u64 v[156:157], v[156:157], 0, v[142:143]
	s_nop 0
	v_lshlrev_b32_e32 v120, 16, v124
	v_and_b32_e32 v121, 0xffff0000, v124
	v_lshlrev_b32_e32 v122, 16, v125
	v_and_b32_e32 v123, 0xffff0000, v125
	v_lshlrev_b32_e32 v124, 16, v126
	v_and_b32_e32 v125, 0xffff0000, v126
	v_lshlrev_b32_e32 v126, 16, v127
	v_and_b32_e32 v127, 0xffff0000, v127
	v_fma_f32 v116, v116, v120, 0
	v_fma_f32 v117, v117, v121, 0
	v_fma_f32 v118, v118, v122, 0
	v_fma_f32 v119, v119, v123, 0
	v_fma_f32 v115, v115, v127, 0
	v_fma_f32 v120, v112, v124, 0
	v_fma_f32 v121, v113, v125, 0
	v_fma_f32 v122, v114, v126, 0
	v_cvt_pk_bf16_f32 v112, v116, v117
	v_cvt_pk_bf16_f32 v113, v118, v119
	v_cvt_pk_bf16_f32 v114, v120, v121
	v_cvt_pk_bf16_f32 v115, v122, v115
	s_waitcnt vmcnt(14)
	s_nop 1
	v_mov_b32_e32 v116, v172
	v_mov_b32_e32 v117, v173
	v_mov_b32_e32 v118, v174
	v_mov_b32_e32 v119, v175
	s_nop 0
	global_store_dwordx4 v[154:155], v[112:115], off offset:256
	s_nop 0
	s_nop 0
	v_lshlrev_b32_e32 v112, 16, v116
	v_and_b32_e32 v113, 0xffff0000, v116
	v_lshlrev_b32_e32 v114, 16, v117
	v_and_b32_e32 v115, 0xffff0000, v117
	v_lshlrev_b32_e32 v116, 16, v118
	v_and_b32_e32 v117, 0xffff0000, v118
	v_lshlrev_b32_e32 v118, 16, v119
	v_and_b32_e32 v119, 0xffff0000, v119
	v_fma_f32 v108, v108, v112, 0
	v_fma_f32 v109, v109, v113, 0
	v_fma_f32 v110, v110, v114, 0
	v_fma_f32 v111, v111, v115, 0
	v_fma_f32 v107, v107, v119, 0
	v_fma_f32 v112, v104, v116, 0
	v_fma_f32 v113, v105, v117, 0
	v_fma_f32 v114, v106, v118, 0
	v_cvt_pk_bf16_f32 v104, v108, v109
	v_cvt_pk_bf16_f32 v105, v110, v111
	v_cvt_pk_bf16_f32 v106, v112, v113
	v_cvt_pk_bf16_f32 v107, v114, v107
	s_waitcnt vmcnt(14)
	s_nop 1
	v_mov_b32_e32 v108, v176
	v_mov_b32_e32 v109, v177
	v_mov_b32_e32 v110, v178
	v_mov_b32_e32 v111, v179
	v_add_u32_e32 v112, 32, v144
	v_lshlrev_b64 v[114:115], 12, v[152:153]
	v_ashrrev_i32_e32 v113, 31, v112
	v_lshl_add_u64 v[114:115], s[14:15], 0, v[114:115]
	v_lshlrev_b64 v[116:117], 13, v[112:113]
	v_lshl_add_u64 v[114:115], v[114:115], 0, v[142:143]
	v_lshl_add_u64 v[116:117], s[16:17], 0, v[116:117]
	global_store_dwordx4 v[114:115], v[104:107], off
	v_lshl_add_u64 v[116:117], v[116:117], 0, v[142:143]
	s_nop 0
	v_lshlrev_b32_e32 v104, 16, v108
	v_and_b32_e32 v105, 0xffff0000, v108
	v_lshlrev_b32_e32 v106, 16, v109
	v_and_b32_e32 v107, 0xffff0000, v109
	v_lshlrev_b32_e32 v108, 16, v110
	v_and_b32_e32 v109, 0xffff0000, v110
	v_lshlrev_b32_e32 v110, 16, v111
	v_and_b32_e32 v111, 0xffff0000, v111
	v_fma_f32 v100, v100, v104, 0
	v_fma_f32 v101, v101, v105, 0
	v_fma_f32 v102, v102, v106, 0
	v_fma_f32 v103, v103, v107, 0
	v_fma_f32 v99, v99, v111, 0
	v_fma_f32 v104, v96, v108, 0
	v_fma_f32 v105, v97, v109, 0
	v_fma_f32 v106, v98, v110, 0
	v_cvt_pk_bf16_f32 v96, v100, v101
	v_cvt_pk_bf16_f32 v97, v102, v103
	v_cvt_pk_bf16_f32 v98, v104, v105
	v_cvt_pk_bf16_f32 v99, v106, v99
	s_waitcnt vmcnt(14)
	s_nop 1
	v_mov_b32_e32 v100, v180
	v_mov_b32_e32 v101, v181
	v_mov_b32_e32 v102, v182
	v_mov_b32_e32 v103, v183
	s_nop 0
	global_store_dwordx4 v[114:115], v[96:99], off offset:256
	s_nop 0
	s_nop 0
	v_lshlrev_b32_e32 v96, 16, v100
	v_and_b32_e32 v97, 0xffff0000, v100
	v_lshlrev_b32_e32 v98, 16, v101
	v_and_b32_e32 v99, 0xffff0000, v101
	v_lshlrev_b32_e32 v100, 16, v102
	v_and_b32_e32 v101, 0xffff0000, v102
	v_lshlrev_b32_e32 v102, 16, v103
	v_and_b32_e32 v103, 0xffff0000, v103
	v_fma_f32 v92, v92, v96, 0
	v_fma_f32 v93, v93, v97, 0
	v_fma_f32 v94, v94, v98, 0
	v_fma_f32 v95, v95, v99, 0
	v_fma_f32 v91, v91, v103, 0
	v_fma_f32 v96, v88, v100, 0
	v_fma_f32 v97, v89, v101, 0
	v_fma_f32 v98, v90, v102, 0
	v_cvt_pk_bf16_f32 v88, v92, v93
	v_cvt_pk_bf16_f32 v89, v94, v95
	v_cvt_pk_bf16_f32 v90, v96, v97
	v_cvt_pk_bf16_f32 v91, v98, v91
	s_waitcnt vmcnt(14)
	s_nop 1
	v_mov_b32_e32 v92, v184
	v_mov_b32_e32 v93, v185
	v_mov_b32_e32 v94, v186
	v_mov_b32_e32 v95, v187
	v_add_u32_e32 v96, 48, v144
	v_lshlrev_b64 v[98:99], 12, v[112:113]
	v_ashrrev_i32_e32 v97, 31, v96
	v_lshl_add_u64 v[98:99], s[14:15], 0, v[98:99]
	v_lshlrev_b64 v[100:101], 13, v[96:97]
	v_lshl_add_u64 v[98:99], v[98:99], 0, v[142:143]
	v_lshl_add_u64 v[100:101], s[16:17], 0, v[100:101]
	global_store_dwordx4 v[98:99], v[88:91], off
	v_lshl_add_u64 v[100:101], v[100:101], 0, v[142:143]
	s_nop 0
	v_lshlrev_b32_e32 v88, 16, v92
	v_and_b32_e32 v89, 0xffff0000, v92
	v_lshlrev_b32_e32 v90, 16, v93
	v_and_b32_e32 v91, 0xffff0000, v93
	v_lshlrev_b32_e32 v92, 16, v94
	v_and_b32_e32 v93, 0xffff0000, v94
	v_lshlrev_b32_e32 v94, 16, v95
	v_and_b32_e32 v95, 0xffff0000, v95
	v_fma_f32 v84, v84, v88, 0
	v_fma_f32 v85, v85, v89, 0
	v_fma_f32 v86, v86, v90, 0
	v_fma_f32 v87, v87, v91, 0
	v_fma_f32 v83, v83, v95, 0
	v_fma_f32 v88, v80, v92, 0
	v_fma_f32 v89, v81, v93, 0
	v_fma_f32 v90, v82, v94, 0
	v_cvt_pk_bf16_f32 v80, v84, v85
	v_cvt_pk_bf16_f32 v81, v86, v87
	v_cvt_pk_bf16_f32 v82, v88, v89
	v_cvt_pk_bf16_f32 v83, v90, v83
	s_waitcnt vmcnt(14)
	s_nop 1
	v_mov_b32_e32 v84, v188
	v_mov_b32_e32 v85, v189
	v_mov_b32_e32 v86, v190
	v_mov_b32_e32 v87, v191
	s_nop 0
	global_store_dwordx4 v[98:99], v[80:83], off offset:256
	s_nop 0
	s_nop 0
	v_lshlrev_b32_e32 v80, 16, v84
	v_and_b32_e32 v81, 0xffff0000, v84
	v_lshlrev_b32_e32 v82, 16, v85
	v_and_b32_e32 v83, 0xffff0000, v85
	v_lshlrev_b32_e32 v84, 16, v86
	v_and_b32_e32 v85, 0xffff0000, v86
	v_lshlrev_b32_e32 v86, 16, v87
	v_and_b32_e32 v87, 0xffff0000, v87
	v_fma_f32 v76, v76, v80, 0
	v_fma_f32 v77, v77, v81, 0
	v_fma_f32 v78, v78, v82, 0
	v_fma_f32 v79, v79, v83, 0
	v_fma_f32 v75, v75, v87, 0
	v_fma_f32 v80, v72, v84, 0
	v_fma_f32 v81, v73, v85, 0
	v_fma_f32 v82, v74, v86, 0
	v_cvt_pk_bf16_f32 v72, v76, v77
	v_cvt_pk_bf16_f32 v73, v78, v79
	v_cvt_pk_bf16_f32 v74, v80, v81
	v_cvt_pk_bf16_f32 v75, v82, v75
	s_waitcnt vmcnt(14)
	s_nop 1
	v_mov_b32_e32 v76, v192
	v_mov_b32_e32 v77, v193
	v_mov_b32_e32 v78, v194
	v_mov_b32_e32 v79, v195
	v_add_u32_e32 v80, 0x80, v144
	v_lshlrev_b64 v[82:83], 12, v[96:97]
	v_ashrrev_i32_e32 v81, 31, v80
	v_lshl_add_u64 v[82:83], s[14:15], 0, v[82:83]
	v_lshlrev_b64 v[84:85], 13, v[80:81]
	v_lshl_add_u64 v[82:83], v[82:83], 0, v[142:143]
	v_lshl_add_u64 v[84:85], s[16:17], 0, v[84:85]
	global_store_dwordx4 v[82:83], v[72:75], off
	v_lshl_add_u64 v[84:85], v[84:85], 0, v[142:143]
	s_nop 0
	v_lshlrev_b32_e32 v72, 16, v76
	v_and_b32_e32 v73, 0xffff0000, v76
	v_lshlrev_b32_e32 v74, 16, v77
	v_and_b32_e32 v75, 0xffff0000, v77
	v_lshlrev_b32_e32 v76, 16, v78
	v_and_b32_e32 v77, 0xffff0000, v78
	v_lshlrev_b32_e32 v78, 16, v79
	v_and_b32_e32 v79, 0xffff0000, v79
	v_fma_f32 v68, v68, v72, 0
	v_fma_f32 v69, v69, v73, 0
	v_fma_f32 v70, v70, v74, 0
	v_fma_f32 v71, v71, v75, 0
	v_fma_f32 v67, v67, v79, 0
	v_fma_f32 v72, v64, v76, 0
	v_fma_f32 v73, v65, v77, 0
	v_fma_f32 v74, v66, v78, 0
	v_cvt_pk_bf16_f32 v64, v68, v69
	v_cvt_pk_bf16_f32 v65, v70, v71
	v_cvt_pk_bf16_f32 v66, v72, v73
	v_cvt_pk_bf16_f32 v67, v74, v67
	s_waitcnt vmcnt(14)
	s_nop 1
	v_mov_b32_e32 v68, v196
	v_mov_b32_e32 v69, v197
	v_mov_b32_e32 v70, v198
	v_mov_b32_e32 v71, v199
	s_nop 0
	global_store_dwordx4 v[82:83], v[64:67], off offset:256
	s_nop 0
	s_nop 0
	v_lshlrev_b32_e32 v64, 16, v68
	v_and_b32_e32 v65, 0xffff0000, v68
	v_lshlrev_b32_e32 v66, 16, v69
	v_and_b32_e32 v67, 0xffff0000, v69
	v_lshlrev_b32_e32 v68, 16, v70
	v_and_b32_e32 v69, 0xffff0000, v70
	v_lshlrev_b32_e32 v70, 16, v71
	v_and_b32_e32 v71, 0xffff0000, v71
	v_fma_f32 v60, v60, v64, 0
	v_fma_f32 v61, v61, v65, 0
	v_fma_f32 v62, v62, v66, 0
	v_fma_f32 v63, v63, v67, 0
	v_fma_f32 v59, v59, v71, 0
	v_fma_f32 v64, v56, v68, 0
	v_fma_f32 v65, v57, v69, 0
	v_fma_f32 v66, v58, v70, 0
	v_cvt_pk_bf16_f32 v56, v60, v61
	v_cvt_pk_bf16_f32 v57, v62, v63
	v_cvt_pk_bf16_f32 v58, v64, v65
	v_cvt_pk_bf16_f32 v59, v66, v59
	s_waitcnt vmcnt(14)
	s_nop 1
	v_mov_b32_e32 v60, v200
	v_mov_b32_e32 v61, v201
	v_mov_b32_e32 v62, v202
	v_mov_b32_e32 v63, v203
	v_add_u32_e32 v64, 0x90, v144
	v_lshlrev_b64 v[66:67], 12, v[80:81]
	v_ashrrev_i32_e32 v65, 31, v64
	v_lshl_add_u64 v[66:67], s[14:15], 0, v[66:67]
	v_lshlrev_b64 v[68:69], 13, v[64:65]
	v_lshl_add_u64 v[66:67], v[66:67], 0, v[142:143]
	v_lshl_add_u64 v[68:69], s[16:17], 0, v[68:69]
	global_store_dwordx4 v[66:67], v[56:59], off
	v_lshl_add_u64 v[68:69], v[68:69], 0, v[142:143]
	s_nop 0
	v_lshlrev_b32_e32 v56, 16, v60
	v_and_b32_e32 v57, 0xffff0000, v60
	v_lshlrev_b32_e32 v58, 16, v61
	v_and_b32_e32 v59, 0xffff0000, v61
	v_lshlrev_b32_e32 v60, 16, v62
	v_and_b32_e32 v61, 0xffff0000, v62
	v_lshlrev_b32_e32 v62, 16, v63
	v_and_b32_e32 v63, 0xffff0000, v63
	v_fma_f32 v52, v52, v56, 0
	v_fma_f32 v53, v53, v57, 0
	v_fma_f32 v54, v54, v58, 0
	v_fma_f32 v55, v55, v59, 0
	v_fma_f32 v51, v51, v63, 0
	v_fma_f32 v56, v48, v60, 0
	v_fma_f32 v57, v49, v61, 0
	v_fma_f32 v58, v50, v62, 0
	v_cvt_pk_bf16_f32 v48, v52, v53
	v_cvt_pk_bf16_f32 v49, v54, v55
	v_cvt_pk_bf16_f32 v50, v56, v57
	v_cvt_pk_bf16_f32 v51, v58, v51
	s_waitcnt vmcnt(14)
	s_nop 1
	v_mov_b32_e32 v52, v204
	v_mov_b32_e32 v53, v205
	v_mov_b32_e32 v54, v206
	v_mov_b32_e32 v55, v207
	s_nop 0
	global_store_dwordx4 v[66:67], v[48:51], off offset:256
	s_nop 0
	s_nop 0
	v_lshlrev_b32_e32 v48, 16, v52
	v_and_b32_e32 v49, 0xffff0000, v52
	v_lshlrev_b32_e32 v50, 16, v53
	v_and_b32_e32 v51, 0xffff0000, v53
	v_lshlrev_b32_e32 v52, 16, v54
	v_and_b32_e32 v53, 0xffff0000, v54
	v_lshlrev_b32_e32 v54, 16, v55
	v_and_b32_e32 v55, 0xffff0000, v55
	v_fma_f32 v44, v44, v48, 0
	v_fma_f32 v45, v45, v49, 0
	v_fma_f32 v46, v46, v50, 0
	v_fma_f32 v47, v47, v51, 0
	v_fma_f32 v43, v43, v55, 0
	v_fma_f32 v48, v40, v52, 0
	v_fma_f32 v49, v41, v53, 0
	v_fma_f32 v50, v42, v54, 0
	v_cvt_pk_bf16_f32 v40, v44, v45
	v_cvt_pk_bf16_f32 v41, v46, v47
	v_cvt_pk_bf16_f32 v42, v48, v49
	v_cvt_pk_bf16_f32 v43, v50, v43
	s_waitcnt vmcnt(14)
	s_nop 1
	v_mov_b32_e32 v44, v208
	v_mov_b32_e32 v45, v209
	v_mov_b32_e32 v46, v210
	v_mov_b32_e32 v47, v211
	v_add_u32_e32 v48, 0xa0, v144
	v_lshlrev_b64 v[50:51], 12, v[64:65]
	v_ashrrev_i32_e32 v49, 31, v48
	v_lshl_add_u64 v[50:51], s[14:15], 0, v[50:51]
	v_lshlrev_b64 v[52:53], 13, v[48:49]
	v_lshl_add_u64 v[50:51], v[50:51], 0, v[142:143]
	v_lshl_add_u64 v[52:53], s[16:17], 0, v[52:53]
	global_store_dwordx4 v[50:51], v[40:43], off
	v_lshl_add_u64 v[52:53], v[52:53], 0, v[142:143]
	s_nop 0
	v_lshlrev_b32_e32 v40, 16, v44
	v_and_b32_e32 v41, 0xffff0000, v44
	v_lshlrev_b32_e32 v42, 16, v45
	v_and_b32_e32 v43, 0xffff0000, v45
	v_lshlrev_b32_e32 v44, 16, v46
	v_and_b32_e32 v45, 0xffff0000, v46
	v_lshlrev_b32_e32 v46, 16, v47
	v_and_b32_e32 v47, 0xffff0000, v47
	v_fma_f32 v36, v36, v40, 0
	v_fma_f32 v37, v37, v41, 0
	v_fma_f32 v38, v38, v42, 0
	v_fma_f32 v39, v39, v43, 0
	v_fma_f32 v35, v35, v47, 0
	v_fma_f32 v40, v32, v44, 0
	v_fma_f32 v41, v33, v45, 0
	v_fma_f32 v42, v34, v46, 0
	v_cvt_pk_bf16_f32 v32, v36, v37
	v_cvt_pk_bf16_f32 v33, v38, v39
	v_cvt_pk_bf16_f32 v34, v40, v41
	v_cvt_pk_bf16_f32 v35, v42, v35
	s_waitcnt vmcnt(14)
	s_nop 1
	v_mov_b32_e32 v36, v212
	v_mov_b32_e32 v37, v213
	v_mov_b32_e32 v38, v214
	v_mov_b32_e32 v39, v215
	s_nop 0
	global_store_dwordx4 v[50:51], v[32:35], off offset:256
	s_nop 0
	s_nop 0
	v_lshlrev_b32_e32 v32, 16, v36
	v_and_b32_e32 v33, 0xffff0000, v36
	v_lshlrev_b32_e32 v34, 16, v37
	v_and_b32_e32 v35, 0xffff0000, v37
	v_lshlrev_b32_e32 v36, 16, v38
	v_and_b32_e32 v37, 0xffff0000, v38
	v_lshlrev_b32_e32 v38, 16, v39
	v_and_b32_e32 v39, 0xffff0000, v39
	v_fma_f32 v28, v28, v32, 0
	v_fma_f32 v29, v29, v33, 0
	v_fma_f32 v30, v30, v34, 0
	v_fma_f32 v31, v31, v35, 0
	v_fma_f32 v27, v27, v39, 0
	v_fma_f32 v32, v24, v36, 0
	v_fma_f32 v33, v25, v37, 0
	v_fma_f32 v34, v26, v38, 0
	v_cvt_pk_bf16_f32 v24, v28, v29
	v_cvt_pk_bf16_f32 v25, v30, v31
	v_cvt_pk_bf16_f32 v26, v32, v33
	v_cvt_pk_bf16_f32 v27, v34, v27
	s_waitcnt vmcnt(14)
	s_nop 1
	v_mov_b32_e32 v28, v216
	v_mov_b32_e32 v29, v217
	v_mov_b32_e32 v30, v218
	v_mov_b32_e32 v31, v219
	v_add_u32_e32 v32, 0xb0, v144
	v_lshlrev_b64 v[34:35], 12, v[48:49]
	v_ashrrev_i32_e32 v33, 31, v32
	v_lshl_add_u64 v[34:35], s[14:15], 0, v[34:35]
	v_lshlrev_b64 v[36:37], 13, v[32:33]
	v_lshl_add_u64 v[34:35], v[34:35], 0, v[142:143]
	v_lshl_add_u64 v[36:37], s[16:17], 0, v[36:37]
	global_store_dwordx4 v[34:35], v[24:27], off
	v_lshl_add_u64 v[36:37], v[36:37], 0, v[142:143]
	s_nop 0
	v_lshlrev_b32_e32 v24, 16, v28
	v_and_b32_e32 v25, 0xffff0000, v28
	v_lshlrev_b32_e32 v26, 16, v29
	v_and_b32_e32 v27, 0xffff0000, v29
	v_lshlrev_b32_e32 v28, 16, v30
	v_and_b32_e32 v29, 0xffff0000, v30
	v_lshlrev_b32_e32 v30, 16, v31
	v_and_b32_e32 v31, 0xffff0000, v31
	v_fma_f32 v20, v20, v24, 0
	v_fma_f32 v21, v21, v25, 0
	v_fma_f32 v22, v22, v26, 0
	v_fma_f32 v23, v23, v27, 0
	v_fma_f32 v19, v19, v31, 0
	v_fma_f32 v24, v16, v28, 0
	v_fma_f32 v25, v17, v29, 0
	v_fma_f32 v26, v18, v30, 0
	v_cvt_pk_bf16_f32 v16, v20, v21
	v_cvt_pk_bf16_f32 v17, v22, v23
	v_cvt_pk_bf16_f32 v18, v24, v25
	v_cvt_pk_bf16_f32 v19, v26, v19
	s_waitcnt vmcnt(14)
	s_nop 1
	v_mov_b32_e32 v20, v220
	v_mov_b32_e32 v21, v221
	v_mov_b32_e32 v22, v222
	v_mov_b32_e32 v23, v223
	s_nop 0
	global_store_dwordx4 v[34:35], v[16:19], off offset:256
	s_nop 0
	s_nop 0
	v_lshlrev_b32_e32 v16, 16, v20
	v_and_b32_e32 v17, 0xffff0000, v20
	v_lshlrev_b32_e32 v18, 16, v21
	v_and_b32_e32 v19, 0xffff0000, v21
	v_lshlrev_b32_e32 v20, 16, v22
	v_and_b32_e32 v21, 0xffff0000, v22
	v_lshlrev_b32_e32 v22, 16, v23
	v_and_b32_e32 v23, 0xffff0000, v23
	v_fma_f32 v12, v12, v16, 0
	v_fma_f32 v13, v13, v17, 0
	v_fma_f32 v14, v14, v18, 0
	v_fma_f32 v15, v15, v19, 0
	v_fma_f32 v11, v11, v23, 0
	v_fma_f32 v16, v8, v20, 0
	v_fma_f32 v17, v9, v21, 0
	v_fma_f32 v18, v10, v22, 0
	v_cvt_pk_bf16_f32 v8, v12, v13
	v_cvt_pk_bf16_f32 v9, v14, v15
	v_cvt_pk_bf16_f32 v10, v16, v17
	v_cvt_pk_bf16_f32 v11, v18, v11
	s_waitcnt vmcnt(14)
	s_nop 1
	v_mov_b32_e32 v12, v224
	v_mov_b32_e32 v13, v225
	v_mov_b32_e32 v14, v226
	v_mov_b32_e32 v15, v227
	v_lshlrev_b64 v[16:17], 12, v[32:33]
	v_lshl_add_u64 v[16:17], s[14:15], 0, v[16:17]
	v_lshl_add_u64 v[16:17], v[16:17], 0, v[142:143]
	global_store_dwordx4 v[16:17], v[8:11], off
	s_nop 0
	s_nop 0
	v_lshlrev_b32_e32 v8, 16, v12
	v_and_b32_e32 v9, 0xffff0000, v12
	v_lshlrev_b32_e32 v10, 16, v13
	v_and_b32_e32 v11, 0xffff0000, v13
	v_lshlrev_b32_e32 v12, 16, v14
	v_and_b32_e32 v13, 0xffff0000, v14
	v_lshlrev_b32_e32 v14, 16, v15
	v_and_b32_e32 v15, 0xffff0000, v15
	v_fma_f32 v3, v3, v15, 0
	v_fma_f32 v4, v4, v8, 0
	v_fma_f32 v5, v5, v9, 0
	v_fma_f32 v6, v6, v10, 0
	v_fma_f32 v7, v7, v11, 0
	v_fma_f32 v8, v0, v12, 0
	v_fma_f32 v9, v1, v13, 0
	v_fma_f32 v10, v2, v14, 0
	v_cvt_pk_bf16_f32 v0, v4, v5
	v_cvt_pk_bf16_f32 v1, v6, v7
	v_cvt_pk_bf16_f32 v2, v8, v9
	v_cvt_pk_bf16_f32 v3, v10, v3
	global_store_dwordx4 v[16:17], v[0:3], off offset:256
	s_cbranch_vccnz .LBB0_1170
	s_andn2_b64 vcc, exec, s[12:13]
	s_cbranch_vccnz .LBB0_1169
	s_barrier
	s_branch .LBB0_1169

.LBB0_1261:
	s_lshl_b32 s0, s65, 8
	v_mov_b32_e32 v142, v147
	v_mov_b32_e32 v143, v146
	s_add_i32 s0, s0, s55
	s_nop 0
	v_add_u32_e32 v144, s0, v142
	s_lshl_b32 s0, s64, 8
	s_or_b32 s0, s0, s56
	v_lshl_add_u32 v142, v143, 3, s0
	v_ashrrev_i32_e32 v145, 31, v144
	v_lshlrev_b64 v[152:153], 13, v[144:145]
	v_ashrrev_i32_e32 v143, 31, v142
	v_lshl_add_u64 v[152:153], s[16:17], 0, v[152:153]
	v_lshlrev_b64 v[142:143], 1, v[142:143]
	v_lshl_add_u64 v[160:161], v[152:153], 0, v[142:143]
	v_lshlrev_b64 v[156:157], 12, v[144:145]
	v_add_co_u32_e32 v152, vcc, s61, v160
	v_lshl_add_u64 v[156:157], s[14:15], 0, v[156:157]
	s_nop 0
	v_addc_co_u32_e32 v153, vcc, 0, v161, vcc
	v_lshl_add_u64 v[162:163], v[156:157], 0, v[142:143]
	v_mov_b32_e32 v172, v152
	v_mov_b32_e32 v173, v153
	v_mov_b32_e32 v174, v162
	v_mov_b32_e32 v175, v163
	global_load_dwordx4 v[176:179], v[172:173], off
	global_load_dwordx4 v[180:183], v[174:175], off
	global_load_dwordx4 v[184:187], v[172:173], off offset:256
	global_load_dwordx4 v[188:191], v[174:175], off offset:256
	s_mov_b64 s[98:99], 0x20000
	v_lshl_add_u64 v[172:173], v[172:173], 0, s[98:99]
	global_load_dwordx4 v[192:195], v[172:173], off
	s_mov_b64 s[98:99], 0x10000
	v_lshl_add_u64 v[174:175], v[174:175], 0, s[98:99]
	global_load_dwordx4 v[196:199], v[174:175], off
	global_load_dwordx4 v[200:203], v[172:173], off offset:256
	global_load_dwordx4 v[204:207], v[174:175], off offset:256
	s_mov_b64 s[98:99], 0x20000
	v_lshl_add_u64 v[172:173], v[172:173], 0, s[98:99]
	global_load_dwordx4 v[208:211], v[172:173], off
	s_mov_b64 s[98:99], 0x10000
	v_lshl_add_u64 v[174:175], v[174:175], 0, s[98:99]
	global_load_dwordx4 v[212:215], v[174:175], off
	global_load_dwordx4 v[216:219], v[172:173], off offset:256
	global_load_dwordx4 v[220:223], v[174:175], off offset:256
	s_mov_b64 s[98:99], 0x20000
	v_lshl_add_u64 v[172:173], v[172:173], 0, s[98:99]
	global_load_dwordx4 v[224:227], v[172:173], off
	s_mov_b64 s[98:99], 0x10000
	v_lshl_add_u64 v[174:175], v[174:175], 0, s[98:99]
	global_load_dwordx4 v[232:235], v[174:175], off
	global_load_dwordx4 v[236:239], v[172:173], off offset:256
	global_load_dwordx4 v[240:243], v[174:175], off offset:256
	s_mov_b64 s[98:99], 0xa0000
	v_lshl_add_u64 v[172:173], v[172:173], 0, s[98:99]
	global_load_dwordx4 v[244:247], v[172:173], off
	s_mov_b64 s[98:99], 0x50000
	v_lshl_add_u64 v[174:175], v[174:175], 0, s[98:99]
	global_load_dwordx4 v[248:251], v[174:175], off
	global_load_dwordx4 v[252:255], v[172:173], off offset:256
	s_waitcnt vmcnt(18)
	s_nop 1
	v_mov_b32_e32 v152, v176
	v_mov_b32_e32 v153, v177
	v_mov_b32_e32 v154, v178
	v_mov_b32_e32 v155, v179
	global_load_dwordx4 v[176:179], v[174:175], off offset:256
	v_lshl_add_u64 v[160:161], v[160:161], 0, s[24:25]
	s_waitcnt vmcnt(18)
	s_nop 1
	v_mov_b32_e32 v156, v180
	v_mov_b32_e32 v157, v181
	v_mov_b32_e32 v158, v182
	v_mov_b32_e32 v159, v183
	s_mov_b64 s[98:99], 0x20000
	v_lshl_add_u64 v[172:173], v[172:173], 0, s[98:99]
	global_load_dwordx4 v[180:183], v[172:173], off
	s_nop 0
	v_lshlrev_b32_e32 v145, 16, v152
	v_and_b32_e32 v152, 0xffff0000, v152
	v_lshlrev_b32_e32 v164, 16, v153
	v_and_b32_e32 v153, 0xffff0000, v153
	v_lshlrev_b32_e32 v165, 16, v154
	v_and_b32_e32 v154, 0xffff0000, v154
	v_lshlrev_b32_e32 v166, 16, v155
	v_and_b32_e32 v155, 0xffff0000, v155
	v_lshlrev_b32_e32 v167, 16, v156
	v_and_b32_e32 v156, 0xffff0000, v156
	v_lshlrev_b32_e32 v168, 16, v157
	v_and_b32_e32 v157, 0xffff0000, v157
	v_lshlrev_b32_e32 v169, 16, v158
	v_and_b32_e32 v158, 0xffff0000, v158
	v_lshlrev_b32_e32 v170, 16, v159
	v_and_b32_e32 v159, 0xffff0000, v159
	v_fmac_f32_e32 v167, v124, v145
	v_fmac_f32_e32 v156, v125, v152
	v_fmac_f32_e32 v168, v126, v164
	v_fmac_f32_e32 v157, v127, v153
	v_fmac_f32_e32 v169, v120, v165
	v_fmac_f32_e32 v158, v121, v154
	v_fmac_f32_e32 v170, v122, v166
	v_fmac_f32_e32 v159, v123, v155
	v_cvt_pk_bf16_f32 v120, v167, v156
	v_cvt_pk_bf16_f32 v121, v168, v157
	v_cvt_pk_bf16_f32 v122, v169, v158
	v_cvt_pk_bf16_f32 v123, v170, v159
	s_waitcnt vmcnt(18)
	s_nop 1
	v_mov_b32_e32 v124, v184
	v_mov_b32_e32 v125, v185
	v_mov_b32_e32 v126, v186
	v_mov_b32_e32 v127, v187
	s_mov_b64 s[98:99], 0x10000
	v_lshl_add_u64 v[174:175], v[174:175], 0, s[98:99]
	global_load_dwordx4 v[184:187], v[174:175], off
	s_waitcnt vmcnt(18)
	s_nop 1
	v_mov_b32_e32 v152, v188
	v_mov_b32_e32 v153, v189
	v_mov_b32_e32 v154, v190
	v_mov_b32_e32 v155, v191
	global_load_dwordx4 v[188:191], v[172:173], off offset:256
	v_add_u32_e32 v156, 16, v144
	v_ashrrev_i32_e32 v157, 31, v156
	v_lshlrev_b64 v[158:159], 13, v[156:157]
	v_lshl_add_u64 v[158:159], s[16:17], 0, v[158:159]
	global_store_dwordx4 v[162:163], v[120:123], off
	v_lshl_add_u64 v[158:159], v[158:159], 0, v[142:143]
	v_add_co_u32_e32 v160, vcc, s61, v158
	s_nop 0
	v_lshlrev_b32_e32 v120, 16, v124
	v_and_b32_e32 v121, 0xffff0000, v124
	v_lshlrev_b32_e32 v145, 16, v152
	v_and_b32_e32 v152, 0xffff0000, v152
	v_fmac_f32_e32 v145, v116, v120
	v_fmac_f32_e32 v152, v117, v121
	v_lshlrev_b64 v[120:121], 12, v[156:157]
	v_lshlrev_b32_e32 v122, 16, v125
	v_and_b32_e32 v123, 0xffff0000, v125
	v_lshlrev_b32_e32 v124, 16, v126
	v_and_b32_e32 v125, 0xffff0000, v126
	v_lshlrev_b32_e32 v165, 16, v154
	v_and_b32_e32 v154, 0xffff0000, v154
	v_lshl_add_u64 v[120:121], s[14:15], 0, v[120:121]
	v_addc_co_u32_e32 v161, vcc, 0, v159, vcc
	v_lshlrev_b32_e32 v126, 16, v127
	v_and_b32_e32 v127, 0xffff0000, v127
	v_lshlrev_b32_e32 v164, 16, v153
	v_and_b32_e32 v153, 0xffff0000, v153
	v_lshlrev_b32_e32 v166, 16, v155
	v_and_b32_e32 v155, 0xffff0000, v155
	v_fmac_f32_e32 v165, v112, v124
	v_fmac_f32_e32 v154, v113, v125
	v_lshl_add_u64 v[124:125], v[120:121], 0, v[142:143]
	v_fmac_f32_e32 v164, v118, v122
	v_fmac_f32_e32 v153, v119, v123
	v_fmac_f32_e32 v166, v114, v126
	v_fmac_f32_e32 v155, v115, v127
	v_cvt_pk_bf16_f32 v112, v145, v152
	v_cvt_pk_bf16_f32 v113, v164, v153
	v_cvt_pk_bf16_f32 v114, v165, v154
	v_cvt_pk_bf16_f32 v115, v166, v155
	s_waitcnt vmcnt(19)
	s_nop 1
	v_mov_b32_e32 v116, v192
	v_mov_b32_e32 v117, v193
	v_mov_b32_e32 v118, v194
	v_mov_b32_e32 v119, v195
	global_load_dwordx4 v[192:195], v[174:175], off offset:256
	s_waitcnt vmcnt(19)
	s_nop 1
	v_mov_b32_e32 v120, v196
	v_mov_b32_e32 v121, v197
	v_mov_b32_e32 v122, v198
	v_mov_b32_e32 v123, v199
	s_mov_b64 s[98:99], 0x20000
	v_lshl_add_u64 v[172:173], v[172:173], 0, s[98:99]
	global_load_dwordx4 v[196:199], v[172:173], off
	v_lshl_add_u64 v[126:127], v[158:159], 0, s[24:25]
	global_store_dwordx4 v[162:163], v[112:115], off offset:256
	s_nop 0
	v_lshlrev_b32_e32 v145, 16, v120
	v_lshlrev_b32_e32 v112, 16, v116
	v_and_b32_e32 v113, 0xffff0000, v116
	v_lshlrev_b32_e32 v114, 16, v117
	v_and_b32_e32 v115, 0xffff0000, v117
	v_lshlrev_b32_e32 v116, 16, v118
	v_and_b32_e32 v117, 0xffff0000, v118
	v_lshlrev_b32_e32 v118, 16, v119
	v_and_b32_e32 v119, 0xffff0000, v119
	v_and_b32_e32 v120, 0xffff0000, v120
	v_lshlrev_b32_e32 v152, 16, v121
	v_and_b32_e32 v121, 0xffff0000, v121
	v_lshlrev_b32_e32 v153, 16, v122
	v_and_b32_e32 v122, 0xffff0000, v122
	v_lshlrev_b32_e32 v154, 16, v123
	v_and_b32_e32 v123, 0xffff0000, v123
	v_fmac_f32_e32 v145, v108, v112
	v_fmac_f32_e32 v120, v109, v113
	v_fmac_f32_e32 v152, v110, v114
	v_fmac_f32_e32 v121, v111, v115
	v_fmac_f32_e32 v153, v104, v116
	v_fmac_f32_e32 v122, v105, v117
	v_fmac_f32_e32 v154, v106, v118
	v_fmac_f32_e32 v123, v107, v119
	v_cvt_pk_bf16_f32 v104, v145, v120
	v_cvt_pk_bf16_f32 v105, v152, v121
	v_cvt_pk_bf16_f32 v106, v153, v122
	v_cvt_pk_bf16_f32 v107, v154, v123
	s_waitcnt vmcnt(20)
	s_nop 1
	v_mov_b32_e32 v108, v200
	v_mov_b32_e32 v109, v201
	v_mov_b32_e32 v110, v202
	v_mov_b32_e32 v111, v203
	s_mov_b64 s[98:99], 0x10000
	v_lshl_add_u64 v[174:175], v[174:175], 0, s[98:99]
	global_load_dwordx4 v[200:203], v[174:175], off
	s_waitcnt vmcnt(20)
	s_nop 1
	v_mov_b32_e32 v112, v204
	v_mov_b32_e32 v113, v205
	v_mov_b32_e32 v114, v206
	v_mov_b32_e32 v115, v207
	global_load_dwordx4 v[204:207], v[172:173], off offset:256
	v_add_u32_e32 v116, 32, v144
	v_ashrrev_i32_e32 v117, 31, v116
	v_lshlrev_b64 v[118:119], 13, v[116:117]
	v_lshl_add_u64 v[118:119], s[16:17], 0, v[118:119]
	global_store_dwordx4 v[124:125], v[104:107], off
	v_lshl_add_u64 v[118:119], v[118:119], 0, v[142:143]
	v_add_co_u32_e32 v120, vcc, s61, v118
	s_nop 0
	v_lshlrev_b32_e32 v104, 16, v108
	v_and_b32_e32 v105, 0xffff0000, v108
	v_lshlrev_b32_e32 v122, 16, v112
	v_and_b32_e32 v112, 0xffff0000, v112
	v_fmac_f32_e32 v122, v100, v104
	v_fmac_f32_e32 v112, v101, v105
	v_lshlrev_b64 v[104:105], 12, v[116:117]
	v_lshlrev_b32_e32 v106, 16, v109
	v_and_b32_e32 v107, 0xffff0000, v109
	v_lshlrev_b32_e32 v108, 16, v110
	v_and_b32_e32 v109, 0xffff0000, v110
	v_lshlrev_b32_e32 v126, 16, v114
	v_and_b32_e32 v114, 0xffff0000, v114
	v_lshl_add_u64 v[104:105], s[14:15], 0, v[104:105]
	v_addc_co_u32_e32 v121, vcc, 0, v119, vcc
	v_lshlrev_b32_e32 v110, 16, v111
	v_and_b32_e32 v111, 0xffff0000, v111
	v_lshlrev_b32_e32 v123, 16, v113
	v_and_b32_e32 v113, 0xffff0000, v113
	v_lshlrev_b32_e32 v127, 16, v115
	v_and_b32_e32 v115, 0xffff0000, v115
	v_fmac_f32_e32 v126, v96, v108
	v_fmac_f32_e32 v114, v97, v109
	v_lshl_add_u64 v[108:109], v[104:105], 0, v[142:143]
	v_fmac_f32_e32 v123, v102, v106
	v_fmac_f32_e32 v113, v103, v107
	v_fmac_f32_e32 v127, v98, v110
	v_fmac_f32_e32 v115, v99, v111
	v_cvt_pk_bf16_f32 v96, v122, v112
	v_cvt_pk_bf16_f32 v97, v123, v113
	v_cvt_pk_bf16_f32 v98, v126, v114
	v_cvt_pk_bf16_f32 v99, v127, v115
	s_waitcnt vmcnt(21)
	s_nop 1
	v_mov_b32_e32 v100, v208
	v_mov_b32_e32 v101, v209
	v_mov_b32_e32 v102, v210
	v_mov_b32_e32 v103, v211
	global_load_dwordx4 v[208:211], v[174:175], off offset:256
	s_waitcnt vmcnt(21)
	s_nop 1
	v_mov_b32_e32 v104, v212
	v_mov_b32_e32 v105, v213
	v_mov_b32_e32 v106, v214
	v_mov_b32_e32 v107, v215
	s_mov_b64 s[98:99], 0x20000
	v_lshl_add_u64 v[172:173], v[172:173], 0, s[98:99]
	global_load_dwordx4 v[212:215], v[172:173], off
	v_lshl_add_u64 v[110:111], v[118:119], 0, s[24:25]
	global_store_dwordx4 v[124:125], v[96:99], off offset:256
	s_nop 0
	v_lshlrev_b32_e32 v112, 16, v104
	v_lshlrev_b32_e32 v96, 16, v100
	v_and_b32_e32 v97, 0xffff0000, v100
	v_lshlrev_b32_e32 v98, 16, v101
	v_and_b32_e32 v99, 0xffff0000, v101
	v_lshlrev_b32_e32 v100, 16, v102
	v_and_b32_e32 v101, 0xffff0000, v102
	v_lshlrev_b32_e32 v102, 16, v103
	v_and_b32_e32 v103, 0xffff0000, v103
	v_and_b32_e32 v104, 0xffff0000, v104
	v_lshlrev_b32_e32 v113, 16, v105
	v_and_b32_e32 v105, 0xffff0000, v105
	v_lshlrev_b32_e32 v114, 16, v106
	v_and_b32_e32 v106, 0xffff0000, v106
	v_lshlrev_b32_e32 v115, 16, v107
	v_and_b32_e32 v107, 0xffff0000, v107
	v_fmac_f32_e32 v112, v92, v96
	v_fmac_f32_e32 v104, v93, v97
	v_fmac_f32_e32 v113, v94, v98
	v_fmac_f32_e32 v105, v95, v99
	v_fmac_f32_e32 v114, v88, v100
	v_fmac_f32_e32 v106, v89, v101
	v_fmac_f32_e32 v115, v90, v102
	v_fmac_f32_e32 v107, v91, v103
	v_cvt_pk_bf16_f32 v88, v112, v104
	v_cvt_pk_bf16_f32 v89, v113, v105
	v_cvt_pk_bf16_f32 v90, v114, v106
	v_cvt_pk_bf16_f32 v91, v115, v107
	s_waitcnt vmcnt(22)
	s_nop 1
	v_mov_b32_e32 v92, v216
	v_mov_b32_e32 v93, v217
	v_mov_b32_e32 v94, v218
	v_mov_b32_e32 v95, v219
	s_mov_b64 s[98:99], 0x10000
	v_lshl_add_u64 v[174:175], v[174:175], 0, s[98:99]
	global_load_dwordx4 v[216:219], v[174:175], off
	s_waitcnt vmcnt(22)
	s_nop 1
	v_mov_b32_e32 v96, v220
	v_mov_b32_e32 v97, v221
	v_mov_b32_e32 v98, v222
	v_mov_b32_e32 v99, v223
	global_load_dwordx4 v[220:223], v[172:173], off offset:256
	v_add_u32_e32 v100, 48, v144
	v_ashrrev_i32_e32 v101, 31, v100
	v_lshlrev_b64 v[102:103], 13, v[100:101]
	v_lshl_add_u64 v[102:103], s[16:17], 0, v[102:103]
	global_store_dwordx4 v[108:109], v[88:91], off
	v_lshl_add_u64 v[102:103], v[102:103], 0, v[142:143]
	v_add_co_u32_e32 v104, vcc, s61, v102
	s_nop 0
	v_lshlrev_b32_e32 v88, 16, v92
	v_and_b32_e32 v89, 0xffff0000, v92
	v_lshlrev_b32_e32 v106, 16, v96
	v_and_b32_e32 v96, 0xffff0000, v96
	v_fmac_f32_e32 v106, v84, v88
	v_fmac_f32_e32 v96, v85, v89
	v_lshlrev_b64 v[88:89], 12, v[100:101]
	v_lshlrev_b32_e32 v90, 16, v93
	v_and_b32_e32 v91, 0xffff0000, v93
	v_lshlrev_b32_e32 v92, 16, v94
	v_and_b32_e32 v93, 0xffff0000, v94
	v_lshlrev_b32_e32 v110, 16, v98
	v_and_b32_e32 v98, 0xffff0000, v98
	v_lshl_add_u64 v[88:89], s[14:15], 0, v[88:89]
	v_addc_co_u32_e32 v105, vcc, 0, v103, vcc
	v_lshlrev_b32_e32 v94, 16, v95
	v_and_b32_e32 v95, 0xffff0000, v95
	v_lshlrev_b32_e32 v107, 16, v97
	v_and_b32_e32 v97, 0xffff0000, v97
	v_lshlrev_b32_e32 v111, 16, v99
	v_and_b32_e32 v99, 0xffff0000, v99
	v_fmac_f32_e32 v110, v80, v92
	v_fmac_f32_e32 v98, v81, v93
	v_lshl_add_u64 v[92:93], v[88:89], 0, v[142:143]
	v_fmac_f32_e32 v107, v86, v90
	v_fmac_f32_e32 v97, v87, v91
	v_fmac_f32_e32 v111, v82, v94
	v_fmac_f32_e32 v99, v83, v95
	v_cvt_pk_bf16_f32 v80, v106, v96
	v_cvt_pk_bf16_f32 v81, v107, v97
	v_cvt_pk_bf16_f32 v82, v110, v98
	v_cvt_pk_bf16_f32 v83, v111, v99
	s_waitcnt vmcnt(23)
	s_nop 1
	v_mov_b32_e32 v84, v224
	v_mov_b32_e32 v85, v225
	v_mov_b32_e32 v86, v226
	v_mov_b32_e32 v87, v227
	global_load_dwordx4 v[224:227], v[174:175], off offset:256
	s_waitcnt vmcnt(23)
	s_nop 1
	v_mov_b32_e32 v88, v232
	v_mov_b32_e32 v89, v233
	v_mov_b32_e32 v90, v234
	v_mov_b32_e32 v91, v235
	v_lshl_add_u64 v[94:95], v[102:103], 0, s[24:25]
	global_store_dwordx4 v[108:109], v[80:83], off offset:256
	s_nop 0
	v_lshlrev_b32_e32 v96, 16, v88
	v_lshlrev_b32_e32 v80, 16, v84
	v_and_b32_e32 v81, 0xffff0000, v84
	v_lshlrev_b32_e32 v82, 16, v85
	v_and_b32_e32 v83, 0xffff0000, v85
	v_lshlrev_b32_e32 v84, 16, v86
	v_and_b32_e32 v85, 0xffff0000, v86
	v_lshlrev_b32_e32 v86, 16, v87
	v_and_b32_e32 v87, 0xffff0000, v87
	v_and_b32_e32 v88, 0xffff0000, v88
	v_lshlrev_b32_e32 v97, 16, v89
	v_and_b32_e32 v89, 0xffff0000, v89
	v_lshlrev_b32_e32 v98, 16, v90
	v_and_b32_e32 v90, 0xffff0000, v90
	v_lshlrev_b32_e32 v99, 16, v91
	v_and_b32_e32 v91, 0xffff0000, v91
	v_fmac_f32_e32 v96, v76, v80
	v_fmac_f32_e32 v88, v77, v81
	v_fmac_f32_e32 v97, v78, v82
	v_fmac_f32_e32 v89, v79, v83
	v_fmac_f32_e32 v98, v72, v84
	v_fmac_f32_e32 v90, v73, v85
	v_fmac_f32_e32 v99, v74, v86
	v_fmac_f32_e32 v91, v75, v87
	v_cvt_pk_bf16_f32 v72, v96, v88
	v_cvt_pk_bf16_f32 v73, v97, v89
	v_cvt_pk_bf16_f32 v74, v98, v90
	v_cvt_pk_bf16_f32 v75, v99, v91
	s_waitcnt vmcnt(23)
	s_nop 1
	v_mov_b32_e32 v76, v236
	v_mov_b32_e32 v77, v237
	v_mov_b32_e32 v78, v238
	v_mov_b32_e32 v79, v239
	s_waitcnt vmcnt(22)
	s_nop 1
	v_mov_b32_e32 v80, v240
	v_mov_b32_e32 v81, v241
	v_mov_b32_e32 v82, v242
	v_mov_b32_e32 v83, v243
	v_add_u32_e32 v84, 0x80, v144
	v_ashrrev_i32_e32 v85, 31, v84
	v_lshlrev_b64 v[86:87], 13, v[84:85]
	v_lshl_add_u64 v[86:87], s[16:17], 0, v[86:87]
	global_store_dwordx4 v[92:93], v[72:75], off
	v_lshl_add_u64 v[86:87], v[86:87], 0, v[142:143]
	v_add_co_u32_e32 v88, vcc, s61, v86
	s_nop 0
	v_lshlrev_b32_e32 v72, 16, v76
	v_and_b32_e32 v73, 0xffff0000, v76
	v_lshlrev_b32_e32 v90, 16, v80
	v_and_b32_e32 v80, 0xffff0000, v80
	v_fmac_f32_e32 v90, v68, v72
	v_fmac_f32_e32 v80, v69, v73
	v_lshlrev_b64 v[72:73], 12, v[84:85]
	v_lshlrev_b32_e32 v74, 16, v77
	v_and_b32_e32 v75, 0xffff0000, v77
	v_lshlrev_b32_e32 v76, 16, v78
	v_and_b32_e32 v77, 0xffff0000, v78
	v_lshlrev_b32_e32 v94, 16, v82
	v_and_b32_e32 v82, 0xffff0000, v82
	v_lshl_add_u64 v[72:73], s[14:15], 0, v[72:73]
	v_addc_co_u32_e32 v89, vcc, 0, v87, vcc
	v_lshlrev_b32_e32 v78, 16, v79
	v_and_b32_e32 v79, 0xffff0000, v79
	v_lshlrev_b32_e32 v91, 16, v81
	v_and_b32_e32 v81, 0xffff0000, v81
	v_lshlrev_b32_e32 v95, 16, v83
	v_and_b32_e32 v83, 0xffff0000, v83
	v_fmac_f32_e32 v94, v64, v76
	v_fmac_f32_e32 v82, v65, v77
	v_lshl_add_u64 v[76:77], v[72:73], 0, v[142:143]
	v_fmac_f32_e32 v91, v70, v74
	v_fmac_f32_e32 v81, v71, v75
	v_fmac_f32_e32 v95, v66, v78
	v_fmac_f32_e32 v83, v67, v79
	v_cvt_pk_bf16_f32 v64, v90, v80
	v_cvt_pk_bf16_f32 v65, v91, v81
	v_cvt_pk_bf16_f32 v66, v94, v82
	v_cvt_pk_bf16_f32 v67, v95, v83
	s_waitcnt vmcnt(22)
	s_nop 1
	v_mov_b32_e32 v68, v244
	v_mov_b32_e32 v69, v245
	v_mov_b32_e32 v70, v246
	v_mov_b32_e32 v71, v247
	s_waitcnt vmcnt(21)
	s_nop 1
	v_mov_b32_e32 v72, v248
	v_mov_b32_e32 v73, v249
	v_mov_b32_e32 v74, v250
	v_mov_b32_e32 v75, v251
	v_lshl_add_u64 v[78:79], v[86:87], 0, s[24:25]
	global_store_dwordx4 v[92:93], v[64:67], off offset:256
	s_nop 0
	v_lshlrev_b32_e32 v80, 16, v72
	v_lshlrev_b32_e32 v64, 16, v68
	v_and_b32_e32 v65, 0xffff0000, v68
	v_lshlrev_b32_e32 v66, 16, v69
	v_and_b32_e32 v67, 0xffff0000, v69
	v_lshlrev_b32_e32 v68, 16, v70
	v_and_b32_e32 v69, 0xffff0000, v70
	v_lshlrev_b32_e32 v70, 16, v71
	v_and_b32_e32 v71, 0xffff0000, v71
	v_and_b32_e32 v72, 0xffff0000, v72
	v_lshlrev_b32_e32 v81, 16, v73
	v_and_b32_e32 v73, 0xffff0000, v73
	v_lshlrev_b32_e32 v82, 16, v74
	v_and_b32_e32 v74, 0xffff0000, v74
	v_lshlrev_b32_e32 v83, 16, v75
	v_and_b32_e32 v75, 0xffff0000, v75
	v_fmac_f32_e32 v80, v60, v64
	v_fmac_f32_e32 v72, v61, v65
	v_fmac_f32_e32 v81, v62, v66
	v_fmac_f32_e32 v73, v63, v67
	v_fmac_f32_e32 v82, v56, v68
	v_fmac_f32_e32 v74, v57, v69
	v_fmac_f32_e32 v83, v58, v70
	v_fmac_f32_e32 v75, v59, v71
	v_cvt_pk_bf16_f32 v56, v80, v72
	v_cvt_pk_bf16_f32 v57, v81, v73
	v_cvt_pk_bf16_f32 v58, v82, v74
	v_cvt_pk_bf16_f32 v59, v83, v75
	s_waitcnt vmcnt(21)
	s_nop 1
	v_mov_b32_e32 v60, v252
	v_mov_b32_e32 v61, v253
	v_mov_b32_e32 v62, v254
	v_mov_b32_e32 v63, v255
	s_waitcnt vmcnt(20)
	s_nop 1
	v_mov_b32_e32 v64, v176
	v_mov_b32_e32 v65, v177
	v_mov_b32_e32 v66, v178
	v_mov_b32_e32 v67, v179
	v_add_u32_e32 v68, 0x90, v144
	v_ashrrev_i32_e32 v69, 31, v68
	v_lshlrev_b64 v[70:71], 13, v[68:69]
	v_lshl_add_u64 v[70:71], s[16:17], 0, v[70:71]
	global_store_dwordx4 v[76:77], v[56:59], off
	v_lshl_add_u64 v[70:71], v[70:71], 0, v[142:143]
	v_add_co_u32_e32 v72, vcc, s61, v70
	s_nop 0
	v_lshlrev_b32_e32 v56, 16, v60
	v_and_b32_e32 v57, 0xffff0000, v60
	v_lshlrev_b32_e32 v74, 16, v64
	v_and_b32_e32 v64, 0xffff0000, v64
	v_fmac_f32_e32 v74, v52, v56
	v_fmac_f32_e32 v64, v53, v57
	v_lshlrev_b64 v[56:57], 12, v[68:69]
	v_lshlrev_b32_e32 v58, 16, v61
	v_and_b32_e32 v59, 0xffff0000, v61
	v_lshlrev_b32_e32 v60, 16, v62
	v_and_b32_e32 v61, 0xffff0000, v62
	v_lshlrev_b32_e32 v78, 16, v66
	v_and_b32_e32 v66, 0xffff0000, v66
	v_lshl_add_u64 v[56:57], s[14:15], 0, v[56:57]
	v_addc_co_u32_e32 v73, vcc, 0, v71, vcc
	v_lshlrev_b32_e32 v62, 16, v63
	v_and_b32_e32 v63, 0xffff0000, v63
	v_lshlrev_b32_e32 v75, 16, v65
	v_and_b32_e32 v65, 0xffff0000, v65
	v_lshlrev_b32_e32 v79, 16, v67
	v_and_b32_e32 v67, 0xffff0000, v67
	v_fmac_f32_e32 v78, v48, v60
	v_fmac_f32_e32 v66, v49, v61
	v_lshl_add_u64 v[60:61], v[56:57], 0, v[142:143]
	v_fmac_f32_e32 v75, v54, v58
	v_fmac_f32_e32 v65, v55, v59
	v_fmac_f32_e32 v79, v50, v62
	v_fmac_f32_e32 v67, v51, v63
	v_cvt_pk_bf16_f32 v48, v74, v64
	v_cvt_pk_bf16_f32 v49, v75, v65
	v_cvt_pk_bf16_f32 v50, v78, v66
	v_cvt_pk_bf16_f32 v51, v79, v67
	s_waitcnt vmcnt(20)
	s_nop 1
	v_mov_b32_e32 v52, v180
	v_mov_b32_e32 v53, v181
	v_mov_b32_e32 v54, v182
	v_mov_b32_e32 v55, v183
	s_waitcnt vmcnt(19)
	s_nop 1
	v_mov_b32_e32 v56, v184
	v_mov_b32_e32 v57, v185
	v_mov_b32_e32 v58, v186
	v_mov_b32_e32 v59, v187
	v_lshl_add_u64 v[62:63], v[70:71], 0, s[24:25]
	global_store_dwordx4 v[76:77], v[48:51], off offset:256
	s_nop 0
	v_lshlrev_b32_e32 v64, 16, v56
	v_lshlrev_b32_e32 v48, 16, v52
	v_and_b32_e32 v49, 0xffff0000, v52
	v_lshlrev_b32_e32 v50, 16, v53
	v_and_b32_e32 v51, 0xffff0000, v53
	v_lshlrev_b32_e32 v52, 16, v54
	v_and_b32_e32 v53, 0xffff0000, v54
	v_lshlrev_b32_e32 v54, 16, v55
	v_and_b32_e32 v55, 0xffff0000, v55
	v_and_b32_e32 v56, 0xffff0000, v56
	v_lshlrev_b32_e32 v65, 16, v57
	v_and_b32_e32 v57, 0xffff0000, v57
	v_lshlrev_b32_e32 v66, 16, v58
	v_and_b32_e32 v58, 0xffff0000, v58
	v_lshlrev_b32_e32 v67, 16, v59
	v_and_b32_e32 v59, 0xffff0000, v59
	v_fmac_f32_e32 v64, v44, v48
	v_fmac_f32_e32 v56, v45, v49
	v_fmac_f32_e32 v65, v46, v50
	v_fmac_f32_e32 v57, v47, v51
	v_fmac_f32_e32 v66, v40, v52
	v_fmac_f32_e32 v58, v41, v53
	v_fmac_f32_e32 v67, v42, v54
	v_fmac_f32_e32 v59, v43, v55
	v_cvt_pk_bf16_f32 v40, v64, v56
	v_cvt_pk_bf16_f32 v41, v65, v57
	v_cvt_pk_bf16_f32 v42, v66, v58
	v_cvt_pk_bf16_f32 v43, v67, v59
	s_waitcnt vmcnt(19)
	s_nop 1
	v_mov_b32_e32 v44, v188
	v_mov_b32_e32 v45, v189
	v_mov_b32_e32 v46, v190
	v_mov_b32_e32 v47, v191
	s_waitcnt vmcnt(17)
	s_nop 1
	v_mov_b32_e32 v48, v192
	v_mov_b32_e32 v49, v193
	v_mov_b32_e32 v50, v194
	v_mov_b32_e32 v51, v195
	v_add_u32_e32 v52, 0xa0, v144
	v_ashrrev_i32_e32 v53, 31, v52
	v_lshlrev_b64 v[54:55], 13, v[52:53]
	v_lshl_add_u64 v[54:55], s[16:17], 0, v[54:55]
	global_store_dwordx4 v[60:61], v[40:43], off
	v_lshl_add_u64 v[54:55], v[54:55], 0, v[142:143]
	v_add_co_u32_e32 v56, vcc, s61, v54
	s_nop 0
	v_lshlrev_b32_e32 v40, 16, v44
	v_and_b32_e32 v41, 0xffff0000, v44
	v_lshlrev_b32_e32 v58, 16, v48
	v_and_b32_e32 v48, 0xffff0000, v48
	v_fmac_f32_e32 v58, v36, v40
	v_fmac_f32_e32 v48, v37, v41
	v_lshlrev_b64 v[40:41], 12, v[52:53]
	v_lshlrev_b32_e32 v42, 16, v45
	v_and_b32_e32 v43, 0xffff0000, v45
	v_lshlrev_b32_e32 v44, 16, v46
	v_and_b32_e32 v45, 0xffff0000, v46
	v_lshlrev_b32_e32 v62, 16, v50
	v_and_b32_e32 v50, 0xffff0000, v50
	v_lshl_add_u64 v[40:41], s[14:15], 0, v[40:41]
	v_addc_co_u32_e32 v57, vcc, 0, v55, vcc
	v_lshlrev_b32_e32 v46, 16, v47
	v_and_b32_e32 v47, 0xffff0000, v47
	v_lshlrev_b32_e32 v59, 16, v49
	v_and_b32_e32 v49, 0xffff0000, v49
	v_lshlrev_b32_e32 v63, 16, v51
	v_and_b32_e32 v51, 0xffff0000, v51
	v_fmac_f32_e32 v62, v32, v44
	v_fmac_f32_e32 v50, v33, v45
	v_lshl_add_u64 v[44:45], v[40:41], 0, v[142:143]
	v_fmac_f32_e32 v59, v38, v42
	v_fmac_f32_e32 v49, v39, v43
	v_fmac_f32_e32 v63, v34, v46
	v_fmac_f32_e32 v51, v35, v47
	v_cvt_pk_bf16_f32 v32, v58, v48
	v_cvt_pk_bf16_f32 v33, v59, v49
	v_cvt_pk_bf16_f32 v34, v62, v50
	v_cvt_pk_bf16_f32 v35, v63, v51
	s_waitcnt vmcnt(17)
	s_nop 1
	v_mov_b32_e32 v36, v196
	v_mov_b32_e32 v37, v197
	v_mov_b32_e32 v38, v198
	v_mov_b32_e32 v39, v199
	s_waitcnt vmcnt(15)
	s_nop 1
	v_mov_b32_e32 v40, v200
	v_mov_b32_e32 v41, v201
	v_mov_b32_e32 v42, v202
	v_mov_b32_e32 v43, v203
	v_lshl_add_u64 v[46:47], v[54:55], 0, s[24:25]
	global_store_dwordx4 v[60:61], v[32:35], off offset:256
	s_nop 0
	v_lshlrev_b32_e32 v48, 16, v40
	v_lshlrev_b32_e32 v32, 16, v36
	v_and_b32_e32 v33, 0xffff0000, v36
	v_lshlrev_b32_e32 v34, 16, v37
	v_and_b32_e32 v35, 0xffff0000, v37
	v_lshlrev_b32_e32 v36, 16, v38
	v_and_b32_e32 v37, 0xffff0000, v38
	v_lshlrev_b32_e32 v38, 16, v39
	v_and_b32_e32 v39, 0xffff0000, v39
	v_and_b32_e32 v40, 0xffff0000, v40
	v_lshlrev_b32_e32 v49, 16, v41
	v_and_b32_e32 v41, 0xffff0000, v41
	v_lshlrev_b32_e32 v50, 16, v42
	v_and_b32_e32 v42, 0xffff0000, v42
	v_lshlrev_b32_e32 v51, 16, v43
	v_and_b32_e32 v43, 0xffff0000, v43
	v_fmac_f32_e32 v48, v28, v32
	v_fmac_f32_e32 v40, v29, v33
	v_fmac_f32_e32 v49, v30, v34
	v_fmac_f32_e32 v41, v31, v35
	v_fmac_f32_e32 v50, v24, v36
	v_fmac_f32_e32 v42, v25, v37
	v_fmac_f32_e32 v51, v26, v38
	v_fmac_f32_e32 v43, v27, v39
	v_cvt_pk_bf16_f32 v24, v48, v40
	v_cvt_pk_bf16_f32 v25, v49, v41
	v_cvt_pk_bf16_f32 v26, v50, v42
	v_cvt_pk_bf16_f32 v27, v51, v43
	s_waitcnt vmcnt(15)
	s_nop 1
	v_mov_b32_e32 v28, v204
	v_mov_b32_e32 v29, v205
	v_mov_b32_e32 v30, v206
	v_mov_b32_e32 v31, v207
	s_waitcnt vmcnt(13)
	s_nop 1
	v_mov_b32_e32 v32, v208
	v_mov_b32_e32 v33, v209
	v_mov_b32_e32 v34, v210
	v_mov_b32_e32 v35, v211
	v_add_u32_e32 v36, 0xb0, v144
	v_ashrrev_i32_e32 v37, 31, v36
	v_lshlrev_b64 v[38:39], 13, v[36:37]
	v_lshl_add_u64 v[38:39], s[16:17], 0, v[38:39]
	global_store_dwordx4 v[44:45], v[24:27], off
	v_lshl_add_u64 v[38:39], v[38:39], 0, v[142:143]
	v_add_co_u32_e32 v40, vcc, s61, v38
	s_nop 0
	v_lshlrev_b32_e32 v24, 16, v28
	v_and_b32_e32 v25, 0xffff0000, v28
	v_lshlrev_b32_e32 v42, 16, v32
	v_and_b32_e32 v32, 0xffff0000, v32
	v_fmac_f32_e32 v42, v20, v24
	v_fmac_f32_e32 v32, v21, v25
	v_lshlrev_b64 v[24:25], 12, v[36:37]
	v_lshlrev_b32_e32 v26, 16, v29
	v_and_b32_e32 v27, 0xffff0000, v29
	v_lshlrev_b32_e32 v28, 16, v30
	v_and_b32_e32 v29, 0xffff0000, v30
	v_lshlrev_b32_e32 v46, 16, v34
	v_and_b32_e32 v34, 0xffff0000, v34
	v_lshl_add_u64 v[24:25], s[14:15], 0, v[24:25]
	v_addc_co_u32_e32 v41, vcc, 0, v39, vcc
	v_lshlrev_b32_e32 v30, 16, v31
	v_and_b32_e32 v31, 0xffff0000, v31
	v_lshlrev_b32_e32 v43, 16, v33
	v_and_b32_e32 v33, 0xffff0000, v33
	v_lshlrev_b32_e32 v47, 16, v35
	v_and_b32_e32 v35, 0xffff0000, v35
	v_fmac_f32_e32 v46, v16, v28
	v_fmac_f32_e32 v34, v17, v29
	v_lshl_add_u64 v[28:29], v[24:25], 0, v[142:143]
	v_fmac_f32_e32 v43, v22, v26
	v_fmac_f32_e32 v33, v23, v27
	v_fmac_f32_e32 v47, v18, v30
	v_fmac_f32_e32 v35, v19, v31
	v_cvt_pk_bf16_f32 v16, v42, v32
	v_cvt_pk_bf16_f32 v17, v43, v33
	v_cvt_pk_bf16_f32 v18, v46, v34
	v_cvt_pk_bf16_f32 v19, v47, v35
	s_waitcnt vmcnt(13)
	s_nop 1
	v_mov_b32_e32 v20, v212
	v_mov_b32_e32 v21, v213
	v_mov_b32_e32 v22, v214
	v_mov_b32_e32 v23, v215
	s_waitcnt vmcnt(11)
	s_nop 1
	v_mov_b32_e32 v24, v216
	v_mov_b32_e32 v25, v217
	v_mov_b32_e32 v26, v218
	v_mov_b32_e32 v27, v219
	v_lshl_add_u64 v[30:31], v[38:39], 0, s[24:25]
	global_store_dwordx4 v[44:45], v[16:19], off offset:256
	s_and_b64 vcc, exec, s[2:3]
	s_mov_b64 s[2:3], -1
	s_nop 0
	v_lshlrev_b32_e32 v16, 16, v20
	v_and_b32_e32 v17, 0xffff0000, v20
	v_lshlrev_b32_e32 v18, 16, v21
	v_and_b32_e32 v19, 0xffff0000, v21
	v_lshlrev_b32_e32 v20, 16, v22
	v_and_b32_e32 v21, 0xffff0000, v22
	v_lshlrev_b32_e32 v22, 16, v23
	v_and_b32_e32 v23, 0xffff0000, v23
	v_lshlrev_b32_e32 v32, 16, v24
	v_and_b32_e32 v24, 0xffff0000, v24
	v_lshlrev_b32_e32 v33, 16, v25
	v_and_b32_e32 v25, 0xffff0000, v25
	v_lshlrev_b32_e32 v34, 16, v26
	v_and_b32_e32 v26, 0xffff0000, v26
	v_lshlrev_b32_e32 v35, 16, v27
	v_and_b32_e32 v27, 0xffff0000, v27
	v_fmac_f32_e32 v32, v12, v16
	v_fmac_f32_e32 v24, v13, v17
	v_fmac_f32_e32 v33, v14, v18
	v_fmac_f32_e32 v25, v15, v19
	v_fmac_f32_e32 v34, v8, v20
	v_fmac_f32_e32 v26, v9, v21
	v_fmac_f32_e32 v35, v10, v22
	v_fmac_f32_e32 v27, v11, v23
	v_cvt_pk_bf16_f32 v8, v32, v24
	v_cvt_pk_bf16_f32 v9, v33, v25
	v_cvt_pk_bf16_f32 v10, v34, v26
	v_cvt_pk_bf16_f32 v11, v35, v27
	s_waitcnt vmcnt(11)
	s_nop 1
	v_mov_b32_e32 v12, v220
	v_mov_b32_e32 v13, v221
	v_mov_b32_e32 v14, v222
	v_mov_b32_e32 v15, v223
	s_waitcnt vmcnt(9)
	s_nop 1
	v_mov_b32_e32 v16, v224
	v_mov_b32_e32 v17, v225
	v_mov_b32_e32 v18, v226
	v_mov_b32_e32 v19, v227
	s_nop 0
	v_lshlrev_b32_e32 v20, 16, v16
	global_store_dwordx4 v[28:29], v[8:11], off
	v_and_b32_e32 v16, 0xffff0000, v16
	v_lshlrev_b32_e32 v21, 16, v17
	v_lshlrev_b32_e32 v8, 16, v12
	v_and_b32_e32 v9, 0xffff0000, v12
	v_lshlrev_b32_e32 v10, 16, v13
	v_and_b32_e32 v11, 0xffff0000, v13
	v_lshlrev_b32_e32 v12, 16, v14
	v_and_b32_e32 v13, 0xffff0000, v14
	v_lshlrev_b32_e32 v14, 16, v15
	v_and_b32_e32 v15, 0xffff0000, v15
	v_and_b32_e32 v17, 0xffff0000, v17
	v_lshlrev_b32_e32 v22, 16, v18
	v_and_b32_e32 v18, 0xffff0000, v18
	v_lshlrev_b32_e32 v23, 16, v19
	v_and_b32_e32 v19, 0xffff0000, v19
	v_fmac_f32_e32 v20, v4, v8
	v_fmac_f32_e32 v16, v5, v9
	v_fmac_f32_e32 v21, v6, v10
	v_fmac_f32_e32 v17, v7, v11
	v_fmac_f32_e32 v22, v0, v12
	v_fmac_f32_e32 v18, v1, v13
	v_fmac_f32_e32 v23, v2, v14
	v_fmac_f32_e32 v19, v3, v15
	v_cvt_pk_bf16_f32 v0, v20, v16
	v_cvt_pk_bf16_f32 v1, v21, v17
	v_cvt_pk_bf16_f32 v2, v22, v18
	v_cvt_pk_bf16_f32 v3, v23, v19
	global_store_dwordx4 v[28:29], v[0:3], off offset:256
	s_cbranch_vccnz .LBB0_1249
	s_andn2_b64 vcc, exec, s[12:13]
	s_cbranch_vccnz .LBB0_1248
	s_barrier
	s_branch .LBB0_1248

.LBB0_1342:
	s_lshl_b32 s0, s67, 8
	v_mov_b32_e32 v142, v147
	v_mov_b32_e32 v153, v146
	s_add_i32 s0, s0, s52
	s_lshl_b32 s34, s14, 2
	v_add_u32_e32 v144, s0, v142
	s_lshl_b32 s0, s14, 8
	s_or_b32 s0, s0, s53
	v_lshl_add_u32 v142, v153, 3, s0
	v_ashrrev_i32_e32 v145, 31, v144
	v_ashrrev_i32_e32 v143, 31, v142
	v_lshlrev_b64 v[154:155], 11, v[144:145]
	v_lshl_add_u64 v[162:163], v[154:155], 0, v[142:143]
	s_waitcnt lgkmcnt(0)
	v_lshl_add_u64 v[164:165], v[162:163], 2, s[12:13]
	v_mov_b32_e32 v170, v164
	v_mov_b32_e32 v171, v165
	global_load_dwordx4 v[172:175], v[170:171], off
	global_load_dwordx4 v[176:179], v[170:171], off offset:16
	global_load_dwordx4 v[180:183], v[170:171], off offset:512
	global_load_dwordx4 v[184:187], v[170:171], off offset:528
	s_mov_b64 s[98:99], 0x20000
	v_lshl_add_u64 v[170:171], v[170:171], 0, s[98:99]
	global_load_dwordx4 v[188:191], v[170:171], off
	global_load_dwordx4 v[192:195], v[170:171], off offset:16
	global_load_dwordx4 v[196:199], v[170:171], off offset:512
	global_load_dwordx4 v[200:203], v[170:171], off offset:528
	s_mov_b64 s[98:99], 0x20000
	v_lshl_add_u64 v[170:171], v[170:171], 0, s[98:99]
	global_load_dwordx4 v[204:207], v[170:171], off
	global_load_dwordx4 v[208:211], v[170:171], off offset:16
	global_load_dwordx4 v[212:215], v[170:171], off offset:512
	global_load_dwordx4 v[216:219], v[170:171], off offset:528
	s_mov_b64 s[98:99], 0x20000
	v_lshl_add_u64 v[170:171], v[170:171], 0, s[98:99]
	global_load_dwordx4 v[220:223], v[170:171], off
	global_load_dwordx4 v[224:227], v[170:171], off offset:16
	global_load_dwordx4 v[232:235], v[170:171], off offset:512
	global_load_dwordx4 v[236:239], v[170:171], off offset:528
	s_mov_b64 s[98:99], 0xa0000
	v_lshl_add_u64 v[170:171], v[170:171], 0, s[98:99]
	global_load_dwordx4 v[240:243], v[170:171], off
	global_load_dwordx4 v[244:247], v[170:171], off offset:16
	global_load_dwordx4 v[248:251], v[170:171], off offset:512
	global_load_dwordx4 v[252:255], v[170:171], off offset:528
	s_waitcnt vmcnt(19)
	s_nop 1
	v_mov_b32_e32 v154, v172
	v_mov_b32_e32 v155, v173
	v_mov_b32_e32 v156, v174
	v_mov_b32_e32 v157, v175
	s_mov_b64 s[98:99], 0x20000
	v_lshl_add_u64 v[170:171], v[170:171], 0, s[98:99]
	global_load_dwordx4 v[172:175], v[170:171], off
	s_waitcnt vmcnt(19)
	s_nop 1
	v_mov_b32_e32 v158, v176
	v_mov_b32_e32 v159, v177
	v_mov_b32_e32 v160, v178
	v_mov_b32_e32 v161, v179
	global_load_dwordx4 v[176:179], v[170:171], off offset:16
	v_lshl_add_u64 v[162:163], v[162:163], 1, s[18:19]
	s_ashr_i32 s35, s34, 31
	s_nop 0
	v_pk_add_f32 v[166:167], v[122:123], v[156:157]
	v_pk_add_f32 v[168:169], v[120:121], v[154:155]
	v_pk_add_f32 v[126:127], v[126:127], v[160:161]
	v_pk_add_f32 v[158:159], v[124:125], v[158:159]
	v_cvt_pk_bf16_f32 v120, v168, v169
	v_cvt_pk_bf16_f32 v121, v166, v167
	v_mul_f32_e32 v161, v169, v169
	v_cvt_pk_bf16_f32 v122, v158, v159
	v_cvt_pk_bf16_f32 v123, v126, v127
	global_store_dwordx4 v[162:163], v[120:123], off
	s_waitcnt vmcnt(20)
	s_nop 1
	v_mov_b32_e32 v122, v180
	v_mov_b32_e32 v123, v181
	v_mov_b32_e32 v124, v182
	v_mov_b32_e32 v125, v183
	global_load_dwordx4 v[180:183], v[170:171], off offset:512
	s_nop 0
	s_waitcnt vmcnt(20)
	s_nop 1
	v_mov_b32_e32 v154, v184
	v_mov_b32_e32 v155, v185
	v_mov_b32_e32 v156, v186
	v_mov_b32_e32 v157, v187
	global_load_dwordx4 v[184:187], v[170:171], off offset:528
	v_mul_f32_e32 v164, v167, v167
	v_and_b32_e32 v121, 64, v152
	v_mul_f32_e32 v159, v159, v159
	v_mul_f32_e32 v127, v127, v127
	v_fmac_f32_e32 v161, v168, v168
	v_fmac_f32_e32 v164, v166, v166
	v_xor_b32_e32 v120, 16, v152
	v_add_u32_e32 v121, 64, v121
	v_fmac_f32_e32 v159, v158, v158
	v_fmac_f32_e32 v127, v126, v126
	v_add_f32_e32 v126, v161, v164
	v_cmp_lt_i32_e32 vcc, v120, v121
	v_add_f32_e32 v126, v126, v159
	v_add_f32_e32 v126, v127, v126
	v_cndmask_b32_e32 v120, v152, v120, vcc
	v_lshlrev_b32_e32 v120, 2, v120
	v_xor_b32_e32 v160, 32, v152
	v_cmp_lt_i32_e64 s[4:5], v160, v121
	v_cmp_eq_u32_e32 vcc, 0, v153
	s_nop 0
	v_pk_add_f32 v[118:119], v[118:119], v[124:125]
	v_pk_add_f32 v[116:117], v[116:117], v[122:123]
	s_nop 0
	v_pk_add_f32 v[124:125], v[112:113], v[154:155]
	v_mul_f32_e32 v112, v117, v117
	v_mul_f32_e32 v113, v119, v119
	v_pk_add_f32 v[122:123], v[114:115], v[156:157]
	v_mul_f32_e32 v114, v125, v125
	v_fmac_f32_e32 v112, v116, v116
	v_fmac_f32_e32 v113, v118, v118
	v_mul_f32_e32 v115, v123, v123
	v_fmac_f32_e32 v114, v124, v124
	v_add_f32_e32 v112, v112, v113
	v_fmac_f32_e32 v115, v122, v122
	v_add_f32_e32 v112, v112, v114
	v_add_f32_e32 v112, v115, v112
	v_add_f32_e32 v112, v126, v112
	ds_bpermute_b32 v113, v120, v112
	v_cndmask_b32_e64 v114, v152, v160, s[4:5]
	v_lshlrev_b32_e32 v114, 2, v114
	v_cvt_pk_bf16_f32 v116, v116, v117
	v_cvt_pk_bf16_f32 v117, v118, v119
	s_waitcnt lgkmcnt(0)
	v_add_f32_e32 v112, v112, v113
	ds_bpermute_b32 v113, v114, v112
	v_cvt_pk_bf16_f32 v118, v124, v125
	v_cvt_pk_bf16_f32 v119, v122, v123
	global_store_dwordx4 v[162:163], v[116:119], off offset:256
	s_and_saveexec_b64 s[4:5], vcc
	s_cbranch_execz .LBB0_1344
	v_lshlrev_b64 v[116:117], 7, v[144:145]
	v_lshl_add_u64 v[116:117], s[20:21], 0, v[116:117]
	v_lshl_add_u64 v[116:117], s[34:35], 2, v[116:117]
	s_lshl_b32 s14, s50, 2
	v_lshl_add_u64 v[116:117], v[116:117], 0, s[14:15]
	s_waitcnt lgkmcnt(0)
	v_add_f32_e32 v112, v112, v113
	global_store_dword v[116:117], v112, off
.LBB0_1344:
	s_or_b64 exec, exec, s[4:5]
	v_add_u32_e32 v112, 16, v144
	s_waitcnt lgkmcnt(0)
	v_ashrrev_i32_e32 v113, 31, v112
	v_lshlrev_b64 v[116:117], 11, v[112:113]
	v_lshl_add_u64 v[126:127], v[116:117], 0, v[142:143]
	v_lshl_add_u64 v[154:155], v[126:127], 2, s[12:13]
	s_waitcnt vmcnt(21)
	s_nop 1
	v_mov_b32_e32 v116, v188
	v_mov_b32_e32 v117, v189
	v_mov_b32_e32 v118, v190
	v_mov_b32_e32 v119, v191
	s_mov_b64 s[98:99], 0x20000
	v_lshl_add_u64 v[170:171], v[170:171], 0, s[98:99]
	global_load_dwordx4 v[188:191], v[170:171], off
	s_waitcnt vmcnt(21)
	s_nop 1
	v_mov_b32_e32 v122, v192
	v_mov_b32_e32 v123, v193
	v_mov_b32_e32 v124, v194
	v_mov_b32_e32 v125, v195
	global_load_dwordx4 v[192:195], v[170:171], off offset:16
	v_lshl_add_u64 v[126:127], v[126:127], 1, s[18:19]
	s_nop 0
	v_pk_add_f32 v[118:119], v[110:111], v[118:119]
	v_pk_add_f32 v[116:117], v[108:109], v[116:117]
	s_nop 0
	v_pk_add_f32 v[124:125], v[106:107], v[124:125]
	v_pk_add_f32 v[122:123], v[104:105], v[122:123]
	v_cvt_pk_bf16_f32 v104, v116, v117
	v_cvt_pk_bf16_f32 v105, v118, v119
	v_mul_f32_e32 v115, v117, v117
	v_cvt_pk_bf16_f32 v106, v122, v123
	v_cvt_pk_bf16_f32 v107, v124, v125
	global_store_dwordx4 v[126:127], v[104:107], off
	s_waitcnt vmcnt(22)
	s_nop 1
	v_mov_b32_e32 v104, v196
	v_mov_b32_e32 v105, v197
	v_mov_b32_e32 v106, v198
	v_mov_b32_e32 v107, v199
	global_load_dwordx4 v[196:199], v[170:171], off offset:512
	s_nop 0
	s_waitcnt vmcnt(22)
	s_nop 1
	v_mov_b32_e32 v108, v200
	v_mov_b32_e32 v109, v201
	v_mov_b32_e32 v110, v202
	v_mov_b32_e32 v111, v203
	global_load_dwordx4 v[200:203], v[170:171], off offset:528
	v_mul_f32_e32 v117, v119, v119
	v_mul_f32_e32 v119, v123, v123
	v_fmac_f32_e32 v115, v116, v116
	v_fmac_f32_e32 v117, v118, v118
	v_mul_f32_e32 v121, v125, v125
	v_fmac_f32_e32 v119, v122, v122
	v_add_f32_e32 v115, v115, v117
	v_fmac_f32_e32 v121, v124, v124
	v_add_f32_e32 v115, v115, v119
	v_add_f32_e32 v115, v121, v115
	s_nop 0
	v_pk_add_f32 v[102:103], v[102:103], v[106:107]
	v_pk_add_f32 v[100:101], v[100:101], v[104:105]
	s_nop 0
	v_pk_add_f32 v[106:107], v[96:97], v[108:109]
	v_mul_f32_e32 v96, v101, v101
	v_mul_f32_e32 v97, v103, v103
	v_pk_add_f32 v[104:105], v[98:99], v[110:111]
	v_mul_f32_e32 v98, v107, v107
	v_fmac_f32_e32 v96, v100, v100
	v_fmac_f32_e32 v97, v102, v102
	v_mul_f32_e32 v99, v105, v105
	v_fmac_f32_e32 v98, v106, v106
	v_add_f32_e32 v96, v96, v97
	v_add_f32_e32 v96, v96, v98
	v_fmac_f32_e32 v99, v104, v104
	v_add_f32_e32 v96, v99, v96
	v_add_f32_e32 v96, v115, v96
	ds_bpermute_b32 v97, v120, v96
	v_cvt_pk_bf16_f32 v98, v100, v101
	v_cvt_pk_bf16_f32 v99, v102, v103
	v_cvt_pk_bf16_f32 v100, v106, v107
	v_cvt_pk_bf16_f32 v101, v104, v105
	s_waitcnt lgkmcnt(0)
	v_add_f32_e32 v96, v96, v97
	ds_bpermute_b32 v97, v114, v96
	global_store_dwordx4 v[126:127], v[98:101], off offset:256
	s_and_saveexec_b64 s[4:5], vcc
	s_cbranch_execz .LBB0_1346
	v_lshlrev_b64 v[98:99], 7, v[112:113]
	v_lshl_add_u64 v[98:99], s[20:21], 0, v[98:99]
	v_lshl_add_u64 v[98:99], s[34:35], 2, v[98:99]
	s_lshl_b32 s14, s50, 2
	v_lshl_add_u64 v[98:99], v[98:99], 0, s[14:15]
	s_waitcnt lgkmcnt(0)
	v_add_f32_e32 v96, v96, v97
	global_store_dword v[98:99], v96, off
.LBB0_1346:
	s_or_b64 exec, exec, s[4:5]
	v_add_u32_e32 v96, 32, v144
	s_waitcnt lgkmcnt(0)
	v_ashrrev_i32_e32 v97, 31, v96
	v_lshlrev_b64 v[98:99], 11, v[96:97]
	v_lshl_add_u64 v[106:107], v[98:99], 0, v[142:143]
	v_lshl_add_u64 v[108:109], v[106:107], 2, s[12:13]
	s_waitcnt vmcnt(23)
	s_nop 1
	v_mov_b32_e32 v98, v204
	v_mov_b32_e32 v99, v205
	v_mov_b32_e32 v100, v206
	v_mov_b32_e32 v101, v207
	s_mov_b64 s[98:99], 0x20000
	v_lshl_add_u64 v[170:171], v[170:171], 0, s[98:99]
	global_load_dwordx4 v[204:207], v[170:171], off
	s_waitcnt vmcnt(23)
	s_nop 1
	v_mov_b32_e32 v102, v208
	v_mov_b32_e32 v103, v209
	v_mov_b32_e32 v104, v210
	v_mov_b32_e32 v105, v211
	global_load_dwordx4 v[208:211], v[170:171], off offset:16
	v_lshl_add_u64 v[106:107], v[106:107], 1, s[18:19]
	s_nop 0
	v_pk_add_f32 v[100:101], v[94:95], v[100:101]
	v_pk_add_f32 v[98:99], v[92:93], v[98:99]
	s_nop 0
	v_pk_add_f32 v[104:105], v[90:91], v[104:105]
	v_pk_add_f32 v[102:103], v[88:89], v[102:103]
	v_cvt_pk_bf16_f32 v88, v98, v99
	v_cvt_pk_bf16_f32 v89, v100, v101
	v_mul_f32_e32 v99, v99, v99
	v_cvt_pk_bf16_f32 v90, v102, v103
	v_cvt_pk_bf16_f32 v91, v104, v105
	global_store_dwordx4 v[106:107], v[88:91], off
	s_waitcnt vmcnt(24)
	s_nop 1
	v_mov_b32_e32 v88, v212
	v_mov_b32_e32 v89, v213
	v_mov_b32_e32 v90, v214
	v_mov_b32_e32 v91, v215
	global_load_dwordx4 v[212:215], v[170:171], off offset:512
	s_nop 0
	s_waitcnt vmcnt(24)
	s_nop 1
	v_mov_b32_e32 v92, v216
	v_mov_b32_e32 v93, v217
	v_mov_b32_e32 v94, v218
	v_mov_b32_e32 v95, v219
	global_load_dwordx4 v[216:219], v[170:171], off offset:528
	v_mul_f32_e32 v101, v101, v101
	v_mul_f32_e32 v103, v103, v103
	v_fmac_f32_e32 v99, v98, v98
	v_fmac_f32_e32 v101, v100, v100
	v_mul_f32_e32 v105, v105, v105
	v_fmac_f32_e32 v103, v102, v102
	v_add_f32_e32 v98, v99, v101
	v_fmac_f32_e32 v105, v104, v104
	v_add_f32_e32 v98, v98, v103
	v_add_f32_e32 v98, v105, v98
	s_nop 0
	v_pk_add_f32 v[86:87], v[86:87], v[90:91]
	v_pk_add_f32 v[84:85], v[84:85], v[88:89]
	s_nop 0
	v_pk_add_f32 v[90:91], v[80:81], v[92:93]
	v_mul_f32_e32 v80, v85, v85
	v_mul_f32_e32 v81, v87, v87
	v_pk_add_f32 v[88:89], v[82:83], v[94:95]
	v_mul_f32_e32 v82, v91, v91
	v_fmac_f32_e32 v80, v84, v84
	v_fmac_f32_e32 v81, v86, v86
	v_mul_f32_e32 v83, v89, v89
	v_fmac_f32_e32 v82, v90, v90
	v_add_f32_e32 v80, v80, v81
	v_add_f32_e32 v80, v80, v82
	v_fmac_f32_e32 v83, v88, v88
	v_add_f32_e32 v80, v83, v80
	v_add_f32_e32 v80, v98, v80
	ds_bpermute_b32 v81, v120, v80
	v_cvt_pk_bf16_f32 v82, v84, v85
	v_cvt_pk_bf16_f32 v83, v86, v87
	v_cvt_pk_bf16_f32 v84, v90, v91
	v_cvt_pk_bf16_f32 v85, v88, v89
	s_waitcnt lgkmcnt(0)
	v_add_f32_e32 v80, v80, v81
	ds_bpermute_b32 v81, v114, v80
	global_store_dwordx4 v[106:107], v[82:85], off offset:256
	s_and_saveexec_b64 s[4:5], vcc
	s_cbranch_execz .LBB0_1348
	v_lshlrev_b64 v[82:83], 7, v[96:97]
	v_lshl_add_u64 v[82:83], s[20:21], 0, v[82:83]
	v_lshl_add_u64 v[82:83], s[34:35], 2, v[82:83]
	s_lshl_b32 s14, s50, 2
	v_lshl_add_u64 v[82:83], v[82:83], 0, s[14:15]
	s_waitcnt lgkmcnt(0)
	v_add_f32_e32 v80, v80, v81
	global_store_dword v[82:83], v80, off
.LBB0_1348:
	s_or_b64 exec, exec, s[4:5]
	v_add_u32_e32 v80, 48, v144
	s_waitcnt lgkmcnt(0)
	v_ashrrev_i32_e32 v81, 31, v80
	v_lshlrev_b64 v[82:83], 11, v[80:81]
	v_lshl_add_u64 v[90:91], v[82:83], 0, v[142:143]
	v_lshl_add_u64 v[92:93], v[90:91], 2, s[12:13]
	s_waitcnt vmcnt(25)
	s_nop 1
	v_mov_b32_e32 v82, v220
	v_mov_b32_e32 v83, v221
	v_mov_b32_e32 v84, v222
	v_mov_b32_e32 v85, v223
	s_waitcnt vmcnt(24)
	s_nop 1
	v_mov_b32_e32 v86, v224
	v_mov_b32_e32 v87, v225
	v_mov_b32_e32 v88, v226
	v_mov_b32_e32 v89, v227
	v_lshl_add_u64 v[90:91], v[90:91], 1, s[18:19]
	s_nop 0
	v_pk_add_f32 v[84:85], v[78:79], v[84:85]
	v_pk_add_f32 v[82:83], v[76:77], v[82:83]
	s_nop 0
	v_pk_add_f32 v[88:89], v[74:75], v[88:89]
	v_pk_add_f32 v[86:87], v[72:73], v[86:87]
	v_cvt_pk_bf16_f32 v72, v82, v83
	v_cvt_pk_bf16_f32 v73, v84, v85
	v_mul_f32_e32 v83, v83, v83
	v_cvt_pk_bf16_f32 v74, v86, v87
	v_cvt_pk_bf16_f32 v75, v88, v89
	global_store_dwordx4 v[90:91], v[72:75], off
	s_waitcnt vmcnt(24)
	s_nop 1
	v_mov_b32_e32 v72, v232
	v_mov_b32_e32 v73, v233
	v_mov_b32_e32 v74, v234
	v_mov_b32_e32 v75, v235
	s_nop 0
	s_waitcnt vmcnt(23)
	s_nop 1
	v_mov_b32_e32 v76, v236
	v_mov_b32_e32 v77, v237
	v_mov_b32_e32 v78, v238
	v_mov_b32_e32 v79, v239
	v_mul_f32_e32 v85, v85, v85
	v_mul_f32_e32 v87, v87, v87
	v_fmac_f32_e32 v83, v82, v82
	v_fmac_f32_e32 v85, v84, v84
	v_mul_f32_e32 v89, v89, v89
	v_fmac_f32_e32 v87, v86, v86
	v_add_f32_e32 v82, v83, v85
	v_fmac_f32_e32 v89, v88, v88
	v_add_f32_e32 v82, v82, v87
	v_add_f32_e32 v82, v89, v82
	s_nop 0
	v_pk_add_f32 v[70:71], v[70:71], v[74:75]
	v_pk_add_f32 v[68:69], v[68:69], v[72:73]
	s_nop 0
	v_pk_add_f32 v[74:75], v[64:65], v[76:77]
	v_mul_f32_e32 v64, v69, v69
	v_mul_f32_e32 v65, v71, v71
	v_pk_add_f32 v[72:73], v[66:67], v[78:79]
	v_mul_f32_e32 v66, v75, v75
	v_fmac_f32_e32 v64, v68, v68
	v_fmac_f32_e32 v65, v70, v70
	v_mul_f32_e32 v67, v73, v73
	v_fmac_f32_e32 v66, v74, v74
	v_add_f32_e32 v64, v64, v65
	v_add_f32_e32 v64, v64, v66
	v_fmac_f32_e32 v67, v72, v72
	v_add_f32_e32 v64, v67, v64
	v_add_f32_e32 v64, v82, v64
	ds_bpermute_b32 v65, v120, v64
	v_cvt_pk_bf16_f32 v66, v68, v69
	v_cvt_pk_bf16_f32 v67, v70, v71
	v_cvt_pk_bf16_f32 v68, v74, v75
	v_cvt_pk_bf16_f32 v69, v72, v73
	s_waitcnt lgkmcnt(0)
	v_add_f32_e32 v64, v64, v65
	ds_bpermute_b32 v65, v114, v64
	global_store_dwordx4 v[90:91], v[66:69], off offset:256
	s_and_saveexec_b64 s[4:5], vcc
	s_cbranch_execz .LBB0_1350
	v_lshlrev_b64 v[66:67], 7, v[80:81]
	v_lshl_add_u64 v[66:67], s[20:21], 0, v[66:67]
	v_lshl_add_u64 v[66:67], s[34:35], 2, v[66:67]
	s_lshl_b32 s14, s50, 2
	v_lshl_add_u64 v[66:67], v[66:67], 0, s[14:15]
	s_waitcnt lgkmcnt(0)
	v_add_f32_e32 v64, v64, v65
	global_store_dword v[66:67], v64, off
.LBB0_1350:
	s_or_b64 exec, exec, s[4:5]
	v_add_u32_e32 v64, 0x80, v144
	s_waitcnt lgkmcnt(0)
	v_ashrrev_i32_e32 v65, 31, v64
	v_lshlrev_b64 v[66:67], 11, v[64:65]
	v_lshl_add_u64 v[74:75], v[66:67], 0, v[142:143]
	v_lshl_add_u64 v[76:77], v[74:75], 2, s[12:13]
	s_waitcnt vmcnt(23)
	s_nop 1
	v_mov_b32_e32 v66, v240
	v_mov_b32_e32 v67, v241
	v_mov_b32_e32 v68, v242
	v_mov_b32_e32 v69, v243
	s_waitcnt vmcnt(22)
	s_nop 1
	v_mov_b32_e32 v70, v244
	v_mov_b32_e32 v71, v245
	v_mov_b32_e32 v72, v246
	v_mov_b32_e32 v73, v247
	v_lshl_add_u64 v[74:75], v[74:75], 1, s[18:19]
	s_nop 0
	v_pk_add_f32 v[68:69], v[62:63], v[68:69]
	v_pk_add_f32 v[66:67], v[60:61], v[66:67]
	s_nop 0
	v_pk_add_f32 v[72:73], v[58:59], v[72:73]
	v_pk_add_f32 v[70:71], v[56:57], v[70:71]
	v_cvt_pk_bf16_f32 v56, v66, v67
	v_cvt_pk_bf16_f32 v57, v68, v69
	v_mul_f32_e32 v67, v67, v67
	v_cvt_pk_bf16_f32 v58, v70, v71
	v_cvt_pk_bf16_f32 v59, v72, v73
	global_store_dwordx4 v[74:75], v[56:59], off
	s_waitcnt vmcnt(22)
	s_nop 1
	v_mov_b32_e32 v56, v248
	v_mov_b32_e32 v57, v249
	v_mov_b32_e32 v58, v250
	v_mov_b32_e32 v59, v251
	s_nop 0
	s_waitcnt vmcnt(21)
	s_nop 1
	v_mov_b32_e32 v60, v252
	v_mov_b32_e32 v61, v253
	v_mov_b32_e32 v62, v254
	v_mov_b32_e32 v63, v255
	v_mul_f32_e32 v69, v69, v69
	v_mul_f32_e32 v71, v71, v71
	v_fmac_f32_e32 v67, v66, v66
	v_fmac_f32_e32 v69, v68, v68
	v_mul_f32_e32 v73, v73, v73
	v_fmac_f32_e32 v71, v70, v70
	v_add_f32_e32 v66, v67, v69
	v_fmac_f32_e32 v73, v72, v72
	v_add_f32_e32 v66, v66, v71
	v_add_f32_e32 v66, v73, v66
	s_nop 0
	v_pk_add_f32 v[54:55], v[54:55], v[58:59]
	v_pk_add_f32 v[52:53], v[52:53], v[56:57]
	s_nop 0
	v_pk_add_f32 v[58:59], v[48:49], v[60:61]
	v_mul_f32_e32 v48, v53, v53
	v_mul_f32_e32 v49, v55, v55
	v_pk_add_f32 v[56:57], v[50:51], v[62:63]
	v_mul_f32_e32 v50, v59, v59
	v_fmac_f32_e32 v48, v52, v52
	v_fmac_f32_e32 v49, v54, v54
	v_mul_f32_e32 v51, v57, v57
	v_fmac_f32_e32 v50, v58, v58
	v_add_f32_e32 v48, v48, v49
	v_add_f32_e32 v48, v48, v50
	v_fmac_f32_e32 v51, v56, v56
	v_add_f32_e32 v48, v51, v48
	v_add_f32_e32 v48, v66, v48
	ds_bpermute_b32 v49, v120, v48
	v_cvt_pk_bf16_f32 v50, v52, v53
	v_cvt_pk_bf16_f32 v51, v54, v55
	v_cvt_pk_bf16_f32 v52, v58, v59
	v_cvt_pk_bf16_f32 v53, v56, v57
	s_waitcnt lgkmcnt(0)
	v_add_f32_e32 v48, v48, v49
	ds_bpermute_b32 v49, v114, v48
	global_store_dwordx4 v[74:75], v[50:53], off offset:256
	s_and_saveexec_b64 s[4:5], vcc
	s_cbranch_execz .LBB0_1352
	v_lshlrev_b64 v[50:51], 7, v[64:65]
	v_lshl_add_u64 v[50:51], s[20:21], 0, v[50:51]
	v_lshl_add_u64 v[50:51], s[34:35], 2, v[50:51]
	s_lshl_b32 s14, s50, 2
	v_lshl_add_u64 v[50:51], v[50:51], 0, s[14:15]
	s_waitcnt lgkmcnt(0)
	v_add_f32_e32 v48, v48, v49
	global_store_dword v[50:51], v48, off
.LBB0_1352:
	s_or_b64 exec, exec, s[4:5]
	v_add_u32_e32 v48, 0x90, v144
	s_waitcnt lgkmcnt(0)
	v_ashrrev_i32_e32 v49, 31, v48
	v_lshlrev_b64 v[50:51], 11, v[48:49]
	v_lshl_add_u64 v[58:59], v[50:51], 0, v[142:143]
	v_lshl_add_u64 v[60:61], v[58:59], 2, s[12:13]
	s_waitcnt vmcnt(21)
	s_nop 1
	v_mov_b32_e32 v50, v172
	v_mov_b32_e32 v51, v173
	v_mov_b32_e32 v52, v174
	v_mov_b32_e32 v53, v175
	s_waitcnt vmcnt(20)
	s_nop 1
	v_mov_b32_e32 v54, v176
	v_mov_b32_e32 v55, v177
	v_mov_b32_e32 v56, v178
	v_mov_b32_e32 v57, v179
	v_lshl_add_u64 v[58:59], v[58:59], 1, s[18:19]
	s_nop 0
	v_pk_add_f32 v[52:53], v[46:47], v[52:53]
	v_pk_add_f32 v[50:51], v[44:45], v[50:51]
	s_nop 0
	v_pk_add_f32 v[56:57], v[42:43], v[56:57]
	v_pk_add_f32 v[54:55], v[40:41], v[54:55]
	v_cvt_pk_bf16_f32 v40, v50, v51
	v_cvt_pk_bf16_f32 v41, v52, v53
	v_mul_f32_e32 v51, v51, v51
	v_cvt_pk_bf16_f32 v42, v54, v55
	v_cvt_pk_bf16_f32 v43, v56, v57
	global_store_dwordx4 v[58:59], v[40:43], off
	s_waitcnt vmcnt(19)
	s_nop 1
	v_mov_b32_e32 v40, v180
	v_mov_b32_e32 v41, v181
	v_mov_b32_e32 v42, v182
	v_mov_b32_e32 v43, v183
	s_nop 0
	s_waitcnt vmcnt(18)
	s_nop 1
	v_mov_b32_e32 v44, v184
	v_mov_b32_e32 v45, v185
	v_mov_b32_e32 v46, v186
	v_mov_b32_e32 v47, v187
	v_mul_f32_e32 v53, v53, v53
	v_mul_f32_e32 v55, v55, v55
	v_fmac_f32_e32 v51, v50, v50
	v_fmac_f32_e32 v53, v52, v52
	v_mul_f32_e32 v57, v57, v57
	v_fmac_f32_e32 v55, v54, v54
	v_add_f32_e32 v50, v51, v53
	v_fmac_f32_e32 v57, v56, v56
	v_add_f32_e32 v50, v50, v55
	v_add_f32_e32 v50, v57, v50
	s_nop 0
	v_pk_add_f32 v[38:39], v[38:39], v[42:43]
	v_pk_add_f32 v[36:37], v[36:37], v[40:41]
	s_nop 0
	v_pk_add_f32 v[42:43], v[32:33], v[44:45]
	v_mul_f32_e32 v32, v37, v37
	v_mul_f32_e32 v33, v39, v39
	v_pk_add_f32 v[40:41], v[34:35], v[46:47]
	v_mul_f32_e32 v34, v43, v43
	v_fmac_f32_e32 v32, v36, v36
	v_fmac_f32_e32 v33, v38, v38
	v_mul_f32_e32 v35, v41, v41
	v_fmac_f32_e32 v34, v42, v42
	v_add_f32_e32 v32, v32, v33
	v_add_f32_e32 v32, v32, v34
	v_fmac_f32_e32 v35, v40, v40
	v_add_f32_e32 v32, v35, v32
	v_add_f32_e32 v32, v50, v32
	ds_bpermute_b32 v33, v120, v32
	v_cvt_pk_bf16_f32 v34, v36, v37
	v_cvt_pk_bf16_f32 v35, v38, v39
	v_cvt_pk_bf16_f32 v36, v42, v43
	v_cvt_pk_bf16_f32 v37, v40, v41
	s_waitcnt lgkmcnt(0)
	v_add_f32_e32 v32, v32, v33
	ds_bpermute_b32 v33, v114, v32
	global_store_dwordx4 v[58:59], v[34:37], off offset:256
	s_and_saveexec_b64 s[4:5], vcc
	s_cbranch_execz .LBB0_1354
	v_lshlrev_b64 v[34:35], 7, v[48:49]
	v_lshl_add_u64 v[34:35], s[20:21], 0, v[34:35]
	v_lshl_add_u64 v[34:35], s[34:35], 2, v[34:35]
	s_lshl_b32 s14, s50, 2
	v_lshl_add_u64 v[34:35], v[34:35], 0, s[14:15]
	s_waitcnt lgkmcnt(0)
	v_add_f32_e32 v32, v32, v33
	global_store_dword v[34:35], v32, off
.LBB0_1354:
	s_or_b64 exec, exec, s[4:5]
	v_add_u32_e32 v32, 0xa0, v144
	s_waitcnt lgkmcnt(0)
	v_ashrrev_i32_e32 v33, 31, v32
	v_lshlrev_b64 v[34:35], 11, v[32:33]
	v_lshl_add_u64 v[42:43], v[34:35], 0, v[142:143]
	v_lshl_add_u64 v[44:45], v[42:43], 2, s[12:13]
	s_waitcnt vmcnt(17)
	s_nop 1
	v_mov_b32_e32 v34, v188
	v_mov_b32_e32 v35, v189
	v_mov_b32_e32 v36, v190
	v_mov_b32_e32 v37, v191
	s_waitcnt vmcnt(16)
	s_nop 1
	v_mov_b32_e32 v38, v192
	v_mov_b32_e32 v39, v193
	v_mov_b32_e32 v40, v194
	v_mov_b32_e32 v41, v195
	v_lshl_add_u64 v[42:43], v[42:43], 1, s[18:19]
	s_nop 0
	v_pk_add_f32 v[36:37], v[30:31], v[36:37]
	v_pk_add_f32 v[34:35], v[28:29], v[34:35]
	s_nop 0
	v_pk_add_f32 v[40:41], v[26:27], v[40:41]
	v_pk_add_f32 v[38:39], v[24:25], v[38:39]
	v_cvt_pk_bf16_f32 v24, v34, v35
	v_cvt_pk_bf16_f32 v25, v36, v37
	v_mul_f32_e32 v35, v35, v35
	v_cvt_pk_bf16_f32 v26, v38, v39
	v_cvt_pk_bf16_f32 v27, v40, v41
	global_store_dwordx4 v[42:43], v[24:27], off
	s_waitcnt vmcnt(15)
	s_nop 1
	v_mov_b32_e32 v24, v196
	v_mov_b32_e32 v25, v197
	v_mov_b32_e32 v26, v198
	v_mov_b32_e32 v27, v199
	s_nop 0
	s_waitcnt vmcnt(14)
	s_nop 1
	v_mov_b32_e32 v28, v200
	v_mov_b32_e32 v29, v201
	v_mov_b32_e32 v30, v202
	v_mov_b32_e32 v31, v203
	v_mul_f32_e32 v37, v37, v37
	v_mul_f32_e32 v39, v39, v39
	v_fmac_f32_e32 v35, v34, v34
	v_fmac_f32_e32 v37, v36, v36
	v_mul_f32_e32 v41, v41, v41
	v_fmac_f32_e32 v39, v38, v38
	v_add_f32_e32 v34, v35, v37
	v_fmac_f32_e32 v41, v40, v40
	v_add_f32_e32 v34, v34, v39
	v_add_f32_e32 v34, v41, v34
	s_nop 0
	v_pk_add_f32 v[22:23], v[22:23], v[26:27]
	v_pk_add_f32 v[20:21], v[20:21], v[24:25]
	s_nop 0
	v_pk_add_f32 v[26:27], v[16:17], v[28:29]
	v_mul_f32_e32 v16, v21, v21
	v_mul_f32_e32 v17, v23, v23
	v_pk_add_f32 v[24:25], v[18:19], v[30:31]
	v_mul_f32_e32 v18, v27, v27
	v_fmac_f32_e32 v16, v20, v20
	v_fmac_f32_e32 v17, v22, v22
	v_mul_f32_e32 v19, v25, v25
	v_fmac_f32_e32 v18, v26, v26
	v_add_f32_e32 v16, v16, v17
	v_add_f32_e32 v16, v16, v18
	v_fmac_f32_e32 v19, v24, v24
	v_add_f32_e32 v16, v19, v16
	v_add_f32_e32 v16, v34, v16
	ds_bpermute_b32 v17, v120, v16
	v_cvt_pk_bf16_f32 v18, v20, v21
	v_cvt_pk_bf16_f32 v19, v22, v23
	v_cvt_pk_bf16_f32 v20, v26, v27
	v_cvt_pk_bf16_f32 v21, v24, v25
	s_waitcnt lgkmcnt(0)
	v_add_f32_e32 v16, v16, v17
	ds_bpermute_b32 v17, v114, v16
	global_store_dwordx4 v[42:43], v[18:21], off offset:256
	s_and_saveexec_b64 s[4:5], vcc
	s_cbranch_execz .LBB0_1356
	v_lshlrev_b64 v[18:19], 7, v[32:33]
	v_lshl_add_u64 v[18:19], s[20:21], 0, v[18:19]
	v_lshl_add_u64 v[18:19], s[34:35], 2, v[18:19]
	s_lshl_b32 s14, s50, 2
	v_lshl_add_u64 v[18:19], v[18:19], 0, s[14:15]
	s_waitcnt lgkmcnt(0)
	v_add_f32_e32 v16, v16, v17
	global_store_dword v[18:19], v16, off
.LBB0_1356:
	s_or_b64 exec, exec, s[4:5]
	v_add_u32_e32 v16, 0xb0, v144
	s_waitcnt lgkmcnt(0)
	v_ashrrev_i32_e32 v17, 31, v16
	v_lshlrev_b64 v[18:19], 11, v[16:17]
	v_lshl_add_u64 v[26:27], v[18:19], 0, v[142:143]
	v_lshl_add_u64 v[28:29], v[26:27], 2, s[12:13]
	s_waitcnt vmcnt(13)
	s_nop 1
	v_mov_b32_e32 v18, v204
	v_mov_b32_e32 v19, v205
	v_mov_b32_e32 v20, v206
	v_mov_b32_e32 v21, v207
	s_waitcnt vmcnt(12)
	s_nop 1
	v_mov_b32_e32 v22, v208
	v_mov_b32_e32 v23, v209
	v_mov_b32_e32 v24, v210
	v_mov_b32_e32 v25, v211
	v_lshl_add_u64 v[26:27], v[26:27], 1, s[18:19]
	s_nop 0
	v_pk_add_f32 v[20:21], v[14:15], v[20:21]
	v_pk_add_f32 v[18:19], v[12:13], v[18:19]
	s_nop 0
	v_pk_add_f32 v[24:25], v[10:11], v[24:25]
	v_pk_add_f32 v[22:23], v[8:9], v[22:23]
	v_cvt_pk_bf16_f32 v8, v18, v19
	v_cvt_pk_bf16_f32 v9, v20, v21
	v_mul_f32_e32 v19, v19, v19
	v_cvt_pk_bf16_f32 v10, v22, v23
	v_cvt_pk_bf16_f32 v11, v24, v25
	global_store_dwordx4 v[26:27], v[8:11], off
	s_waitcnt vmcnt(11)
	s_nop 1
	v_mov_b32_e32 v8, v212
	v_mov_b32_e32 v9, v213
	v_mov_b32_e32 v10, v214
	v_mov_b32_e32 v11, v215
	s_nop 0
	s_waitcnt vmcnt(10)
	s_nop 1
	v_mov_b32_e32 v12, v216
	v_mov_b32_e32 v13, v217
	v_mov_b32_e32 v14, v218
	v_mov_b32_e32 v15, v219
	v_mul_f32_e32 v21, v21, v21
	v_mul_f32_e32 v23, v23, v23
	v_fmac_f32_e32 v19, v18, v18
	v_fmac_f32_e32 v21, v20, v20
	v_mul_f32_e32 v25, v25, v25
	v_fmac_f32_e32 v23, v22, v22
	v_add_f32_e32 v18, v19, v21
	v_fmac_f32_e32 v25, v24, v24
	v_add_f32_e32 v18, v18, v23
	v_add_f32_e32 v18, v25, v18
	s_nop 0
	v_pk_add_f32 v[6:7], v[6:7], v[10:11]
	v_pk_add_f32 v[4:5], v[4:5], v[8:9]
	s_nop 0
	v_pk_add_f32 v[10:11], v[0:1], v[12:13]
	v_mul_f32_e32 v0, v5, v5
	v_mul_f32_e32 v1, v7, v7
	v_pk_add_f32 v[8:9], v[2:3], v[14:15]
	v_mul_f32_e32 v2, v11, v11
	v_fmac_f32_e32 v0, v4, v4
	v_fmac_f32_e32 v1, v6, v6
	v_mul_f32_e32 v3, v9, v9
	v_fmac_f32_e32 v2, v10, v10
	v_add_f32_e32 v0, v0, v1
	v_add_f32_e32 v0, v0, v2
	v_fmac_f32_e32 v3, v8, v8
	v_add_f32_e32 v0, v3, v0
	v_add_f32_e32 v0, v18, v0
	ds_bpermute_b32 v1, v120, v0
	v_cvt_pk_bf16_f32 v2, v4, v5
	v_cvt_pk_bf16_f32 v3, v6, v7
	v_cvt_pk_bf16_f32 v4, v10, v11
	v_cvt_pk_bf16_f32 v5, v8, v9
	s_waitcnt lgkmcnt(0)
	v_add_f32_e32 v0, v0, v1
	ds_bpermute_b32 v1, v114, v0
	global_store_dwordx4 v[26:27], v[2:5], off offset:256
	s_and_saveexec_b64 s[4:5], vcc
	s_cbranch_execz .LBB0_1358
	v_lshlrev_b64 v[2:3], 7, v[16:17]
	v_lshl_add_u64 v[2:3], s[20:21], 0, v[2:3]
	v_lshl_add_u64 v[2:3], s[34:35], 2, v[2:3]
	s_lshl_b32 s14, s50, 2
	v_lshl_add_u64 v[2:3], v[2:3], 0, s[14:15]
	s_waitcnt lgkmcnt(0)
	v_add_f32_e32 v0, v0, v1
	global_store_dword v[2:3], v0, off

.LBB0_1577:
	v_mov_b32_e32 v138, v141
	v_mov_b32_e32 v139, v140
	s_lshl_b32 s33, s72, 8
	s_add_i32 s33, s33, s63
	v_add_u32_e32 v138, s33, v138
	s_lshl_b32 s33, s71, 8
	s_or_b32 s33, s33, s64
	v_lshl_add_u32 v146, v139, 2, s33
	v_ashrrev_i32_e32 v139, 31, v138
	v_ashrrev_i32_e32 v147, 31, v146
	v_lshlrev_b64 v[138:139], 11, v[138:139]
	v_lshl_add_u64 v[138:139], v[138:139], 0, v[146:147]
	v_lshl_add_u64 v[146:147], v[138:139], 1, s[14:15]
	v_mov_b32_e32 v154, v146
	v_mov_b32_e32 v155, v147
	global_load_dwordx2 v[156:157], v[154:155], off
	global_load_dwordx2 v[158:159], v[154:155], off offset:32
	global_load_dwordx2 v[160:161], v[154:155], off offset:256
	global_load_dwordx2 v[162:163], v[154:155], off offset:288
	s_mov_b64 s[98:99], 0x10000
	v_lshl_add_u64 v[154:155], v[154:155], 0, s[98:99]
	global_load_dwordx2 v[164:165], v[154:155], off
	global_load_dwordx2 v[166:167], v[154:155], off offset:32
	global_load_dwordx2 v[168:169], v[154:155], off offset:256
	global_load_dwordx2 v[170:171], v[154:155], off offset:288
	s_mov_b64 s[98:99], 0x10000
	v_lshl_add_u64 v[154:155], v[154:155], 0, s[98:99]
	global_load_dwordx2 v[172:173], v[154:155], off
	global_load_dwordx2 v[174:175], v[154:155], off offset:32
	global_load_dwordx2 v[176:177], v[154:155], off offset:256
	global_load_dwordx2 v[178:179], v[154:155], off offset:288
	s_mov_b64 s[98:99], 0x10000
	v_lshl_add_u64 v[154:155], v[154:155], 0, s[98:99]
	global_load_dwordx2 v[180:181], v[154:155], off
	global_load_dwordx2 v[182:183], v[154:155], off offset:32
	global_load_dwordx2 v[184:185], v[154:155], off offset:256
	global_load_dwordx2 v[186:187], v[154:155], off offset:288
	s_mov_b64 s[98:99], 0x50000
	v_lshl_add_u64 v[154:155], v[154:155], 0, s[98:99]
	global_load_dwordx2 v[188:189], v[154:155], off
	global_load_dwordx2 v[190:191], v[154:155], off offset:32
	global_load_dwordx2 v[192:193], v[154:155], off offset:256
	global_load_dwordx2 v[194:195], v[154:155], off offset:288
	s_mov_b64 s[98:99], 0x10000
	v_lshl_add_u64 v[154:155], v[154:155], 0, s[98:99]
	global_load_dwordx2 v[196:197], v[154:155], off
	global_load_dwordx2 v[198:199], v[154:155], off offset:32
	global_load_dwordx2 v[200:201], v[154:155], off offset:256
	global_load_dwordx2 v[202:203], v[154:155], off offset:288
	s_mov_b64 s[98:99], 0x10000
	v_lshl_add_u64 v[154:155], v[154:155], 0, s[98:99]
	global_load_dwordx2 v[204:205], v[154:155], off
	global_load_dwordx2 v[206:207], v[154:155], off offset:32
	global_load_dwordx2 v[208:209], v[154:155], off offset:256
	global_load_dwordx2 v[210:211], v[154:155], off offset:288
	s_mov_b64 s[98:99], 0x10000
	v_lshl_add_u64 v[154:155], v[154:155], 0, s[98:99]
	global_load_dwordx2 v[212:213], v[154:155], off
	global_load_dwordx2 v[214:215], v[154:155], off offset:32
	global_load_dwordx2 v[216:217], v[154:155], off offset:256
	global_load_dwordx2 v[218:219], v[154:155], off offset:288
	s_waitcnt vmcnt(31)
	s_nop 1
	v_mov_b32_e32 v148, v156
	v_mov_b32_e32 v149, v157
	v_lshl_add_u64 v[150:151], v[138:139], 2, s[4:5]
	s_and_b64 vcc, exec, s[0:1]
	s_mov_b64 s[0:1], -1
	s_nop 0
	v_lshlrev_b32_e32 v152, 16, v148
	v_and_b32_e32 v153, 0xffff0000, v148
	v_lshlrev_b32_e32 v148, 16, v149
	v_and_b32_e32 v149, 0xffff0000, v149
	v_pk_add_f32 v[126:127], v[126:127], v[148:149]
	v_pk_add_f32 v[124:125], v[124:125], v[152:153]
	global_store_dwordx4 v[150:151], v[124:127], off
	s_waitcnt vmcnt(31)
	s_nop 1
	v_mov_b32_e32 v124, v158
	v_mov_b32_e32 v125, v159
	s_nop 0
	v_lshlrev_b32_e32 v126, 16, v124
	v_and_b32_e32 v127, 0xffff0000, v124
	v_lshlrev_b32_e32 v124, 16, v125
	v_and_b32_e32 v125, 0xffff0000, v125
	v_pk_add_f32 v[122:123], v[122:123], v[124:125]
	v_pk_add_f32 v[120:121], v[120:121], v[126:127]
	global_store_dwordx4 v[150:151], v[120:123], off offset:64
	s_waitcnt vmcnt(31)
	s_nop 1
	v_mov_b32_e32 v120, v160
	v_mov_b32_e32 v121, v161
	s_nop 0
	v_lshlrev_b32_e32 v122, 16, v120
	v_and_b32_e32 v123, 0xffff0000, v120
	v_lshlrev_b32_e32 v120, 16, v121
	v_and_b32_e32 v121, 0xffff0000, v121
	v_pk_add_f32 v[118:119], v[118:119], v[120:121]
	v_pk_add_f32 v[116:117], v[116:117], v[122:123]
	global_store_dwordx4 v[150:151], v[116:119], off offset:512
	s_waitcnt vmcnt(31)
	s_nop 1
	v_mov_b32_e32 v116, v162
	v_mov_b32_e32 v117, v163
	s_nop 0
	v_lshlrev_b32_e32 v122, 16, v116
	v_and_b32_e32 v123, 0xffff0000, v116
	v_lshlrev_b32_e32 v116, 16, v117
	v_and_b32_e32 v117, 0xffff0000, v117
	v_lshl_add_u64 v[118:119], v[138:139], 0, s[22:23]
	v_pk_add_f32 v[114:115], v[114:115], v[116:117]
	v_pk_add_f32 v[112:113], v[112:113], v[122:123]
	v_lshl_add_u64 v[120:121], v[118:119], 1, s[14:15]
	global_store_dwordx4 v[150:151], v[112:115], off offset:576
	s_waitcnt vmcnt(31)
	s_nop 1
	v_mov_b32_e32 v112, v164
	v_mov_b32_e32 v113, v165
	s_nop 0
	v_lshlrev_b32_e32 v116, 16, v112
	v_and_b32_e32 v117, 0xffff0000, v112
	v_lshlrev_b32_e32 v112, 16, v113
	v_and_b32_e32 v113, 0xffff0000, v113
	v_lshl_add_u64 v[114:115], v[118:119], 2, s[4:5]
	v_pk_add_f32 v[110:111], v[110:111], v[112:113]
	v_pk_add_f32 v[108:109], v[108:109], v[116:117]
	global_store_dwordx4 v[114:115], v[108:111], off
	s_waitcnt vmcnt(31)
	s_nop 1
	v_mov_b32_e32 v108, v166
	v_mov_b32_e32 v109, v167
	s_nop 0
	v_lshlrev_b32_e32 v110, 16, v108
	v_and_b32_e32 v111, 0xffff0000, v108
	v_lshlrev_b32_e32 v108, 16, v109
	v_and_b32_e32 v109, 0xffff0000, v109
	v_pk_add_f32 v[106:107], v[106:107], v[108:109]
	v_pk_add_f32 v[104:105], v[104:105], v[110:111]
	global_store_dwordx4 v[114:115], v[104:107], off offset:64
	s_waitcnt vmcnt(31)
	s_nop 1
	v_mov_b32_e32 v104, v168
	v_mov_b32_e32 v105, v169
	s_nop 0
	v_lshlrev_b32_e32 v106, 16, v104
	v_and_b32_e32 v107, 0xffff0000, v104
	v_lshlrev_b32_e32 v104, 16, v105
	v_and_b32_e32 v105, 0xffff0000, v105
	v_pk_add_f32 v[102:103], v[102:103], v[104:105]
	v_pk_add_f32 v[100:101], v[100:101], v[106:107]
	global_store_dwordx4 v[114:115], v[100:103], off offset:512
	s_waitcnt vmcnt(31)
	s_nop 1
	v_mov_b32_e32 v100, v170
	v_mov_b32_e32 v101, v171
	s_nop 0
	v_lshlrev_b32_e32 v106, 16, v100
	v_and_b32_e32 v107, 0xffff0000, v100
	v_lshlrev_b32_e32 v100, 16, v101
	v_and_b32_e32 v101, 0xffff0000, v101
	v_lshl_add_u64 v[102:103], v[138:139], 0, s[24:25]
	v_pk_add_f32 v[98:99], v[98:99], v[100:101]
	v_pk_add_f32 v[96:97], v[96:97], v[106:107]
	v_lshl_add_u64 v[104:105], v[102:103], 1, s[14:15]
	global_store_dwordx4 v[114:115], v[96:99], off offset:576
	s_waitcnt vmcnt(31)
	s_nop 1
	v_mov_b32_e32 v96, v172
	v_mov_b32_e32 v97, v173
	s_nop 0
	v_lshlrev_b32_e32 v100, 16, v96
	v_and_b32_e32 v101, 0xffff0000, v96
	v_lshlrev_b32_e32 v96, 16, v97
	v_and_b32_e32 v97, 0xffff0000, v97
	v_lshl_add_u64 v[98:99], v[102:103], 2, s[4:5]
	v_pk_add_f32 v[94:95], v[94:95], v[96:97]
	v_pk_add_f32 v[92:93], v[92:93], v[100:101]
	global_store_dwordx4 v[98:99], v[92:95], off
	s_waitcnt vmcnt(31)
	s_nop 1
	v_mov_b32_e32 v92, v174
	v_mov_b32_e32 v93, v175
	s_nop 0
	v_lshlrev_b32_e32 v94, 16, v92
	v_and_b32_e32 v95, 0xffff0000, v92
	v_lshlrev_b32_e32 v92, 16, v93
	v_and_b32_e32 v93, 0xffff0000, v93
	v_pk_add_f32 v[90:91], v[90:91], v[92:93]
	v_pk_add_f32 v[88:89], v[88:89], v[94:95]
	global_store_dwordx4 v[98:99], v[88:91], off offset:64
	s_waitcnt vmcnt(31)
	s_nop 1
	v_mov_b32_e32 v88, v176
	v_mov_b32_e32 v89, v177
	s_nop 0
	v_lshlrev_b32_e32 v90, 16, v88
	v_and_b32_e32 v91, 0xffff0000, v88
	v_lshlrev_b32_e32 v88, 16, v89
	v_and_b32_e32 v89, 0xffff0000, v89
	v_pk_add_f32 v[86:87], v[86:87], v[88:89]
	v_pk_add_f32 v[84:85], v[84:85], v[90:91]
	global_store_dwordx4 v[98:99], v[84:87], off offset:512
	s_waitcnt vmcnt(31)
	s_nop 1
	v_mov_b32_e32 v84, v178
	v_mov_b32_e32 v85, v179
	s_nop 0
	v_lshlrev_b32_e32 v90, 16, v84
	v_and_b32_e32 v91, 0xffff0000, v84
	v_lshlrev_b32_e32 v84, 16, v85
	v_and_b32_e32 v85, 0xffff0000, v85
	v_lshl_add_u64 v[86:87], v[138:139], 0, s[26:27]
	v_pk_add_f32 v[82:83], v[82:83], v[84:85]
	v_pk_add_f32 v[80:81], v[80:81], v[90:91]
	v_lshl_add_u64 v[88:89], v[86:87], 1, s[14:15]
	global_store_dwordx4 v[98:99], v[80:83], off offset:576
	s_waitcnt vmcnt(31)
	s_nop 1
	v_mov_b32_e32 v80, v180
	v_mov_b32_e32 v81, v181
	s_nop 0
	v_lshlrev_b32_e32 v84, 16, v80
	v_and_b32_e32 v85, 0xffff0000, v80
	v_lshlrev_b32_e32 v80, 16, v81
	v_and_b32_e32 v81, 0xffff0000, v81
	v_lshl_add_u64 v[82:83], v[86:87], 2, s[4:5]
	v_pk_add_f32 v[78:79], v[78:79], v[80:81]
	v_pk_add_f32 v[76:77], v[76:77], v[84:85]
	global_store_dwordx4 v[82:83], v[76:79], off
	s_waitcnt vmcnt(31)
	s_nop 1
	v_mov_b32_e32 v76, v182
	v_mov_b32_e32 v77, v183
	s_nop 0
	v_lshlrev_b32_e32 v78, 16, v76
	v_and_b32_e32 v79, 0xffff0000, v76
	v_lshlrev_b32_e32 v76, 16, v77
	v_and_b32_e32 v77, 0xffff0000, v77
	v_pk_add_f32 v[74:75], v[74:75], v[76:77]
	v_pk_add_f32 v[72:73], v[72:73], v[78:79]
	global_store_dwordx4 v[82:83], v[72:75], off offset:64
	s_waitcnt vmcnt(31)
	s_nop 1
	v_mov_b32_e32 v72, v184
	v_mov_b32_e32 v73, v185
	s_nop 0
	v_lshlrev_b32_e32 v74, 16, v72
	v_and_b32_e32 v75, 0xffff0000, v72
	v_lshlrev_b32_e32 v72, 16, v73
	v_and_b32_e32 v73, 0xffff0000, v73
	v_pk_add_f32 v[70:71], v[70:71], v[72:73]
	v_pk_add_f32 v[68:69], v[68:69], v[74:75]
	global_store_dwordx4 v[82:83], v[68:71], off offset:512
	s_waitcnt vmcnt(31)
	s_nop 1
	v_mov_b32_e32 v68, v186
	v_mov_b32_e32 v69, v187
	s_nop 0
	v_lshlrev_b32_e32 v74, 16, v68
	v_and_b32_e32 v75, 0xffff0000, v68
	v_lshlrev_b32_e32 v68, 16, v69
	v_and_b32_e32 v69, 0xffff0000, v69
	v_lshl_add_u64 v[70:71], v[138:139], 0, s[28:29]
	v_pk_add_f32 v[66:67], v[66:67], v[68:69]
	v_pk_add_f32 v[64:65], v[64:65], v[74:75]
	v_lshl_add_u64 v[72:73], v[70:71], 1, s[14:15]
	global_store_dwordx4 v[82:83], v[64:67], off offset:576
	s_waitcnt vmcnt(31)
	s_nop 1
	v_mov_b32_e32 v64, v188
	v_mov_b32_e32 v65, v189
	s_nop 0
	v_lshlrev_b32_e32 v68, 16, v64
	v_and_b32_e32 v69, 0xffff0000, v64
	v_lshlrev_b32_e32 v64, 16, v65
	v_and_b32_e32 v65, 0xffff0000, v65
	v_lshl_add_u64 v[66:67], v[70:71], 2, s[4:5]
	v_pk_add_f32 v[62:63], v[62:63], v[64:65]
	v_pk_add_f32 v[60:61], v[60:61], v[68:69]
	global_store_dwordx4 v[66:67], v[60:63], off
	s_waitcnt vmcnt(31)
	s_nop 1
	v_mov_b32_e32 v60, v190
	v_mov_b32_e32 v61, v191
	s_nop 0
	v_lshlrev_b32_e32 v62, 16, v60
	v_and_b32_e32 v63, 0xffff0000, v60
	v_lshlrev_b32_e32 v60, 16, v61
	v_and_b32_e32 v61, 0xffff0000, v61
	v_pk_add_f32 v[58:59], v[58:59], v[60:61]
	v_pk_add_f32 v[56:57], v[56:57], v[62:63]
	global_store_dwordx4 v[66:67], v[56:59], off offset:64
	s_waitcnt vmcnt(31)
	s_nop 1
	v_mov_b32_e32 v56, v192
	v_mov_b32_e32 v57, v193
	s_nop 0
	v_lshlrev_b32_e32 v58, 16, v56
	v_and_b32_e32 v59, 0xffff0000, v56
	v_lshlrev_b32_e32 v56, 16, v57
	v_and_b32_e32 v57, 0xffff0000, v57
	v_pk_add_f32 v[54:55], v[54:55], v[56:57]
	v_pk_add_f32 v[52:53], v[52:53], v[58:59]
	global_store_dwordx4 v[66:67], v[52:55], off offset:512
	s_waitcnt vmcnt(31)
	s_nop 1
	v_mov_b32_e32 v52, v194
	v_mov_b32_e32 v53, v195
	s_nop 0
	v_lshlrev_b32_e32 v58, 16, v52
	v_and_b32_e32 v59, 0xffff0000, v52
	v_lshlrev_b32_e32 v52, 16, v53
	v_and_b32_e32 v53, 0xffff0000, v53
	v_lshl_add_u64 v[54:55], v[138:139], 0, s[30:31]
	v_pk_add_f32 v[50:51], v[50:51], v[52:53]
	v_pk_add_f32 v[48:49], v[48:49], v[58:59]
	v_lshl_add_u64 v[56:57], v[54:55], 1, s[14:15]
	global_store_dwordx4 v[66:67], v[48:51], off offset:576
	s_waitcnt vmcnt(31)
	s_nop 1
	v_mov_b32_e32 v48, v196
	v_mov_b32_e32 v49, v197
	s_nop 0
	v_lshlrev_b32_e32 v52, 16, v48
	v_and_b32_e32 v53, 0xffff0000, v48
	v_lshlrev_b32_e32 v48, 16, v49
	v_and_b32_e32 v49, 0xffff0000, v49
	v_lshl_add_u64 v[50:51], v[54:55], 2, s[4:5]
	v_pk_add_f32 v[46:47], v[46:47], v[48:49]
	v_pk_add_f32 v[44:45], v[44:45], v[52:53]
	global_store_dwordx4 v[50:51], v[44:47], off
	s_waitcnt vmcnt(31)
	s_nop 1
	v_mov_b32_e32 v44, v198
	v_mov_b32_e32 v45, v199
	s_nop 0
	v_lshlrev_b32_e32 v46, 16, v44
	v_and_b32_e32 v47, 0xffff0000, v44
	v_lshlrev_b32_e32 v44, 16, v45
	v_and_b32_e32 v45, 0xffff0000, v45
	v_pk_add_f32 v[42:43], v[42:43], v[44:45]
	v_pk_add_f32 v[40:41], v[40:41], v[46:47]
	global_store_dwordx4 v[50:51], v[40:43], off offset:64
	s_waitcnt vmcnt(31)
	s_nop 1
	v_mov_b32_e32 v40, v200
	v_mov_b32_e32 v41, v201
	s_nop 0
	v_lshlrev_b32_e32 v42, 16, v40
	v_and_b32_e32 v43, 0xffff0000, v40
	v_lshlrev_b32_e32 v40, 16, v41
	v_and_b32_e32 v41, 0xffff0000, v41
	v_pk_add_f32 v[38:39], v[38:39], v[40:41]
	v_pk_add_f32 v[36:37], v[36:37], v[42:43]
	global_store_dwordx4 v[50:51], v[36:39], off offset:512
	s_waitcnt vmcnt(31)
	s_nop 1
	v_mov_b32_e32 v36, v202
	v_mov_b32_e32 v37, v203
	s_nop 0
	v_lshlrev_b32_e32 v42, 16, v36
	v_and_b32_e32 v43, 0xffff0000, v36
	v_lshlrev_b32_e32 v36, 16, v37
	v_and_b32_e32 v37, 0xffff0000, v37
	v_lshl_add_u64 v[38:39], v[138:139], 0, s[34:35]
	v_pk_add_f32 v[34:35], v[34:35], v[36:37]
	v_pk_add_f32 v[32:33], v[32:33], v[42:43]
	v_lshl_add_u64 v[40:41], v[38:39], 1, s[14:15]
	global_store_dwordx4 v[50:51], v[32:35], off offset:576
	s_waitcnt vmcnt(31)
	s_nop 1
	v_mov_b32_e32 v32, v204
	v_mov_b32_e32 v33, v205
	s_nop 0
	v_lshlrev_b32_e32 v36, 16, v32
	v_and_b32_e32 v37, 0xffff0000, v32
	v_lshlrev_b32_e32 v32, 16, v33
	v_and_b32_e32 v33, 0xffff0000, v33
	v_lshl_add_u64 v[34:35], v[38:39], 2, s[4:5]
	v_pk_add_f32 v[30:31], v[30:31], v[32:33]
	v_pk_add_f32 v[28:29], v[28:29], v[36:37]
	global_store_dwordx4 v[34:35], v[28:31], off
	s_waitcnt vmcnt(31)
	s_nop 1
	v_mov_b32_e32 v28, v206
	v_mov_b32_e32 v29, v207
	s_nop 0
	v_lshlrev_b32_e32 v30, 16, v28
	v_and_b32_e32 v31, 0xffff0000, v28
	v_lshlrev_b32_e32 v28, 16, v29
	v_and_b32_e32 v29, 0xffff0000, v29
	v_pk_add_f32 v[26:27], v[26:27], v[28:29]
	v_pk_add_f32 v[24:25], v[24:25], v[30:31]
	global_store_dwordx4 v[34:35], v[24:27], off offset:64
	s_waitcnt vmcnt(31)
	s_nop 1
	v_mov_b32_e32 v24, v208
	v_mov_b32_e32 v25, v209
	s_nop 0
	v_lshlrev_b32_e32 v26, 16, v24
	v_and_b32_e32 v27, 0xffff0000, v24
	v_lshlrev_b32_e32 v24, 16, v25
	v_and_b32_e32 v25, 0xffff0000, v25
	v_pk_add_f32 v[22:23], v[22:23], v[24:25]
	v_pk_add_f32 v[20:21], v[20:21], v[26:27]
	global_store_dwordx4 v[34:35], v[20:23], off offset:512
	s_waitcnt vmcnt(31)
	s_nop 1
	v_mov_b32_e32 v20, v210
	v_mov_b32_e32 v21, v211
	s_nop 0
	v_lshlrev_b32_e32 v26, 16, v20
	v_and_b32_e32 v27, 0xffff0000, v20
	v_lshlrev_b32_e32 v20, 16, v21
	v_and_b32_e32 v21, 0xffff0000, v21
	v_lshl_add_u64 v[22:23], v[138:139], 0, s[36:37]
	v_pk_add_f32 v[18:19], v[18:19], v[20:21]
	v_pk_add_f32 v[16:17], v[16:17], v[26:27]
	v_lshl_add_u64 v[24:25], v[22:23], 1, s[14:15]
	global_store_dwordx4 v[34:35], v[16:19], off offset:576
	s_waitcnt vmcnt(31)
	s_nop 1
	v_mov_b32_e32 v16, v212
	v_mov_b32_e32 v17, v213
	s_nop 0
	v_lshlrev_b32_e32 v20, 16, v16
	v_and_b32_e32 v21, 0xffff0000, v16
	v_lshlrev_b32_e32 v16, 16, v17
	v_and_b32_e32 v17, 0xffff0000, v17
	v_lshl_add_u64 v[18:19], v[22:23], 2, s[4:5]
	v_pk_add_f32 v[14:15], v[14:15], v[16:17]
	v_pk_add_f32 v[12:13], v[12:13], v[20:21]
	global_store_dwordx4 v[18:19], v[12:15], off
	s_waitcnt vmcnt(31)
	s_nop 1
	v_mov_b32_e32 v12, v214
	v_mov_b32_e32 v13, v215
	s_nop 0
	v_lshlrev_b32_e32 v14, 16, v12
	v_and_b32_e32 v15, 0xffff0000, v12
	v_lshlrev_b32_e32 v12, 16, v13
	v_and_b32_e32 v13, 0xffff0000, v13
	v_pk_add_f32 v[10:11], v[10:11], v[12:13]
	v_pk_add_f32 v[8:9], v[8:9], v[14:15]
	global_store_dwordx4 v[18:19], v[8:11], off offset:64
	s_waitcnt vmcnt(31)
	s_nop 1
	v_mov_b32_e32 v8, v216
	v_mov_b32_e32 v9, v217
	s_nop 0
	v_lshlrev_b32_e32 v10, 16, v8
	v_and_b32_e32 v11, 0xffff0000, v8
	v_lshlrev_b32_e32 v8, 16, v9
	v_and_b32_e32 v9, 0xffff0000, v9
	v_pk_add_f32 v[6:7], v[6:7], v[8:9]
	v_pk_add_f32 v[4:5], v[4:5], v[10:11]
	global_store_dwordx4 v[18:19], v[4:7], off offset:512
	s_waitcnt vmcnt(31)
	s_nop 1
	v_mov_b32_e32 v4, v218
	v_mov_b32_e32 v5, v219
	s_nop 0
	v_lshlrev_b32_e32 v6, 16, v4
	v_and_b32_e32 v7, 0xffff0000, v4
	v_lshlrev_b32_e32 v4, 16, v5
	v_and_b32_e32 v5, 0xffff0000, v5
	v_pk_add_f32 v[2:3], v[2:3], v[4:5]
	v_pk_add_f32 v[0:1], v[0:1], v[6:7]
	global_store_dwordx4 v[18:19], v[0:3], off offset:576
	s_cbranch_vccnz .LBB0_1565
	s_andn2_b64 vcc, exec, s[12:13]
	s_cbranch_vccnz .LBB0_1564
	s_barrier
	s_branch .LBB0_1564

; template <bool COOP>
; __global__ void __launch_bounds__(NTHR, 2) mega(Args args) {
	.amdhsa_kernel _Z4megaILb1EEv4Args
		.amdhsa_group_segment_fixed_size 0
		.amdhsa_private_segment_fixed_size 0
		.amdhsa_kernarg_size 480
		.amdhsa_user_sgpr_count 2
		.amdhsa_user_sgpr_dispatch_ptr 0
		.amdhsa_user_sgpr_queue_ptr 0
		.amdhsa_user_sgpr_kernarg_segment_ptr 1
		.amdhsa_user_sgpr_dispatch_id 0
		.amdhsa_user_sgpr_kernarg_preload_length 0
		.amdhsa_user_sgpr_kernarg_preload_offset 0
		.amdhsa_user_sgpr_private_segment_size 0
		.amdhsa_uses_dynamic_stack 0
		.amdhsa_enable_private_segment 0
		.amdhsa_system_sgpr_workgroup_id_x 1
		.amdhsa_system_sgpr_workgroup_id_y 0
		.amdhsa_system_sgpr_workgroup_id_z 0
		.amdhsa_system_sgpr_workgroup_info 0
		.amdhsa_system_vgpr_workitem_id 2
		.amdhsa_next_free_vgpr 256
		.amdhsa_next_free_sgpr 100
		.amdhsa_accum_offset 256
		.amdhsa_reserve_vcc 1
		.amdhsa_float_round_mode_32 0
		.amdhsa_float_round_mode_16_64 0
		.amdhsa_float_denorm_mode_32 3
		.amdhsa_float_denorm_mode_16_64 3
		.amdhsa_dx10_clamp 1
		.amdhsa_ieee_mode 1
		.amdhsa_fp16_overflow 0
		.amdhsa_tg_split 0
		.amdhsa_exception_fp_ieee_invalid_op 0
		.amdhsa_exception_fp_denorm_src 0
		.amdhsa_exception_fp_ieee_div_zero 0
		.amdhsa_exception_fp_ieee_overflow 0
		.amdhsa_exception_fp_ieee_underflow 0
		.amdhsa_exception_fp_ieee_inexact 0
		.amdhsa_exception_int_div_zero 0
	.end_amdhsa_kernel

; template <bool COOP>
; __global__ void __launch_bounds__(NTHR, 2) mega(Args args) {
amdhsa.kernels:
  - .agpr_count:     0
    .args:
      - .offset:         0
        .size:           224
        .value_kind:     by_value
      - .offset:         224
        .size:           4
        .value_kind:     hidden_block_count_x
      - .offset:         228
        .size:           4
        .value_kind:     hidden_block_count_y
      - .offset:         232
        .size:           4
        .value_kind:     hidden_block_count_z
      - .offset:         236
        .size:           2
        .value_kind:     hidden_group_size_x
      - .offset:         238
        .size:           2
        .value_kind:     hidden_group_size_y
      - .offset:         240
        .size:           2
        .value_kind:     hidden_group_size_z
      - .offset:         242
        .size:           2
        .value_kind:     hidden_remainder_x
      - .offset:         244
        .size:           2
        .value_kind:     hidden_remainder_y
      - .offset:         246
        .size:           2
        .value_kind:     hidden_remainder_z
      - .offset:         264
        .size:           8
        .value_kind:     hidden_global_offset_x
      - .offset:         272
        .size:           8
        .value_kind:     hidden_global_offset_y
      - .offset:         280
        .size:           8
        .value_kind:     hidden_global_offset_z
      - .offset:         288
        .size:           2
        .value_kind:     hidden_grid_dims
      - .offset:         312
        .size:           8
        .value_kind:     hidden_multigrid_sync_arg
      - .offset:         344
        .size:           4
        .value_kind:     hidden_dynamic_lds_size
    .group_segment_fixed_size: 0
    .kernarg_segment_align: 8
    .kernarg_segment_size: 480
    .language:       OpenCL C
    .language_version:
      - 2
      - 0
    .max_flat_workgroup_size: 512
    .name:           _Z4megaILb1EEv4Args
    .private_segment_fixed_size: 0
    .sgpr_count:     106
    .sgpr_spill_count: 9
    .symbol:         _Z4megaILb1EEv4Args.kd
    .uniform_work_group_size: 1
    .uses_dynamic_stack: false
    .vgpr_count:     256
    .vgpr_spill_count: 0
    .wavefront_size: 64
  - .agpr_count:     0
    .args:
      - .offset:         0
        .size:           224
        .value_kind:     by_value
      - .offset:         224
        .size:           4
        .value_kind:     hidden_block_count_x
      - .offset:         228
        .size:           4
        .value_kind:     hidden_block_count_y
      - .offset:         232
        .size:           4
        .value_kind:     hidden_block_count_z
      - .offset:         236
        .size:           2
        .value_kind:     hidden_group_size_x
      - .offset:         238
        .size:           2
        .value_kind:     hidden_group_size_y
      - .offset:         240
        .size:           2
        .value_kind:     hidden_group_size_z
      - .offset:         242
        .size:           2
        .value_kind:     hidden_remainder_x
      - .offset:         244
        .size:           2
        .value_kind:     hidden_remainder_y
      - .offset:         246
        .size:           2
        .value_kind:     hidden_remainder_z
      - .offset:         264
        .size:           8
        .value_kind:     hidden_global_offset_x
      - .offset:         272
        .size:           8
        .value_kind:     hidden_global_offset_y
      - .offset:         280
        .size:           8
        .value_kind:     hidden_global_offset_z
      - .offset:         288
        .size:           2
        .value_kind:     hidden_grid_dims
      - .offset:         344
        .size:           4
        .value_kind:     hidden_dynamic_lds_size
    .group_segment_fixed_size: 0
    .kernarg_segment_align: 8
    .kernarg_segment_size: 480
    .language:       OpenCL C
    .language_version:
      - 2
      - 0
    .max_flat_workgroup_size: 512
    .name:           _Z4megaILb0EEv4Args
    .private_segment_fixed_size: 0
    .sgpr_count:     106
    .sgpr_spill_count: 11
    .symbol:         _Z4megaILb0EEv4Args.kd
    .uniform_work_group_size: 1
    .uses_dynamic_stack: false
    .vgpr_count:     232
    .vgpr_spill_count: 0
    .wavefront_size: 64
